# first 4 MFMAs of each MFMA segment hoisted above the segment-opening barrier in all 10 K-loops
# baseline (speedup 1.0000x reference)
; #define PG8_STAGE(bufoff, gbase, voff) do { if constexpr (VAR != 1 && VAR != 3) { _Pragma("unroll") for (int _i = 0; _i < 2; ++_i) \
;         asm volatile("s_mov_b32 m0, %2\n\ts_nop 0\n\tglobal_load_lds_dwordx4 %0, %1" :: "v"((voff)[_i]), "s"((const char*)(gbase)), "s"(ldsbase + (unsigned)((bufoff) + _i * 8192)) : "memory", "m0"); } } while (0)
; #define PG8_LDA(dst, b, h) do { if constexpr (VAR < 2) _Pragma("unroll") for (int m = 0; m < 4; ++m) _Pragma("unroll") for (int k = 0; k < 2; ++k) dst[m][k] = *(const LAS bf16x8*)(lds + PG8_SA(b, h) + aoff + m * 2048 + k * 1024); } while (0)
; #define PG8_LDB(dst, b, h) do { if constexpr (VAR < 2) _Pragma("unroll") for (int n = 0; n < 2; ++n) _Pragma("unroll") for (int k = 0; k < 2; ++k) dst[n][k] = *(const LAS bf16x8*)(lds + PG8_SB(b, h) + boff + n * 2048 + k * 1024); } while (0)
; #define PG8_WAIT_V(n) asm volatile("s_waitcnt vmcnt(" #n ")" ::: "memory")
; #define PG8_WAIT_L(n) asm volatile("s_waitcnt lgkmcnt(" #n ")" ::: "memory")
; #define PG8_BAR do { if constexpr (VAR != 3) __builtin_amdgcn_s_barrier(); } while (0)
; #define PG8_SCHED __builtin_amdgcn_sched_barrier(0)
;     ...
;         for (int t = 0; t < nt; t += 2) {
;             const bool last = (t == nt - 2);
;             const char* a1 = cA + (size_t)(t + 1) * kstep;
;             const char* a2 = last ? nA : cA + (size_t)(t + 2) * kstep; const char* b2 = last ? nB : cB + (size_t)(t + 2) * kstep;
;             const char* a3 = a2 + kstep; const char* b3 = b2 + kstep;
;             PG8_LDB(B0, 0, 0); PG8_LDB(B1, 0, 1); PG8_SCHED; PG8_LDA(At, 0, 0); PG8_STAGE(PG8_SA(1, 1), a1 + hstepA, voffA);
;             PG8_WAIT_V(8); PG8_WAIT_L(0); PG8_BAR; PG8_MMA(0, 0, At, B0); PG8_MMA(0, 1, At, B1); PG8_BAR; PG8_SCHED;
;             PG8_LDA(At, 0, 1); PG8_STAGE(PG8_SB(0, 0), b2, voffB); PG8_STAGE(PG8_SB(0, 1), b2 + hstepB, voffB); PG8_STAGE(PG8_SA(0, 0), a2, voffA);
;             PG8_WAIT_V(8); PG8_WAIT_L(0); PG8_BAR; PG8_MMA(1, 0, At, B0); PG8_MMA(1, 1, At, B1); PG8_BAR; PG8_SCHED;
.LBB0_346:
	ds_read_b128 v[156:159], v151
	ds_read_b128 v[160:163], v151 offset:1024
	ds_read_b128 v[164:167], v151 offset:2048
	ds_read_b128 v[168:171], v151 offset:3072
	ds_read_b128 v[172:175], v152
	ds_read_b128 v[176:179], v152 offset:1024
	ds_read_b128 v[180:183], v152 offset:2048
	ds_read_b128 v[184:187], v152 offset:3072
	s_cmp_eq_u32 vcc_hi, 60
	s_cselect_b32 s96, s15, s66
	s_cselect_b32 s97, s14, s67
	s_cselect_b32 s94, s65, s69
	s_cselect_b32 s95, s63, vcc_lo
	s_add_u32 s92, s96, 0x80
	s_addc_u32 s93, s97, 0
	ds_read_b128 v[188:191], v153
	ds_read_b128 v[192:195], v153 offset:1024
	ds_read_b128 v[196:199], v153 offset:2048
	ds_read_b128 v[200:203], v153 offset:3072
	ds_read_b128 v[204:207], v153 offset:4096
	ds_read_b128 v[208:211], v153 offset:5120
	ds_read_b128 v[212:215], v153 offset:6144
	ds_read_b128 v[216:219], v153 offset:7168
	s_mov_b32 m0, s56
	s_nop 0
	global_load_lds_dwordx4 v1, s[90:91]
	s_nop 0
	s_mov_b32 m0, s57
	s_nop 0
	global_load_lds_dwordx4 v147, s[90:91]
	s_waitcnt lgkmcnt(7)
	v_mfma_f32_16x16x32_bf16 v[126:129], v[156:159], v[188:191], v[126:129]
	v_mfma_f32_16x16x32_bf16 v[122:125], v[164:167], v[188:191], v[122:125]
	s_waitcnt lgkmcnt(5)
	v_mfma_f32_16x16x32_bf16 v[118:121], v[156:159], v[196:199], v[118:121]
	v_mfma_f32_16x16x32_bf16 v[110:113], v[164:167], v[196:199], v[110:113]
	s_waitcnt vmcnt(8)
	s_waitcnt lgkmcnt(0)
	s_barrier
	s_setprio 1
	s_waitcnt lgkmcnt(3)
	v_mfma_f32_16x16x32_bf16 v[102:105], v[156:159], v[204:207], v[102:105]
	v_mfma_f32_16x16x32_bf16 v[94:97], v[164:167], v[204:207], v[94:97]
	s_waitcnt lgkmcnt(1)
	v_mfma_f32_16x16x32_bf16 v[86:89], v[156:159], v[212:215], v[86:89]
	v_mfma_f32_16x16x32_bf16 v[78:81], v[164:167], v[212:215], v[78:81]
	v_mfma_f32_16x16x32_bf16 v[126:129], v[160:163], v[192:195], v[126:129]
	v_mfma_f32_16x16x32_bf16 v[122:125], v[168:171], v[192:195], v[122:125]
	v_mfma_f32_16x16x32_bf16 v[118:121], v[160:163], v[200:203], v[118:121]
	v_mfma_f32_16x16x32_bf16 v[110:113], v[168:171], v[200:203], v[110:113]
	v_mfma_f32_16x16x32_bf16 v[102:105], v[160:163], v[208:211], v[102:105]
	v_mfma_f32_16x16x32_bf16 v[94:97], v[168:171], v[208:211], v[94:97]
	s_waitcnt lgkmcnt(0)
	v_mfma_f32_16x16x32_bf16 v[86:89], v[160:163], v[216:219], v[86:89]
	v_mfma_f32_16x16x32_bf16 v[78:81], v[168:171], v[216:219], v[78:81]
	s_setprio 0
	s_setprio 1
	v_mfma_f32_16x16x32_bf16 v[114:117], v[172:175], v[188:191], v[114:117]
	v_mfma_f32_16x16x32_bf16 v[106:109], v[180:183], v[188:191], v[106:109]
	v_mfma_f32_16x16x32_bf16 v[98:101], v[172:175], v[196:199], v[98:101]
	v_mfma_f32_16x16x32_bf16 v[90:93], v[180:183], v[196:199], v[90:93]
	v_mfma_f32_16x16x32_bf16 v[82:85], v[172:175], v[204:207], v[82:85]
	v_mfma_f32_16x16x32_bf16 v[74:77], v[180:183], v[204:207], v[74:77]
	v_mfma_f32_16x16x32_bf16 v[70:73], v[172:175], v[212:215], v[70:73]
	v_mfma_f32_16x16x32_bf16 v[66:69], v[180:183], v[212:215], v[66:69]
	v_mfma_f32_16x16x32_bf16 v[114:117], v[176:179], v[192:195], v[114:117]
	v_mfma_f32_16x16x32_bf16 v[106:109], v[184:187], v[192:195], v[106:109]
	v_mfma_f32_16x16x32_bf16 v[98:101], v[176:179], v[200:203], v[98:101]
	v_mfma_f32_16x16x32_bf16 v[90:93], v[184:187], v[200:203], v[90:93]
	v_mfma_f32_16x16x32_bf16 v[82:85], v[176:179], v[208:211], v[82:85]
	v_mfma_f32_16x16x32_bf16 v[74:77], v[184:187], v[208:211], v[74:77]
	v_mfma_f32_16x16x32_bf16 v[70:73], v[176:179], v[216:219], v[70:73]
	v_mfma_f32_16x16x32_bf16 v[66:69], v[184:187], v[216:219], v[66:69]
	s_setprio 0
	s_barrier
	ds_read_b128 v[188:191], v153 offset:16384
	ds_read_b128 v[192:195], v153 offset:17408
	ds_read_b128 v[196:199], v153 offset:18432
	ds_read_b128 v[200:203], v153 offset:19456
	ds_read_b128 v[204:207], v153 offset:20480
	ds_read_b128 v[208:211], v153 offset:21504
	ds_read_b128 v[212:215], v153 offset:22528
	ds_read_b128 v[216:219], v153 offset:23552
	s_mov_b32 m0, s25
	s_nop 0
	global_load_lds_dwordx4 v146, s[94:95]
	s_add_u32 s6, s94, 0x100000
	s_mov_b32 m0, s26
	s_nop 0
	global_load_lds_dwordx4 v148, s[94:95]
	s_addc_u32 s7, s95, 0
	s_mov_b32 m0, s27
	s_nop 0
	global_load_lds_dwordx4 v146, s[6:7]
	s_nop 0
	s_mov_b32 m0, s28
	s_nop 0
	global_load_lds_dwordx4 v148, s[6:7]
	s_nop 0
	s_mov_b32 m0, s19
	s_nop 0
	global_load_lds_dwordx4 v1, s[96:97]
	s_nop 0
	s_mov_b32 m0, s29
	s_nop 0
	global_load_lds_dwordx4 v147, s[96:97]
	s_waitcnt lgkmcnt(7)
	v_mfma_f32_16x16x32_bf16 v[62:65], v[156:159], v[188:191], v[62:65]
	v_mfma_f32_16x16x32_bf16 v[58:61], v[164:167], v[188:191], v[58:61]
	s_waitcnt lgkmcnt(5)
	v_mfma_f32_16x16x32_bf16 v[54:57], v[156:159], v[196:199], v[54:57]
	v_mfma_f32_16x16x32_bf16 v[46:49], v[164:167], v[196:199], v[46:49]
	s_waitcnt vmcnt(8)
	s_waitcnt lgkmcnt(0)
	s_barrier
; #define PG8_STAGE(bufoff, gbase, voff) do { if constexpr (VAR != 1 && VAR != 3) { _Pragma("unroll") for (int _i = 0; _i < 2; ++_i) \
;         asm volatile("s_mov_b32 m0, %2\n\ts_nop 0\n\tglobal_load_lds_dwordx4 %0, %1" :: "v"((voff)[_i]), "s"((const char*)(gbase)), "s"(ldsbase + (unsigned)((bufoff) + _i * 8192)) : "memory", "m0"); } } while (0)
; #define PG8_LDA(dst, b, h) do { if constexpr (VAR < 2) _Pragma("unroll") for (int m = 0; m < 4; ++m) _Pragma("unroll") for (int k = 0; k < 2; ++k) dst[m][k] = *(const LAS bf16x8*)(lds + PG8_SA(b, h) + aoff + m * 2048 + k * 1024); } while (0)
; #define PG8_LDB(dst, b, h) do { if constexpr (VAR < 2) _Pragma("unroll") for (int n = 0; n < 2; ++n) _Pragma("unroll") for (int k = 0; k < 2; ++k) dst[n][k] = *(const LAS bf16x8*)(lds + PG8_SB(b, h) + boff + n * 2048 + k * 1024); } while (0)
; #define PG8_WAIT_V(n) asm volatile("s_waitcnt vmcnt(" #n ")" ::: "memory")
; #define PG8_WAIT_L(n) asm volatile("s_waitcnt lgkmcnt(" #n ")" ::: "memory")
; #define PG8_BAR do { if constexpr (VAR != 3) __builtin_amdgcn_s_barrier(); } while (0)
; #define PG8_SCHED __builtin_amdgcn_sched_barrier(0)
;     ...
;             PG8_WAIT_V(8); PG8_WAIT_L(0); PG8_BAR; PG8_MMA(1, 0, At, B0); PG8_MMA(1, 1, At, B1); PG8_BAR; PG8_SCHED;
;             PG8_LDB(B0, 1, 0); PG8_LDB(B1, 1, 1); PG8_SCHED; PG8_LDA(At, 1, 0); PG8_STAGE(PG8_SA(0, 1), a2 + hstepA, voffA);
;             PG8_WAIT_V(8); PG8_WAIT_L(0); PG8_BAR; PG8_MMA(0, 0, At, B0); PG8_MMA(0, 1, At, B1); PG8_BAR; PG8_SCHED;
	s_setprio 1
	s_waitcnt lgkmcnt(3)
	v_mfma_f32_16x16x32_bf16 v[38:41], v[156:159], v[204:207], v[38:41]
	v_mfma_f32_16x16x32_bf16 v[30:33], v[164:167], v[204:207], v[30:33]
	s_waitcnt lgkmcnt(1)
	v_mfma_f32_16x16x32_bf16 v[22:25], v[156:159], v[212:215], v[22:25]
	v_mfma_f32_16x16x32_bf16 v[14:17], v[164:167], v[212:215], v[14:17]
	v_mfma_f32_16x16x32_bf16 v[62:65], v[160:163], v[192:195], v[62:65]
	v_mfma_f32_16x16x32_bf16 v[58:61], v[168:171], v[192:195], v[58:61]
	v_mfma_f32_16x16x32_bf16 v[54:57], v[160:163], v[200:203], v[54:57]
	v_mfma_f32_16x16x32_bf16 v[46:49], v[168:171], v[200:203], v[46:49]
	v_mfma_f32_16x16x32_bf16 v[38:41], v[160:163], v[208:211], v[38:41]
	v_mfma_f32_16x16x32_bf16 v[30:33], v[168:171], v[208:211], v[30:33]
	s_waitcnt lgkmcnt(0)
	v_mfma_f32_16x16x32_bf16 v[22:25], v[160:163], v[216:219], v[22:25]
	v_mfma_f32_16x16x32_bf16 v[14:17], v[168:171], v[216:219], v[14:17]
	s_setprio 0
	s_setprio 1
	v_mfma_f32_16x16x32_bf16 v[50:53], v[172:175], v[188:191], v[50:53]
	v_mfma_f32_16x16x32_bf16 v[42:45], v[180:183], v[188:191], v[42:45]
	v_mfma_f32_16x16x32_bf16 v[34:37], v[172:175], v[196:199], v[34:37]
	v_mfma_f32_16x16x32_bf16 v[26:29], v[180:183], v[196:199], v[26:29]
	v_mfma_f32_16x16x32_bf16 v[18:21], v[172:175], v[204:207], v[18:21]
	v_mfma_f32_16x16x32_bf16 v[10:13], v[180:183], v[204:207], v[10:13]
	v_mfma_f32_16x16x32_bf16 v[6:9], v[172:175], v[212:215], v[6:9]
	v_mfma_f32_16x16x32_bf16 v[2:5], v[180:183], v[212:215], v[2:5]
	v_mfma_f32_16x16x32_bf16 v[50:53], v[176:179], v[192:195], v[50:53]
	v_mfma_f32_16x16x32_bf16 v[42:45], v[184:187], v[192:195], v[42:45]
	v_mfma_f32_16x16x32_bf16 v[34:37], v[176:179], v[200:203], v[34:37]
	v_mfma_f32_16x16x32_bf16 v[26:29], v[184:187], v[200:203], v[26:29]
	v_mfma_f32_16x16x32_bf16 v[18:21], v[176:179], v[208:211], v[18:21]
	v_mfma_f32_16x16x32_bf16 v[10:13], v[184:187], v[208:211], v[10:13]
	v_mfma_f32_16x16x32_bf16 v[6:9], v[176:179], v[216:219], v[6:9]
	v_mfma_f32_16x16x32_bf16 v[2:5], v[184:187], v[216:219], v[2:5]
	s_setprio 0
	s_barrier
	ds_read_b128 v[156:159], v154
	ds_read_b128 v[160:163], v154 offset:1024
	ds_read_b128 v[164:167], v154 offset:2048
	ds_read_b128 v[168:171], v154 offset:3072
	ds_read_b128 v[172:175], v155
	ds_read_b128 v[176:179], v155 offset:1024
	ds_read_b128 v[180:183], v155 offset:2048
	ds_read_b128 v[184:187], v155 offset:3072
	ds_read_b128 v[188:191], v153 offset:32768
	ds_read_b128 v[192:195], v153 offset:33792
	ds_read_b128 v[196:199], v153 offset:34816
	ds_read_b128 v[200:203], v153 offset:35840
	ds_read_b128 v[204:207], v153 offset:36864
	ds_read_b128 v[208:211], v153 offset:37888
	ds_read_b128 v[212:215], v153 offset:38912
	ds_read_b128 v[216:219], v153 offset:39936
	s_add_u32 s6, s96, 0x100000
	s_addc_u32 s7, s97, 0
	s_mov_b32 m0, s30
	s_nop 0
	global_load_lds_dwordx4 v1, s[6:7]
	s_nop 0
	s_mov_b32 m0, s31
	s_nop 0
	global_load_lds_dwordx4 v147, s[6:7]
	s_waitcnt lgkmcnt(7)
	v_mfma_f32_16x16x32_bf16 v[126:129], v[156:159], v[188:191], v[126:129]
	v_mfma_f32_16x16x32_bf16 v[122:125], v[164:167], v[188:191], v[122:125]
	s_waitcnt lgkmcnt(5)
	v_mfma_f32_16x16x32_bf16 v[118:121], v[156:159], v[196:199], v[118:121]
	v_mfma_f32_16x16x32_bf16 v[110:113], v[164:167], v[196:199], v[110:113]
	s_waitcnt vmcnt(8)
	s_waitcnt lgkmcnt(0)
	s_barrier
	s_setprio 1
	s_waitcnt lgkmcnt(3)
	v_mfma_f32_16x16x32_bf16 v[102:105], v[156:159], v[204:207], v[102:105]
	v_mfma_f32_16x16x32_bf16 v[94:97], v[164:167], v[204:207], v[94:97]
	s_waitcnt lgkmcnt(1)
	v_mfma_f32_16x16x32_bf16 v[86:89], v[156:159], v[212:215], v[86:89]
	v_mfma_f32_16x16x32_bf16 v[78:81], v[164:167], v[212:215], v[78:81]
	v_mfma_f32_16x16x32_bf16 v[126:129], v[160:163], v[192:195], v[126:129]
	v_mfma_f32_16x16x32_bf16 v[122:125], v[168:171], v[192:195], v[122:125]
	v_mfma_f32_16x16x32_bf16 v[118:121], v[160:163], v[200:203], v[118:121]
	v_mfma_f32_16x16x32_bf16 v[110:113], v[168:171], v[200:203], v[110:113]
	v_mfma_f32_16x16x32_bf16 v[102:105], v[160:163], v[208:211], v[102:105]
	v_mfma_f32_16x16x32_bf16 v[94:97], v[168:171], v[208:211], v[94:97]
	s_waitcnt lgkmcnt(0)
	v_mfma_f32_16x16x32_bf16 v[86:89], v[160:163], v[216:219], v[86:89]
	v_mfma_f32_16x16x32_bf16 v[78:81], v[168:171], v[216:219], v[78:81]
	s_setprio 0
	s_setprio 1
	v_mfma_f32_16x16x32_bf16 v[114:117], v[172:175], v[188:191], v[114:117]
	v_mfma_f32_16x16x32_bf16 v[106:109], v[180:183], v[188:191], v[106:109]
	v_mfma_f32_16x16x32_bf16 v[98:101], v[172:175], v[196:199], v[98:101]
	v_mfma_f32_16x16x32_bf16 v[90:93], v[180:183], v[196:199], v[90:93]
	v_mfma_f32_16x16x32_bf16 v[82:85], v[172:175], v[204:207], v[82:85]
	v_mfma_f32_16x16x32_bf16 v[74:77], v[180:183], v[204:207], v[74:77]
	v_mfma_f32_16x16x32_bf16 v[70:73], v[172:175], v[212:215], v[70:73]
	v_mfma_f32_16x16x32_bf16 v[66:69], v[180:183], v[212:215], v[66:69]
	v_mfma_f32_16x16x32_bf16 v[114:117], v[176:179], v[192:195], v[114:117]
	v_mfma_f32_16x16x32_bf16 v[106:109], v[184:187], v[192:195], v[106:109]
	v_mfma_f32_16x16x32_bf16 v[98:101], v[176:179], v[200:203], v[98:101]
	v_mfma_f32_16x16x32_bf16 v[90:93], v[184:187], v[200:203], v[90:93]
	v_mfma_f32_16x16x32_bf16 v[82:85], v[176:179], v[208:211], v[82:85]
	v_mfma_f32_16x16x32_bf16 v[74:77], v[184:187], v[208:211], v[74:77]
	v_mfma_f32_16x16x32_bf16 v[70:73], v[176:179], v[216:219], v[70:73]
	v_mfma_f32_16x16x32_bf16 v[66:69], v[184:187], v[216:219], v[66:69]
	s_setprio 0
	s_barrier
; #define PG8_STAGE(bufoff, gbase, voff) do { if constexpr (VAR != 1 && VAR != 3) { _Pragma("unroll") for (int _i = 0; _i < 2; ++_i) \
;         asm volatile("s_mov_b32 m0, %2\n\ts_nop 0\n\tglobal_load_lds_dwordx4 %0, %1" :: "v"((voff)[_i]), "s"((const char*)(gbase)), "s"(ldsbase + (unsigned)((bufoff) + _i * 8192)) : "memory", "m0"); } } while (0)
; #define PG8_LDA(dst, b, h) do { if constexpr (VAR < 2) _Pragma("unroll") for (int m = 0; m < 4; ++m) _Pragma("unroll") for (int k = 0; k < 2; ++k) dst[m][k] = *(const LAS bf16x8*)(lds + PG8_SA(b, h) + aoff + m * 2048 + k * 1024); } while (0)
; #define PG8_WAIT_V(n) asm volatile("s_waitcnt vmcnt(" #n ")" ::: "memory")
; #define PG8_WAIT_L(n) asm volatile("s_waitcnt lgkmcnt(" #n ")" ::: "memory")
; #define PG8_BAR do { if constexpr (VAR != 3) __builtin_amdgcn_s_barrier(); } while (0)
; #define PG8_SCHED __builtin_amdgcn_sched_barrier(0)
;     ...
;             PG8_LDA(At, 1, 1); PG8_STAGE(PG8_SB(1, 0), b3, voffB); PG8_STAGE(PG8_SB(1, 1), b3 + hstepB, voffB); PG8_STAGE(PG8_SA(1, 0), a3, voffA);
;             PG8_WAIT_V(8); PG8_WAIT_L(0); PG8_BAR; PG8_MMA(1, 0, At, B0); PG8_MMA(1, 1, At, B1); PG8_BAR; PG8_SCHED;
;         }
;         if (wr == 0) PG8_BAR;
	ds_read_b128 v[188:191], v153 offset:49152
	ds_read_b128 v[192:195], v153 offset:50176
	ds_read_b128 v[196:199], v153 offset:51200
	ds_read_b128 v[200:203], v153 offset:52224
	ds_read_b128 v[204:207], v153 offset:53248
	ds_read_b128 v[208:211], v153 offset:54272
	ds_read_b128 v[212:215], v153 offset:55296
	ds_read_b128 v[216:219], v153 offset:56320
	s_add_u32 s6, s94, 0x80
	s_addc_u32 s7, s95, 0
	s_mov_b32 m0, s33
	s_nop 0
	global_load_lds_dwordx4 v146, s[6:7]
	s_nop 0
	s_mov_b32 m0, s35
	s_nop 0
	global_load_lds_dwordx4 v148, s[6:7]
	s_add_u32 s6, s94, 0x100080
	s_addc_u32 s7, s95, 0
	s_mov_b32 m0, s54
	s_nop 0
	global_load_lds_dwordx4 v146, s[6:7]
	s_nop 0
	s_mov_b32 m0, s55
	s_nop 0
	global_load_lds_dwordx4 v148, s[6:7]
	s_nop 0
	s_mov_b32 m0, s52
	s_nop 0
	global_load_lds_dwordx4 v1, s[92:93]
	s_nop 0
	s_mov_b32 m0, s53
	s_nop 0
	global_load_lds_dwordx4 v147, s[92:93]
	s_waitcnt lgkmcnt(7)
	v_mfma_f32_16x16x32_bf16 v[62:65], v[156:159], v[188:191], v[62:65]
	v_mfma_f32_16x16x32_bf16 v[58:61], v[164:167], v[188:191], v[58:61]
	s_waitcnt lgkmcnt(5)
	v_mfma_f32_16x16x32_bf16 v[54:57], v[156:159], v[196:199], v[54:57]
	v_mfma_f32_16x16x32_bf16 v[46:49], v[164:167], v[196:199], v[46:49]
	s_waitcnt vmcnt(8)
	s_waitcnt lgkmcnt(0)
	s_barrier
	s_setprio 1
	s_waitcnt lgkmcnt(3)
	v_mfma_f32_16x16x32_bf16 v[38:41], v[156:159], v[204:207], v[38:41]
	v_mfma_f32_16x16x32_bf16 v[30:33], v[164:167], v[204:207], v[30:33]
	s_waitcnt lgkmcnt(1)
	v_mfma_f32_16x16x32_bf16 v[22:25], v[156:159], v[212:215], v[22:25]
	v_mfma_f32_16x16x32_bf16 v[14:17], v[164:167], v[212:215], v[14:17]
	v_mfma_f32_16x16x32_bf16 v[62:65], v[160:163], v[192:195], v[62:65]
	v_mfma_f32_16x16x32_bf16 v[58:61], v[168:171], v[192:195], v[58:61]
	v_mfma_f32_16x16x32_bf16 v[54:57], v[160:163], v[200:203], v[54:57]
	v_mfma_f32_16x16x32_bf16 v[46:49], v[168:171], v[200:203], v[46:49]
	v_mfma_f32_16x16x32_bf16 v[38:41], v[160:163], v[208:211], v[38:41]
	v_mfma_f32_16x16x32_bf16 v[30:33], v[168:171], v[208:211], v[30:33]
	s_waitcnt lgkmcnt(0)
	v_mfma_f32_16x16x32_bf16 v[22:25], v[160:163], v[216:219], v[22:25]
	v_mfma_f32_16x16x32_bf16 v[14:17], v[168:171], v[216:219], v[14:17]
	s_setprio 0
	s_setprio 1
	v_mfma_f32_16x16x32_bf16 v[50:53], v[172:175], v[188:191], v[50:53]
	v_mfma_f32_16x16x32_bf16 v[42:45], v[180:183], v[188:191], v[42:45]
	v_mfma_f32_16x16x32_bf16 v[34:37], v[172:175], v[196:199], v[34:37]
	v_mfma_f32_16x16x32_bf16 v[26:29], v[180:183], v[196:199], v[26:29]
	v_mfma_f32_16x16x32_bf16 v[18:21], v[172:175], v[204:207], v[18:21]
	v_mfma_f32_16x16x32_bf16 v[10:13], v[180:183], v[204:207], v[10:13]
	v_mfma_f32_16x16x32_bf16 v[6:9], v[172:175], v[212:215], v[6:9]
	v_mfma_f32_16x16x32_bf16 v[2:5], v[180:183], v[212:215], v[2:5]
	v_mfma_f32_16x16x32_bf16 v[50:53], v[176:179], v[192:195], v[50:53]
	v_mfma_f32_16x16x32_bf16 v[42:45], v[184:187], v[192:195], v[42:45]
	v_mfma_f32_16x16x32_bf16 v[34:37], v[176:179], v[200:203], v[34:37]
	v_mfma_f32_16x16x32_bf16 v[26:29], v[184:187], v[200:203], v[26:29]
	v_mfma_f32_16x16x32_bf16 v[18:21], v[176:179], v[208:211], v[18:21]
	v_mfma_f32_16x16x32_bf16 v[10:13], v[184:187], v[208:211], v[10:13]
	v_mfma_f32_16x16x32_bf16 v[6:9], v[176:179], v[216:219], v[6:9]
	v_mfma_f32_16x16x32_bf16 v[2:5], v[184:187], v[216:219], v[2:5]
	s_setprio 0
	s_barrier
	s_add_i32 vcc_hi, vcc_hi, 2
	s_add_u32 s66, s66, 0x100
	s_addc_u32 s67, s67, 0
	s_add_u32 s69, s69, 0x100
	s_addc_u32 vcc_lo, vcc_lo, 0
	s_add_u32 s90, s90, 0x100
	s_addc_u32 s91, s91, 0
	s_cmp_gt_u32 vcc_hi, 61
	s_cbranch_scc0 .LBB0_346
	s_and_b64 vcc, exec, s[4:5]
	s_cbranch_vccz .LBB0_349
	s_barrier

; #define PG8_STAGE(bufoff, gbase, voff) do { if constexpr (VAR != 1 && VAR != 3) { _Pragma("unroll") for (int _i = 0; _i < 2; ++_i) \
;         asm volatile("s_mov_b32 m0, %2\n\ts_nop 0\n\tglobal_load_lds_dwordx4 %0, %1" :: "v"((voff)[_i]), "s"((const char*)(gbase)), "s"(ldsbase + (unsigned)((bufoff) + _i * 8192)) : "memory", "m0"); } } while (0)
; #define PG8_LDA(dst, b, h) do { if constexpr (VAR < 2) _Pragma("unroll") for (int m = 0; m < 4; ++m) _Pragma("unroll") for (int k = 0; k < 2; ++k) dst[m][k] = *(const LAS bf16x8*)(lds + PG8_SA(b, h) + aoff + m * 2048 + k * 1024); } while (0)
; #define PG8_LDB(dst, b, h) do { if constexpr (VAR < 2) _Pragma("unroll") for (int n = 0; n < 2; ++n) _Pragma("unroll") for (int k = 0; k < 2; ++k) dst[n][k] = *(const LAS bf16x8*)(lds + PG8_SB(b, h) + boff + n * 2048 + k * 1024); } while (0)
; #define PG8_WAIT_V(n) asm volatile("s_waitcnt vmcnt(" #n ")" ::: "memory")
; #define PG8_WAIT_L(n) asm volatile("s_waitcnt lgkmcnt(" #n ")" ::: "memory")
; #define PG8_BAR do { if constexpr (VAR != 3) __builtin_amdgcn_s_barrier(); } while (0)
; #define PG8_SCHED __builtin_amdgcn_sched_barrier(0)
;     ...
;         for (int t = 0; t < nt; t += 2) {
;             const bool last = (t == nt - 2);
;             const char* a1 = cA + (size_t)(t + 1) * kstep;
;             const char* a2 = last ? nA : cA + (size_t)(t + 2) * kstep; const char* b2 = last ? nB : cB + (size_t)(t + 2) * kstep;
;             const char* a3 = a2 + kstep; const char* b3 = b2 + kstep;
;             PG8_LDB(B0, 0, 0); PG8_LDB(B1, 0, 1); PG8_SCHED; PG8_LDA(At, 0, 0); PG8_STAGE(PG8_SA(1, 1), a1 + hstepA, voffA);
;             PG8_WAIT_V(8); PG8_WAIT_L(0); PG8_BAR; PG8_MMA(0, 0, At, B0); PG8_MMA(0, 1, At, B1); PG8_BAR; PG8_SCHED;
;             PG8_LDA(At, 0, 1); PG8_STAGE(PG8_SB(0, 0), b2, voffB); PG8_STAGE(PG8_SB(0, 1), b2 + hstepB, voffB); PG8_STAGE(PG8_SA(0, 0), a2, voffA);
;             PG8_WAIT_V(8); PG8_WAIT_L(0); PG8_BAR; PG8_MMA(1, 0, At, B0); PG8_MMA(1, 1, At, B1); PG8_BAR; PG8_SCHED;
.LBB0_539:
	ds_read_b128 v[138:141], v159
	ds_read_b128 v[164:167], v159 offset:1024
	ds_read_b128 v[168:171], v159 offset:2048
	ds_read_b128 v[172:175], v159 offset:3072
	ds_read_b128 v[176:179], v160
	ds_read_b128 v[180:183], v160 offset:1024
	ds_read_b128 v[184:187], v160 offset:2048
	ds_read_b128 v[188:191], v160 offset:3072
	s_cmp_eq_u32 s6, 28
	s_cselect_b32 s94, s15, vcc_lo
	s_cselect_b32 s95, s14, vcc_hi
	s_cselect_b32 s92, s73, s54
	s_cselect_b32 s93, s71, s55
	s_add_u32 s90, s94, 0x80
	s_addc_u32 s91, s95, 0
	ds_read_b128 v[192:195], v161
	ds_read_b128 v[196:199], v161 offset:1024
	ds_read_b128 v[200:203], v161 offset:2048
	ds_read_b128 v[204:207], v161 offset:3072
	ds_read_b128 v[208:211], v161 offset:4096
	ds_read_b128 v[212:215], v161 offset:5120
	ds_read_b128 v[216:219], v161 offset:6144
	ds_read_b128 v[220:223], v161 offset:7168
	s_mov_b32 m0, s57
	s_nop 0
	global_load_lds_dwordx4 v151, s[88:89]
	s_nop 0
	s_mov_b32 m0, s24
	s_nop 0
	global_load_lds_dwordx4 v153, s[88:89]
	s_waitcnt lgkmcnt(7)
	v_mfma_i32_16x16x64_i8 v[126:129], v[138:141], v[192:195], v[126:129]
	v_mfma_i32_16x16x64_i8 v[118:121], v[168:171], v[192:195], v[118:121]
	s_waitcnt lgkmcnt(5)
	v_mfma_i32_16x16x64_i8 v[110:113], v[138:141], v[200:203], v[110:113]
	v_mfma_i32_16x16x64_i8 v[102:105], v[168:171], v[200:203], v[102:105]
	s_waitcnt vmcnt(8)
	s_waitcnt lgkmcnt(0)
	s_barrier
	s_setprio 1
	s_waitcnt lgkmcnt(3)
	v_mfma_i32_16x16x64_i8 v[94:97], v[138:141], v[208:211], v[94:97]
	v_mfma_i32_16x16x64_i8 v[86:89], v[168:171], v[208:211], v[86:89]
	s_waitcnt lgkmcnt(1)
	v_mfma_i32_16x16x64_i8 v[78:81], v[138:141], v[216:219], v[78:81]
	v_mfma_i32_16x16x64_i8 v[70:73], v[168:171], v[216:219], v[70:73]
	v_mfma_i32_16x16x64_i8 v[126:129], v[164:167], v[196:199], v[126:129]
	v_mfma_i32_16x16x64_i8 v[118:121], v[172:175], v[196:199], v[118:121]
	v_mfma_i32_16x16x64_i8 v[110:113], v[164:167], v[204:207], v[110:113]
	v_mfma_i32_16x16x64_i8 v[102:105], v[172:175], v[204:207], v[102:105]
	v_mfma_i32_16x16x64_i8 v[94:97], v[164:167], v[212:215], v[94:97]
	v_mfma_i32_16x16x64_i8 v[86:89], v[172:175], v[212:215], v[86:89]
	s_waitcnt lgkmcnt(0)
	v_mfma_i32_16x16x64_i8 v[78:81], v[164:167], v[220:223], v[78:81]
	v_mfma_i32_16x16x64_i8 v[70:73], v[172:175], v[220:223], v[70:73]
	s_setprio 0
	s_setprio 1
	v_mfma_i32_16x16x64_i8 v[122:125], v[176:179], v[192:195], v[122:125]
	v_mfma_i32_16x16x64_i8 v[114:117], v[184:187], v[192:195], v[114:117]
	v_mfma_i32_16x16x64_i8 v[106:109], v[176:179], v[200:203], v[106:109]
	v_mfma_i32_16x16x64_i8 v[98:101], v[184:187], v[200:203], v[98:101]
	v_mfma_i32_16x16x64_i8 v[90:93], v[176:179], v[208:211], v[90:93]
	v_mfma_i32_16x16x64_i8 v[82:85], v[184:187], v[208:211], v[82:85]
	v_mfma_i32_16x16x64_i8 v[74:77], v[176:179], v[216:219], v[74:77]
	v_mfma_i32_16x16x64_i8 v[66:69], v[184:187], v[216:219], v[66:69]
	v_mfma_i32_16x16x64_i8 v[122:125], v[180:183], v[196:199], v[122:125]
	v_mfma_i32_16x16x64_i8 v[114:117], v[188:191], v[196:199], v[114:117]
	v_mfma_i32_16x16x64_i8 v[106:109], v[180:183], v[204:207], v[106:109]
	v_mfma_i32_16x16x64_i8 v[98:101], v[188:191], v[204:207], v[98:101]
	v_mfma_i32_16x16x64_i8 v[90:93], v[180:183], v[212:215], v[90:93]
	v_mfma_i32_16x16x64_i8 v[82:85], v[188:191], v[212:215], v[82:85]
	v_mfma_i32_16x16x64_i8 v[74:77], v[180:183], v[220:223], v[74:77]
	v_mfma_i32_16x16x64_i8 v[66:69], v[188:191], v[220:223], v[66:69]
	s_setprio 0
	s_barrier
	ds_read_b128 v[192:195], v161 offset:16384
	ds_read_b128 v[196:199], v161 offset:17408
	ds_read_b128 v[200:203], v161 offset:18432
	ds_read_b128 v[204:207], v161 offset:19456
	ds_read_b128 v[208:211], v161 offset:20480
	ds_read_b128 v[212:215], v161 offset:21504
	ds_read_b128 v[216:219], v161 offset:22528
	ds_read_b128 v[220:223], v161 offset:23552
	s_mov_b32 m0, s29
	s_nop 0
	global_load_lds_dwordx4 v152, s[92:93]
	s_add_u32 s10, s92, 0x80000
	s_mov_b32 m0, s30
	s_nop 0
	global_load_lds_dwordx4 v154, s[92:93]
	s_addc_u32 s11, s93, 0
	s_mov_b32 m0, s31
	s_nop 0
	global_load_lds_dwordx4 v152, s[10:11]
	s_nop 0
	s_mov_b32 m0, s33
	s_nop 0
	global_load_lds_dwordx4 v154, s[10:11]
	s_nop 0
	s_mov_b32 m0, s26
	s_nop 0
	global_load_lds_dwordx4 v151, s[94:95]
	s_nop 0
	s_mov_b32 m0, s35
	s_nop 0
	global_load_lds_dwordx4 v153, s[94:95]
	s_waitcnt lgkmcnt(7)
	v_mfma_i32_16x16x64_i8 v[62:65], v[138:141], v[192:195], v[62:65]
	v_mfma_i32_16x16x64_i8 v[54:57], v[168:171], v[192:195], v[54:57]
	s_waitcnt lgkmcnt(5)
	v_mfma_i32_16x16x64_i8 v[46:49], v[138:141], v[200:203], v[46:49]
	v_mfma_i32_16x16x64_i8 v[38:41], v[168:171], v[200:203], v[38:41]
	s_waitcnt vmcnt(8)
	s_waitcnt lgkmcnt(0)
	s_barrier
	s_setprio 1
	s_waitcnt lgkmcnt(3)
	v_mfma_i32_16x16x64_i8 v[30:33], v[138:141], v[208:211], v[30:33]
	v_mfma_i32_16x16x64_i8 v[22:25], v[168:171], v[208:211], v[22:25]
	s_waitcnt lgkmcnt(1)
	v_mfma_i32_16x16x64_i8 v[14:17], v[138:141], v[216:219], v[14:17]
	v_mfma_i32_16x16x64_i8 v[6:9], v[168:171], v[216:219], v[6:9]
	v_mfma_i32_16x16x64_i8 v[62:65], v[164:167], v[196:199], v[62:65]
	v_mfma_i32_16x16x64_i8 v[54:57], v[172:175], v[196:199], v[54:57]
	v_mfma_i32_16x16x64_i8 v[46:49], v[164:167], v[204:207], v[46:49]
	v_mfma_i32_16x16x64_i8 v[38:41], v[172:175], v[204:207], v[38:41]
	v_mfma_i32_16x16x64_i8 v[30:33], v[164:167], v[212:215], v[30:33]
	v_mfma_i32_16x16x64_i8 v[22:25], v[172:175], v[212:215], v[22:25]
	s_waitcnt lgkmcnt(0)
	v_mfma_i32_16x16x64_i8 v[14:17], v[164:167], v[220:223], v[14:17]
	v_mfma_i32_16x16x64_i8 v[6:9], v[172:175], v[220:223], v[6:9]
	s_setprio 0
	s_setprio 1
	v_mfma_i32_16x16x64_i8 v[58:61], v[176:179], v[192:195], v[58:61]
	v_mfma_i32_16x16x64_i8 v[50:53], v[184:187], v[192:195], v[50:53]
	v_mfma_i32_16x16x64_i8 v[42:45], v[176:179], v[200:203], v[42:45]
	v_mfma_i32_16x16x64_i8 v[34:37], v[184:187], v[200:203], v[34:37]
	v_mfma_i32_16x16x64_i8 v[26:29], v[176:179], v[208:211], v[26:29]
	v_mfma_i32_16x16x64_i8 v[18:21], v[184:187], v[208:211], v[18:21]
	v_mfma_i32_16x16x64_i8 v[10:13], v[176:179], v[216:219], v[10:13]
	v_mfma_i32_16x16x64_i8 v[2:5], v[184:187], v[216:219], v[2:5]
	v_mfma_i32_16x16x64_i8 v[58:61], v[180:183], v[196:199], v[58:61]
	v_mfma_i32_16x16x64_i8 v[50:53], v[188:191], v[196:199], v[50:53]
	v_mfma_i32_16x16x64_i8 v[42:45], v[180:183], v[204:207], v[42:45]
	v_mfma_i32_16x16x64_i8 v[34:37], v[188:191], v[204:207], v[34:37]
	v_mfma_i32_16x16x64_i8 v[26:29], v[180:183], v[212:215], v[26:29]
	v_mfma_i32_16x16x64_i8 v[18:21], v[188:191], v[212:215], v[18:21]
	v_mfma_i32_16x16x64_i8 v[10:13], v[180:183], v[220:223], v[10:13]
	v_mfma_i32_16x16x64_i8 v[2:5], v[188:191], v[220:223], v[2:5]
	s_setprio 0
	s_barrier
; #define PG8_STAGE(bufoff, gbase, voff) do { if constexpr (VAR != 1 && VAR != 3) { _Pragma("unroll") for (int _i = 0; _i < 2; ++_i) \
;         asm volatile("s_mov_b32 m0, %2\n\ts_nop 0\n\tglobal_load_lds_dwordx4 %0, %1" :: "v"((voff)[_i]), "s"((const char*)(gbase)), "s"(ldsbase + (unsigned)((bufoff) + _i * 8192)) : "memory", "m0"); } } while (0)
; #define PG8_LDA(dst, b, h) do { if constexpr (VAR < 2) _Pragma("unroll") for (int m = 0; m < 4; ++m) _Pragma("unroll") for (int k = 0; k < 2; ++k) dst[m][k] = *(const LAS bf16x8*)(lds + PG8_SA(b, h) + aoff + m * 2048 + k * 1024); } while (0)
; #define PG8_LDB(dst, b, h) do { if constexpr (VAR < 2) _Pragma("unroll") for (int n = 0; n < 2; ++n) _Pragma("unroll") for (int k = 0; k < 2; ++k) dst[n][k] = *(const LAS bf16x8*)(lds + PG8_SB(b, h) + boff + n * 2048 + k * 1024); } while (0)
; #define PG8_WAIT_V(n) asm volatile("s_waitcnt vmcnt(" #n ")" ::: "memory")
; #define PG8_WAIT_L(n) asm volatile("s_waitcnt lgkmcnt(" #n ")" ::: "memory")
; #define PG8_BAR do { if constexpr (VAR != 3) __builtin_amdgcn_s_barrier(); } while (0)
; #define PG8_SCHED __builtin_amdgcn_sched_barrier(0)
;     ...
;             PG8_LDB(B0, 1, 0); PG8_LDB(B1, 1, 1); PG8_SCHED; PG8_LDA(At, 1, 0); PG8_STAGE(PG8_SA(0, 1), a2 + hstepA, voffA);
;             PG8_WAIT_V(8); PG8_WAIT_L(0); PG8_BAR; PG8_MMA(0, 0, At, B0); PG8_MMA(0, 1, At, B1); PG8_BAR; PG8_SCHED;
;             PG8_LDA(At, 1, 1); PG8_STAGE(PG8_SB(1, 0), b3, voffB); PG8_STAGE(PG8_SB(1, 1), b3 + hstepB, voffB); PG8_STAGE(PG8_SA(1, 0), a3, voffA);
;             PG8_WAIT_V(8); PG8_WAIT_L(0); PG8_BAR; PG8_MMA(1, 0, At, B0); PG8_MMA(1, 1, At, B1); PG8_BAR; PG8_SCHED;
;         }
;         if (wr == 0) PG8_BAR;
	ds_read_b128 v[138:141], v162
	ds_read_b128 v[164:167], v162 offset:1024
	ds_read_b128 v[168:171], v162 offset:2048
	ds_read_b128 v[172:175], v162 offset:3072
	ds_read_b128 v[176:179], v163
	ds_read_b128 v[180:183], v163 offset:1024
	ds_read_b128 v[184:187], v163 offset:2048
	ds_read_b128 v[188:191], v163 offset:3072
	ds_read_b128 v[192:195], v161 offset:32768
	ds_read_b128 v[196:199], v161 offset:33792
	ds_read_b128 v[200:203], v161 offset:34816
	ds_read_b128 v[204:207], v161 offset:35840
	ds_read_b128 v[208:211], v161 offset:36864
	ds_read_b128 v[212:215], v161 offset:37888
	ds_read_b128 v[216:219], v161 offset:38912
	ds_read_b128 v[220:223], v161 offset:39936
	s_add_u32 s10, s94, 0x80000
	s_addc_u32 s11, s95, 0
	s_mov_b32 m0, s62
	s_nop 0
	global_load_lds_dwordx4 v151, s[10:11]
	s_nop 0
	s_mov_b32 m0, s63
	s_nop 0
	global_load_lds_dwordx4 v153, s[10:11]
	s_waitcnt lgkmcnt(7)
	v_mfma_i32_16x16x64_i8 v[126:129], v[138:141], v[192:195], v[126:129]
	v_mfma_i32_16x16x64_i8 v[118:121], v[168:171], v[192:195], v[118:121]
	s_waitcnt lgkmcnt(5)
	v_mfma_i32_16x16x64_i8 v[110:113], v[138:141], v[200:203], v[110:113]
	v_mfma_i32_16x16x64_i8 v[102:105], v[168:171], v[200:203], v[102:105]
	s_waitcnt vmcnt(8)
	s_waitcnt lgkmcnt(0)
	s_barrier
	s_setprio 1
	s_waitcnt lgkmcnt(3)
	v_mfma_i32_16x16x64_i8 v[94:97], v[138:141], v[208:211], v[94:97]
	v_mfma_i32_16x16x64_i8 v[86:89], v[168:171], v[208:211], v[86:89]
	s_waitcnt lgkmcnt(1)
	v_mfma_i32_16x16x64_i8 v[78:81], v[138:141], v[216:219], v[78:81]
	v_mfma_i32_16x16x64_i8 v[70:73], v[168:171], v[216:219], v[70:73]
	v_mfma_i32_16x16x64_i8 v[126:129], v[164:167], v[196:199], v[126:129]
	v_mfma_i32_16x16x64_i8 v[118:121], v[172:175], v[196:199], v[118:121]
	v_mfma_i32_16x16x64_i8 v[110:113], v[164:167], v[204:207], v[110:113]
	v_mfma_i32_16x16x64_i8 v[102:105], v[172:175], v[204:207], v[102:105]
	v_mfma_i32_16x16x64_i8 v[94:97], v[164:167], v[212:215], v[94:97]
	v_mfma_i32_16x16x64_i8 v[86:89], v[172:175], v[212:215], v[86:89]
	s_waitcnt lgkmcnt(0)
	v_mfma_i32_16x16x64_i8 v[78:81], v[164:167], v[220:223], v[78:81]
	v_mfma_i32_16x16x64_i8 v[70:73], v[172:175], v[220:223], v[70:73]
	s_setprio 0
	s_setprio 1
	v_mfma_i32_16x16x64_i8 v[122:125], v[176:179], v[192:195], v[122:125]
	v_mfma_i32_16x16x64_i8 v[114:117], v[184:187], v[192:195], v[114:117]
	v_mfma_i32_16x16x64_i8 v[106:109], v[176:179], v[200:203], v[106:109]
	v_mfma_i32_16x16x64_i8 v[98:101], v[184:187], v[200:203], v[98:101]
	v_mfma_i32_16x16x64_i8 v[90:93], v[176:179], v[208:211], v[90:93]
	v_mfma_i32_16x16x64_i8 v[82:85], v[184:187], v[208:211], v[82:85]
	v_mfma_i32_16x16x64_i8 v[74:77], v[176:179], v[216:219], v[74:77]
	v_mfma_i32_16x16x64_i8 v[66:69], v[184:187], v[216:219], v[66:69]
	v_mfma_i32_16x16x64_i8 v[122:125], v[180:183], v[196:199], v[122:125]
	v_mfma_i32_16x16x64_i8 v[114:117], v[188:191], v[196:199], v[114:117]
	v_mfma_i32_16x16x64_i8 v[106:109], v[180:183], v[204:207], v[106:109]
	v_mfma_i32_16x16x64_i8 v[98:101], v[188:191], v[204:207], v[98:101]
	v_mfma_i32_16x16x64_i8 v[90:93], v[180:183], v[212:215], v[90:93]
	v_mfma_i32_16x16x64_i8 v[82:85], v[188:191], v[212:215], v[82:85]
	v_mfma_i32_16x16x64_i8 v[74:77], v[180:183], v[220:223], v[74:77]
	v_mfma_i32_16x16x64_i8 v[66:69], v[188:191], v[220:223], v[66:69]
	s_setprio 0
	s_barrier
	ds_read_b128 v[192:195], v161 offset:49152
	ds_read_b128 v[196:199], v161 offset:50176
	ds_read_b128 v[200:203], v161 offset:51200
	ds_read_b128 v[204:207], v161 offset:52224
	ds_read_b128 v[208:211], v161 offset:53248
	ds_read_b128 v[212:215], v161 offset:54272
	ds_read_b128 v[216:219], v161 offset:55296
	ds_read_b128 v[220:223], v161 offset:56320
	s_add_u32 s10, s92, 0x80
	s_addc_u32 s11, s93, 0
	s_mov_b32 m0, s87
	s_nop 0
	global_load_lds_dwordx4 v152, s[10:11]
	s_nop 0
	s_mov_b32 m0, s96
	s_nop 0
	global_load_lds_dwordx4 v154, s[10:11]
	s_add_u32 s10, s92, 0x80080
	s_addc_u32 s11, s93, 0
	s_mov_b32 m0, s53
	s_nop 0
	global_load_lds_dwordx4 v152, s[10:11]
	s_nop 0
	s_mov_b32 m0, s56
	s_nop 0
	global_load_lds_dwordx4 v154, s[10:11]
	s_nop 0
	s_mov_b32 m0, s97
	s_nop 0
	global_load_lds_dwordx4 v151, s[90:91]
	s_nop 0
	s_mov_b32 m0, s52
	s_nop 0
	global_load_lds_dwordx4 v153, s[90:91]
	s_waitcnt lgkmcnt(7)
	v_mfma_i32_16x16x64_i8 v[62:65], v[138:141], v[192:195], v[62:65]
	v_mfma_i32_16x16x64_i8 v[54:57], v[168:171], v[192:195], v[54:57]
	s_waitcnt lgkmcnt(5)
	v_mfma_i32_16x16x64_i8 v[46:49], v[138:141], v[200:203], v[46:49]
	v_mfma_i32_16x16x64_i8 v[38:41], v[168:171], v[200:203], v[38:41]
	s_waitcnt vmcnt(8)
	s_waitcnt lgkmcnt(0)
	s_barrier
	s_setprio 1
	s_waitcnt lgkmcnt(3)
	v_mfma_i32_16x16x64_i8 v[30:33], v[138:141], v[208:211], v[30:33]
	v_mfma_i32_16x16x64_i8 v[22:25], v[168:171], v[208:211], v[22:25]
	s_waitcnt lgkmcnt(1)
	v_mfma_i32_16x16x64_i8 v[14:17], v[138:141], v[216:219], v[14:17]
	v_mfma_i32_16x16x64_i8 v[6:9], v[168:171], v[216:219], v[6:9]
	v_mfma_i32_16x16x64_i8 v[62:65], v[164:167], v[196:199], v[62:65]
	v_mfma_i32_16x16x64_i8 v[54:57], v[172:175], v[196:199], v[54:57]
	v_mfma_i32_16x16x64_i8 v[46:49], v[164:167], v[204:207], v[46:49]
	v_mfma_i32_16x16x64_i8 v[38:41], v[172:175], v[204:207], v[38:41]
	v_mfma_i32_16x16x64_i8 v[30:33], v[164:167], v[212:215], v[30:33]
	v_mfma_i32_16x16x64_i8 v[22:25], v[172:175], v[212:215], v[22:25]
	s_waitcnt lgkmcnt(0)
	v_mfma_i32_16x16x64_i8 v[14:17], v[164:167], v[220:223], v[14:17]
	v_mfma_i32_16x16x64_i8 v[6:9], v[172:175], v[220:223], v[6:9]
	s_setprio 0
	s_setprio 1
	v_mfma_i32_16x16x64_i8 v[58:61], v[176:179], v[192:195], v[58:61]
	v_mfma_i32_16x16x64_i8 v[50:53], v[184:187], v[192:195], v[50:53]
	v_mfma_i32_16x16x64_i8 v[42:45], v[176:179], v[200:203], v[42:45]
	v_mfma_i32_16x16x64_i8 v[34:37], v[184:187], v[200:203], v[34:37]
	v_mfma_i32_16x16x64_i8 v[26:29], v[176:179], v[208:211], v[26:29]
	v_mfma_i32_16x16x64_i8 v[18:21], v[184:187], v[208:211], v[18:21]
	v_mfma_i32_16x16x64_i8 v[10:13], v[176:179], v[216:219], v[10:13]
	v_mfma_i32_16x16x64_i8 v[2:5], v[184:187], v[216:219], v[2:5]
	v_mfma_i32_16x16x64_i8 v[58:61], v[180:183], v[196:199], v[58:61]
	v_mfma_i32_16x16x64_i8 v[50:53], v[188:191], v[196:199], v[50:53]
	v_mfma_i32_16x16x64_i8 v[42:45], v[180:183], v[204:207], v[42:45]
	v_mfma_i32_16x16x64_i8 v[34:37], v[188:191], v[204:207], v[34:37]
	v_mfma_i32_16x16x64_i8 v[26:29], v[180:183], v[212:215], v[26:29]
	v_mfma_i32_16x16x64_i8 v[18:21], v[188:191], v[212:215], v[18:21]
	v_mfma_i32_16x16x64_i8 v[10:13], v[180:183], v[220:223], v[10:13]
	v_mfma_i32_16x16x64_i8 v[2:5], v[188:191], v[220:223], v[2:5]
	s_setprio 0
	s_barrier
	s_add_i32 s6, s6, 2
	s_add_u32 vcc_lo, vcc_lo, 0x100
	s_addc_u32 vcc_hi, vcc_hi, 0
	s_add_u32 s54, s54, 0x100
	s_addc_u32 s55, s55, 0
	s_add_u32 s88, s88, 0x100
	s_addc_u32 s89, s89, 0
	s_cmp_gt_u32 s6, 29
	s_cbranch_scc0 .LBB0_539
	s_and_b64 vcc, exec, s[66:67]
	s_cbranch_vccz .LBB0_542
	s_barrier

; #define PG8_STAGE(bufoff, gbase, voff) do { if constexpr (VAR != 1 && VAR != 3) { _Pragma("unroll") for (int _i = 0; _i < 2; ++_i) \
;         asm volatile("s_mov_b32 m0, %2\n\ts_nop 0\n\tglobal_load_lds_dwordx4 %0, %1" :: "v"((voff)[_i]), "s"((const char*)(gbase)), "s"(ldsbase + (unsigned)((bufoff) + _i * 8192)) : "memory", "m0"); } } while (0)
; #define PG8_LDA(dst, b, h) do { if constexpr (VAR < 2) _Pragma("unroll") for (int m = 0; m < 4; ++m) _Pragma("unroll") for (int k = 0; k < 2; ++k) dst[m][k] = *(const LAS bf16x8*)(lds + PG8_SA(b, h) + aoff + m * 2048 + k * 1024); } while (0)
; #define PG8_LDB(dst, b, h) do { if constexpr (VAR < 2) _Pragma("unroll") for (int n = 0; n < 2; ++n) _Pragma("unroll") for (int k = 0; k < 2; ++k) dst[n][k] = *(const LAS bf16x8*)(lds + PG8_SB(b, h) + boff + n * 2048 + k * 1024); } while (0)
; #define PG8_WAIT_V(n) asm volatile("s_waitcnt vmcnt(" #n ")" ::: "memory")
; #define PG8_WAIT_L(n) asm volatile("s_waitcnt lgkmcnt(" #n ")" ::: "memory")
; #define PG8_BAR do { if constexpr (VAR != 3) __builtin_amdgcn_s_barrier(); } while (0)
; #define PG8_SCHED __builtin_amdgcn_sched_barrier(0)
;     ...
;         for (int t = 0; t < nt; t += 2) {
;             const bool last = (t == nt - 2);
;             const char* a1 = cA + (size_t)(t + 1) * kstep;
;             const char* a2 = last ? nA : cA + (size_t)(t + 2) * kstep; const char* b2 = last ? nB : cB + (size_t)(t + 2) * kstep;
;             const char* a3 = a2 + kstep; const char* b3 = b2 + kstep;
;             PG8_LDB(B0, 0, 0); PG8_LDB(B1, 0, 1); PG8_SCHED; PG8_LDA(At, 0, 0); PG8_STAGE(PG8_SA(1, 1), a1 + hstepA, voffA);
;             PG8_WAIT_V(8); PG8_WAIT_L(0); PG8_BAR; PG8_MMA(0, 0, At, B0); PG8_MMA(0, 1, At, B1); PG8_BAR; PG8_SCHED;
;             PG8_LDA(At, 0, 1); PG8_STAGE(PG8_SB(0, 0), b2, voffB); PG8_STAGE(PG8_SB(0, 1), b2 + hstepB, voffB); PG8_STAGE(PG8_SA(0, 0), a2, voffA);
;             PG8_WAIT_V(8); PG8_WAIT_L(0); PG8_BAR; PG8_MMA(1, 0, At, B0); PG8_MMA(1, 1, At, B1); PG8_BAR; PG8_SCHED;
.LBB0_561:
	ds_read_b128 v[136:139], v152
	ds_read_b128 v[140:143], v152 offset:1024
	ds_read_b128 v[158:161], v152 offset:2048
	ds_read_b128 v[162:165], v152 offset:3072
	ds_read_b128 v[166:169], v153
	ds_read_b128 v[170:173], v153 offset:1024
	ds_read_b128 v[174:177], v153 offset:2048
	ds_read_b128 v[178:181], v153 offset:3072
	s_cmp_eq_u32 s6, 60
	s_cselect_b32 s84, s14, s65
	s_cselect_b32 s85, s1, s92
	s_cselect_b32 s74, s61, s93
	s_cselect_b32 s75, s15, s94
	s_add_u32 s72, s84, 0x80
	s_addc_u32 s73, s85, 0
	ds_read_b128 v[182:185], v154
	ds_read_b128 v[186:189], v154 offset:1024
	ds_read_b128 v[190:193], v154 offset:2048
	ds_read_b128 v[194:197], v154 offset:3072
	ds_read_b128 v[198:201], v154 offset:4096
	ds_read_b128 v[202:205], v154 offset:5120
	ds_read_b128 v[206:209], v154 offset:6144
	ds_read_b128 v[210:213], v154 offset:7168
	s_mov_b32 m0, s86
	s_nop 0
	global_load_lds_dwordx4 v1, s[70:71]
	s_nop 0
	s_mov_b32 m0, s87
	s_nop 0
	global_load_lds_dwordx4 v147, s[70:71]
	s_waitcnt lgkmcnt(7)
	v_mfma_f32_16x16x32_bf16 v[126:129], v[136:139], v[182:185], v[126:129]
	v_mfma_f32_16x16x32_bf16 v[118:121], v[158:161], v[182:185], v[118:121]
	s_waitcnt lgkmcnt(5)
	v_mfma_f32_16x16x32_bf16 v[110:113], v[136:139], v[190:193], v[110:113]
	v_mfma_f32_16x16x32_bf16 v[102:105], v[158:161], v[190:193], v[102:105]
	s_waitcnt vmcnt(8)
	s_waitcnt lgkmcnt(0)
	s_barrier
	s_setprio 1
	s_waitcnt lgkmcnt(3)
	v_mfma_f32_16x16x32_bf16 v[94:97], v[136:139], v[198:201], v[94:97]
	v_mfma_f32_16x16x32_bf16 v[86:89], v[158:161], v[198:201], v[86:89]
	s_waitcnt lgkmcnt(1)
	v_mfma_f32_16x16x32_bf16 v[78:81], v[136:139], v[206:209], v[78:81]
	v_mfma_f32_16x16x32_bf16 v[70:73], v[158:161], v[206:209], v[70:73]
	v_mfma_f32_16x16x32_bf16 v[126:129], v[140:143], v[186:189], v[126:129]
	v_mfma_f32_16x16x32_bf16 v[118:121], v[162:165], v[186:189], v[118:121]
	v_mfma_f32_16x16x32_bf16 v[110:113], v[140:143], v[194:197], v[110:113]
	v_mfma_f32_16x16x32_bf16 v[102:105], v[162:165], v[194:197], v[102:105]
	v_mfma_f32_16x16x32_bf16 v[94:97], v[140:143], v[202:205], v[94:97]
	v_mfma_f32_16x16x32_bf16 v[86:89], v[162:165], v[202:205], v[86:89]
	s_waitcnt lgkmcnt(0)
	v_mfma_f32_16x16x32_bf16 v[78:81], v[140:143], v[210:213], v[78:81]
	v_mfma_f32_16x16x32_bf16 v[70:73], v[162:165], v[210:213], v[70:73]
	s_setprio 0
	s_setprio 1
	v_mfma_f32_16x16x32_bf16 v[122:125], v[166:169], v[182:185], v[122:125]
	v_mfma_f32_16x16x32_bf16 v[114:117], v[174:177], v[182:185], v[114:117]
	v_mfma_f32_16x16x32_bf16 v[106:109], v[166:169], v[190:193], v[106:109]
	v_mfma_f32_16x16x32_bf16 v[98:101], v[174:177], v[190:193], v[98:101]
	v_mfma_f32_16x16x32_bf16 v[90:93], v[166:169], v[198:201], v[90:93]
	v_mfma_f32_16x16x32_bf16 v[82:85], v[174:177], v[198:201], v[82:85]
	v_mfma_f32_16x16x32_bf16 v[74:77], v[166:169], v[206:209], v[74:77]
	v_mfma_f32_16x16x32_bf16 v[66:69], v[174:177], v[206:209], v[66:69]
	v_mfma_f32_16x16x32_bf16 v[122:125], v[170:173], v[186:189], v[122:125]
	v_mfma_f32_16x16x32_bf16 v[114:117], v[178:181], v[186:189], v[114:117]
	v_mfma_f32_16x16x32_bf16 v[106:109], v[170:173], v[194:197], v[106:109]
	v_mfma_f32_16x16x32_bf16 v[98:101], v[178:181], v[194:197], v[98:101]
	v_mfma_f32_16x16x32_bf16 v[90:93], v[170:173], v[202:205], v[90:93]
	v_mfma_f32_16x16x32_bf16 v[82:85], v[178:181], v[202:205], v[82:85]
	v_mfma_f32_16x16x32_bf16 v[74:77], v[170:173], v[210:213], v[74:77]
	v_mfma_f32_16x16x32_bf16 v[66:69], v[178:181], v[210:213], v[66:69]
	s_setprio 0
	s_barrier
	ds_read_b128 v[182:185], v154 offset:16384
	ds_read_b128 v[186:189], v154 offset:17408
	ds_read_b128 v[190:193], v154 offset:18432
	ds_read_b128 v[194:197], v154 offset:19456
	ds_read_b128 v[198:201], v154 offset:20480
	ds_read_b128 v[202:205], v154 offset:21504
	ds_read_b128 v[206:209], v154 offset:22528
	ds_read_b128 v[210:213], v154 offset:23552
	s_mov_b32 m0, s21
	s_nop 0
	global_load_lds_dwordx4 v146, s[74:75]
	s_add_u32 s10, s74, 0x100000
	s_mov_b32 m0, s23
	s_nop 0
	global_load_lds_dwordx4 v148, s[74:75]
	s_addc_u32 s11, s75, 0
	s_mov_b32 m0, s29
	s_nop 0
	global_load_lds_dwordx4 v146, s[10:11]
	s_nop 0
	s_mov_b32 m0, s30
	s_nop 0
	global_load_lds_dwordx4 v148, s[10:11]
	s_nop 0
	s_mov_b32 m0, s25
	s_nop 0
	global_load_lds_dwordx4 v1, s[84:85]
	s_nop 0
	s_mov_b32 m0, s31
	s_nop 0
	global_load_lds_dwordx4 v147, s[84:85]
	s_waitcnt lgkmcnt(7)
	v_mfma_f32_16x16x32_bf16 v[62:65], v[136:139], v[182:185], v[62:65]
	v_mfma_f32_16x16x32_bf16 v[54:57], v[158:161], v[182:185], v[54:57]
	s_waitcnt lgkmcnt(5)
	v_mfma_f32_16x16x32_bf16 v[46:49], v[136:139], v[190:193], v[46:49]
	v_mfma_f32_16x16x32_bf16 v[38:41], v[158:161], v[190:193], v[38:41]
	s_waitcnt vmcnt(8)
	s_waitcnt lgkmcnt(0)
	s_barrier
; #define PG8_STAGE(bufoff, gbase, voff) do { if constexpr (VAR != 1 && VAR != 3) { _Pragma("unroll") for (int _i = 0; _i < 2; ++_i) \
;         asm volatile("s_mov_b32 m0, %2\n\ts_nop 0\n\tglobal_load_lds_dwordx4 %0, %1" :: "v"((voff)[_i]), "s"((const char*)(gbase)), "s"(ldsbase + (unsigned)((bufoff) + _i * 8192)) : "memory", "m0"); } } while (0)
; #define PG8_LDA(dst, b, h) do { if constexpr (VAR < 2) _Pragma("unroll") for (int m = 0; m < 4; ++m) _Pragma("unroll") for (int k = 0; k < 2; ++k) dst[m][k] = *(const LAS bf16x8*)(lds + PG8_SA(b, h) + aoff + m * 2048 + k * 1024); } while (0)
; #define PG8_LDB(dst, b, h) do { if constexpr (VAR < 2) _Pragma("unroll") for (int n = 0; n < 2; ++n) _Pragma("unroll") for (int k = 0; k < 2; ++k) dst[n][k] = *(const LAS bf16x8*)(lds + PG8_SB(b, h) + boff + n * 2048 + k * 1024); } while (0)
; #define PG8_WAIT_V(n) asm volatile("s_waitcnt vmcnt(" #n ")" ::: "memory")
; #define PG8_WAIT_L(n) asm volatile("s_waitcnt lgkmcnt(" #n ")" ::: "memory")
; #define PG8_BAR do { if constexpr (VAR != 3) __builtin_amdgcn_s_barrier(); } while (0)
; #define PG8_SCHED __builtin_amdgcn_sched_barrier(0)
;     ...
;             PG8_WAIT_V(8); PG8_WAIT_L(0); PG8_BAR; PG8_MMA(1, 0, At, B0); PG8_MMA(1, 1, At, B1); PG8_BAR; PG8_SCHED;
;             PG8_LDB(B0, 1, 0); PG8_LDB(B1, 1, 1); PG8_SCHED; PG8_LDA(At, 1, 0); PG8_STAGE(PG8_SA(0, 1), a2 + hstepA, voffA);
;             PG8_WAIT_V(8); PG8_WAIT_L(0); PG8_BAR; PG8_MMA(0, 0, At, B0); PG8_MMA(0, 1, At, B1); PG8_BAR; PG8_SCHED;
	s_setprio 1
	s_waitcnt lgkmcnt(3)
	v_mfma_f32_16x16x32_bf16 v[30:33], v[136:139], v[198:201], v[30:33]
	v_mfma_f32_16x16x32_bf16 v[22:25], v[158:161], v[198:201], v[22:25]
	s_waitcnt lgkmcnt(1)
	v_mfma_f32_16x16x32_bf16 v[14:17], v[136:139], v[206:209], v[14:17]
	v_mfma_f32_16x16x32_bf16 v[6:9], v[158:161], v[206:209], v[6:9]
	v_mfma_f32_16x16x32_bf16 v[62:65], v[140:143], v[186:189], v[62:65]
	v_mfma_f32_16x16x32_bf16 v[54:57], v[162:165], v[186:189], v[54:57]
	v_mfma_f32_16x16x32_bf16 v[46:49], v[140:143], v[194:197], v[46:49]
	v_mfma_f32_16x16x32_bf16 v[38:41], v[162:165], v[194:197], v[38:41]
	v_mfma_f32_16x16x32_bf16 v[30:33], v[140:143], v[202:205], v[30:33]
	v_mfma_f32_16x16x32_bf16 v[22:25], v[162:165], v[202:205], v[22:25]
	s_waitcnt lgkmcnt(0)
	v_mfma_f32_16x16x32_bf16 v[14:17], v[140:143], v[210:213], v[14:17]
	v_mfma_f32_16x16x32_bf16 v[6:9], v[162:165], v[210:213], v[6:9]
	s_setprio 0
	s_setprio 1
	v_mfma_f32_16x16x32_bf16 v[58:61], v[166:169], v[182:185], v[58:61]
	v_mfma_f32_16x16x32_bf16 v[50:53], v[174:177], v[182:185], v[50:53]
	v_mfma_f32_16x16x32_bf16 v[42:45], v[166:169], v[190:193], v[42:45]
	v_mfma_f32_16x16x32_bf16 v[34:37], v[174:177], v[190:193], v[34:37]
	v_mfma_f32_16x16x32_bf16 v[26:29], v[166:169], v[198:201], v[26:29]
	v_mfma_f32_16x16x32_bf16 v[18:21], v[174:177], v[198:201], v[18:21]
	v_mfma_f32_16x16x32_bf16 v[10:13], v[166:169], v[206:209], v[10:13]
	v_mfma_f32_16x16x32_bf16 v[2:5], v[174:177], v[206:209], v[2:5]
	v_mfma_f32_16x16x32_bf16 v[58:61], v[170:173], v[186:189], v[58:61]
	v_mfma_f32_16x16x32_bf16 v[50:53], v[178:181], v[186:189], v[50:53]
	v_mfma_f32_16x16x32_bf16 v[42:45], v[170:173], v[194:197], v[42:45]
	v_mfma_f32_16x16x32_bf16 v[34:37], v[178:181], v[194:197], v[34:37]
	v_mfma_f32_16x16x32_bf16 v[26:29], v[170:173], v[202:205], v[26:29]
	v_mfma_f32_16x16x32_bf16 v[18:21], v[178:181], v[202:205], v[18:21]
	v_mfma_f32_16x16x32_bf16 v[10:13], v[170:173], v[210:213], v[10:13]
	v_mfma_f32_16x16x32_bf16 v[2:5], v[178:181], v[210:213], v[2:5]
	s_setprio 0
	s_barrier
	ds_read_b128 v[136:139], v155
	ds_read_b128 v[140:143], v155 offset:1024
	ds_read_b128 v[158:161], v155 offset:2048
	ds_read_b128 v[162:165], v155 offset:3072
	ds_read_b128 v[166:169], v156
	ds_read_b128 v[170:173], v156 offset:1024
	ds_read_b128 v[174:177], v156 offset:2048
	ds_read_b128 v[178:181], v156 offset:3072
	ds_read_b128 v[182:185], v154 offset:32768
	ds_read_b128 v[186:189], v154 offset:33792
	ds_read_b128 v[190:193], v154 offset:34816
	ds_read_b128 v[194:197], v154 offset:35840
	ds_read_b128 v[198:201], v154 offset:36864
	ds_read_b128 v[202:205], v154 offset:37888
	ds_read_b128 v[206:209], v154 offset:38912
	ds_read_b128 v[210:213], v154 offset:39936
	s_add_u32 s10, s84, 0x100000
	s_addc_u32 s11, s85, 0
	s_mov_b32 m0, s33
	s_nop 0
	global_load_lds_dwordx4 v1, s[10:11]
	s_nop 0
	s_mov_b32 m0, s35
	s_nop 0
	global_load_lds_dwordx4 v147, s[10:11]
	s_waitcnt lgkmcnt(7)
	v_mfma_f32_16x16x32_bf16 v[126:129], v[136:139], v[182:185], v[126:129]
	v_mfma_f32_16x16x32_bf16 v[118:121], v[158:161], v[182:185], v[118:121]
	s_waitcnt lgkmcnt(5)
	v_mfma_f32_16x16x32_bf16 v[110:113], v[136:139], v[190:193], v[110:113]
	v_mfma_f32_16x16x32_bf16 v[102:105], v[158:161], v[190:193], v[102:105]
	s_waitcnt vmcnt(8)
	s_waitcnt lgkmcnt(0)
	s_barrier
	s_setprio 1
	s_waitcnt lgkmcnt(3)
	v_mfma_f32_16x16x32_bf16 v[94:97], v[136:139], v[198:201], v[94:97]
	v_mfma_f32_16x16x32_bf16 v[86:89], v[158:161], v[198:201], v[86:89]
	s_waitcnt lgkmcnt(1)
	v_mfma_f32_16x16x32_bf16 v[78:81], v[136:139], v[206:209], v[78:81]
	v_mfma_f32_16x16x32_bf16 v[70:73], v[158:161], v[206:209], v[70:73]
	v_mfma_f32_16x16x32_bf16 v[126:129], v[140:143], v[186:189], v[126:129]
	v_mfma_f32_16x16x32_bf16 v[118:121], v[162:165], v[186:189], v[118:121]
	v_mfma_f32_16x16x32_bf16 v[110:113], v[140:143], v[194:197], v[110:113]
	v_mfma_f32_16x16x32_bf16 v[102:105], v[162:165], v[194:197], v[102:105]
	v_mfma_f32_16x16x32_bf16 v[94:97], v[140:143], v[202:205], v[94:97]
	v_mfma_f32_16x16x32_bf16 v[86:89], v[162:165], v[202:205], v[86:89]
	s_waitcnt lgkmcnt(0)
	v_mfma_f32_16x16x32_bf16 v[78:81], v[140:143], v[210:213], v[78:81]
	v_mfma_f32_16x16x32_bf16 v[70:73], v[162:165], v[210:213], v[70:73]
	s_setprio 0
	s_setprio 1
	v_mfma_f32_16x16x32_bf16 v[122:125], v[166:169], v[182:185], v[122:125]
	v_mfma_f32_16x16x32_bf16 v[114:117], v[174:177], v[182:185], v[114:117]
	v_mfma_f32_16x16x32_bf16 v[106:109], v[166:169], v[190:193], v[106:109]
	v_mfma_f32_16x16x32_bf16 v[98:101], v[174:177], v[190:193], v[98:101]
	v_mfma_f32_16x16x32_bf16 v[90:93], v[166:169], v[198:201], v[90:93]
	v_mfma_f32_16x16x32_bf16 v[82:85], v[174:177], v[198:201], v[82:85]
	v_mfma_f32_16x16x32_bf16 v[74:77], v[166:169], v[206:209], v[74:77]
	v_mfma_f32_16x16x32_bf16 v[66:69], v[174:177], v[206:209], v[66:69]
	v_mfma_f32_16x16x32_bf16 v[122:125], v[170:173], v[186:189], v[122:125]
	v_mfma_f32_16x16x32_bf16 v[114:117], v[178:181], v[186:189], v[114:117]
	v_mfma_f32_16x16x32_bf16 v[106:109], v[170:173], v[194:197], v[106:109]
	v_mfma_f32_16x16x32_bf16 v[98:101], v[178:181], v[194:197], v[98:101]
	v_mfma_f32_16x16x32_bf16 v[90:93], v[170:173], v[202:205], v[90:93]
	v_mfma_f32_16x16x32_bf16 v[82:85], v[178:181], v[202:205], v[82:85]
	v_mfma_f32_16x16x32_bf16 v[74:77], v[170:173], v[210:213], v[74:77]
	v_mfma_f32_16x16x32_bf16 v[66:69], v[178:181], v[210:213], v[66:69]
	s_setprio 0
	s_barrier
; #define PG8_STAGE(bufoff, gbase, voff) do { if constexpr (VAR != 1 && VAR != 3) { _Pragma("unroll") for (int _i = 0; _i < 2; ++_i) \
;         asm volatile("s_mov_b32 m0, %2\n\ts_nop 0\n\tglobal_load_lds_dwordx4 %0, %1" :: "v"((voff)[_i]), "s"((const char*)(gbase)), "s"(ldsbase + (unsigned)((bufoff) + _i * 8192)) : "memory", "m0"); } } while (0)
; #define PG8_LDA(dst, b, h) do { if constexpr (VAR < 2) _Pragma("unroll") for (int m = 0; m < 4; ++m) _Pragma("unroll") for (int k = 0; k < 2; ++k) dst[m][k] = *(const LAS bf16x8*)(lds + PG8_SA(b, h) + aoff + m * 2048 + k * 1024); } while (0)
; #define PG8_WAIT_V(n) asm volatile("s_waitcnt vmcnt(" #n ")" ::: "memory")
; #define PG8_WAIT_L(n) asm volatile("s_waitcnt lgkmcnt(" #n ")" ::: "memory")
; #define PG8_BAR do { if constexpr (VAR != 3) __builtin_amdgcn_s_barrier(); } while (0)
; #define PG8_SCHED __builtin_amdgcn_sched_barrier(0)
;     ...
;             PG8_LDA(At, 1, 1); PG8_STAGE(PG8_SB(1, 0), b3, voffB); PG8_STAGE(PG8_SB(1, 1), b3 + hstepB, voffB); PG8_STAGE(PG8_SA(1, 0), a3, voffA);
;             PG8_WAIT_V(8); PG8_WAIT_L(0); PG8_BAR; PG8_MMA(1, 0, At, B0); PG8_MMA(1, 1, At, B1); PG8_BAR; PG8_SCHED;
;         }
;         if (wr == 0) PG8_BAR;
	ds_read_b128 v[182:185], v154 offset:49152
	ds_read_b128 v[186:189], v154 offset:50176
	ds_read_b128 v[190:193], v154 offset:51200
	ds_read_b128 v[194:197], v154 offset:52224
	ds_read_b128 v[198:201], v154 offset:53248
	ds_read_b128 v[202:205], v154 offset:54272
	ds_read_b128 v[206:209], v154 offset:55296
	ds_read_b128 v[210:213], v154 offset:56320
	s_add_u32 s10, s74, 0x80
	s_addc_u32 s11, s75, 0
	s_mov_b32 m0, s52
	s_nop 0
	global_load_lds_dwordx4 v146, s[10:11]
	s_nop 0
	s_mov_b32 m0, s53
	s_nop 0
	global_load_lds_dwordx4 v148, s[10:11]
	s_add_u32 s10, s74, 0x100080
	s_addc_u32 s11, s75, 0
	s_mov_b32 m0, s62
	s_nop 0
	global_load_lds_dwordx4 v146, s[10:11]
	s_nop 0
	s_mov_b32 m0, s63
	s_nop 0
	global_load_lds_dwordx4 v148, s[10:11]
	s_nop 0
	s_mov_b32 m0, s56
	s_nop 0
	global_load_lds_dwordx4 v1, s[72:73]
	s_nop 0
	s_mov_b32 m0, s57
	s_nop 0
	global_load_lds_dwordx4 v147, s[72:73]
	s_waitcnt lgkmcnt(7)
	v_mfma_f32_16x16x32_bf16 v[62:65], v[136:139], v[182:185], v[62:65]
	v_mfma_f32_16x16x32_bf16 v[54:57], v[158:161], v[182:185], v[54:57]
	s_waitcnt lgkmcnt(5)
	v_mfma_f32_16x16x32_bf16 v[46:49], v[136:139], v[190:193], v[46:49]
	v_mfma_f32_16x16x32_bf16 v[38:41], v[158:161], v[190:193], v[38:41]
	s_waitcnt vmcnt(8)
	s_waitcnt lgkmcnt(0)
	s_barrier
	s_setprio 1
	s_waitcnt lgkmcnt(3)
	v_mfma_f32_16x16x32_bf16 v[30:33], v[136:139], v[198:201], v[30:33]
	v_mfma_f32_16x16x32_bf16 v[22:25], v[158:161], v[198:201], v[22:25]
	s_waitcnt lgkmcnt(1)
	v_mfma_f32_16x16x32_bf16 v[14:17], v[136:139], v[206:209], v[14:17]
	v_mfma_f32_16x16x32_bf16 v[6:9], v[158:161], v[206:209], v[6:9]
	v_mfma_f32_16x16x32_bf16 v[62:65], v[140:143], v[186:189], v[62:65]
	v_mfma_f32_16x16x32_bf16 v[54:57], v[162:165], v[186:189], v[54:57]
	v_mfma_f32_16x16x32_bf16 v[46:49], v[140:143], v[194:197], v[46:49]
	v_mfma_f32_16x16x32_bf16 v[38:41], v[162:165], v[194:197], v[38:41]
	v_mfma_f32_16x16x32_bf16 v[30:33], v[140:143], v[202:205], v[30:33]
	v_mfma_f32_16x16x32_bf16 v[22:25], v[162:165], v[202:205], v[22:25]
	s_waitcnt lgkmcnt(0)
	v_mfma_f32_16x16x32_bf16 v[14:17], v[140:143], v[210:213], v[14:17]
	v_mfma_f32_16x16x32_bf16 v[6:9], v[162:165], v[210:213], v[6:9]
	s_setprio 0
	s_setprio 1
	v_mfma_f32_16x16x32_bf16 v[58:61], v[166:169], v[182:185], v[58:61]
	v_mfma_f32_16x16x32_bf16 v[50:53], v[174:177], v[182:185], v[50:53]
	v_mfma_f32_16x16x32_bf16 v[42:45], v[166:169], v[190:193], v[42:45]
	v_mfma_f32_16x16x32_bf16 v[34:37], v[174:177], v[190:193], v[34:37]
	v_mfma_f32_16x16x32_bf16 v[26:29], v[166:169], v[198:201], v[26:29]
	v_mfma_f32_16x16x32_bf16 v[18:21], v[174:177], v[198:201], v[18:21]
	v_mfma_f32_16x16x32_bf16 v[10:13], v[166:169], v[206:209], v[10:13]
	v_mfma_f32_16x16x32_bf16 v[2:5], v[174:177], v[206:209], v[2:5]
	v_mfma_f32_16x16x32_bf16 v[58:61], v[170:173], v[186:189], v[58:61]
	v_mfma_f32_16x16x32_bf16 v[50:53], v[178:181], v[186:189], v[50:53]
	v_mfma_f32_16x16x32_bf16 v[42:45], v[170:173], v[194:197], v[42:45]
	v_mfma_f32_16x16x32_bf16 v[34:37], v[178:181], v[194:197], v[34:37]
	v_mfma_f32_16x16x32_bf16 v[26:29], v[170:173], v[202:205], v[26:29]
	v_mfma_f32_16x16x32_bf16 v[18:21], v[178:181], v[202:205], v[18:21]
	v_mfma_f32_16x16x32_bf16 v[10:13], v[170:173], v[210:213], v[10:13]
	v_mfma_f32_16x16x32_bf16 v[2:5], v[178:181], v[210:213], v[2:5]
	s_setprio 0
	s_barrier
	s_add_i32 s6, s6, 2
	s_add_u32 s65, s65, 0x100
	s_addc_u32 s92, s92, 0
	s_add_u32 s93, s93, 0x100
	s_addc_u32 s94, s94, 0
	s_add_u32 s70, s70, 0x100
	s_addc_u32 s71, s71, 0
	s_cmp_gt_u32 s6, 61
	s_cbranch_scc0 .LBB0_561
	s_and_b64 vcc, exec, s[54:55]
	s_cbranch_vccz .LBB0_564
	s_barrier

; #define PG8_STAGE(bufoff, gbase, voff) do { if constexpr (VAR != 1 && VAR != 3) { _Pragma("unroll") for (int _i = 0; _i < 2; ++_i) \
;         asm volatile("s_mov_b32 m0, %2\n\ts_nop 0\n\tglobal_load_lds_dwordx4 %0, %1" :: "v"((voff)[_i]), "s"((const char*)(gbase)), "s"(ldsbase + (unsigned)((bufoff) + _i * 8192)) : "memory", "m0"); } } while (0)
; #define PG8_LDA(dst, b, h) do { if constexpr (VAR < 2) _Pragma("unroll") for (int m = 0; m < 4; ++m) _Pragma("unroll") for (int k = 0; k < 2; ++k) dst[m][k] = *(const LAS bf16x8*)(lds + PG8_SA(b, h) + aoff + m * 2048 + k * 1024); } while (0)
; #define PG8_LDB(dst, b, h) do { if constexpr (VAR < 2) _Pragma("unroll") for (int n = 0; n < 2; ++n) _Pragma("unroll") for (int k = 0; k < 2; ++k) dst[n][k] = *(const LAS bf16x8*)(lds + PG8_SB(b, h) + boff + n * 2048 + k * 1024); } while (0)
; #define PG8_WAIT_V(n) asm volatile("s_waitcnt vmcnt(" #n ")" ::: "memory")
; #define PG8_WAIT_L(n) asm volatile("s_waitcnt lgkmcnt(" #n ")" ::: "memory")
; #define PG8_BAR do { if constexpr (VAR != 3) __builtin_amdgcn_s_barrier(); } while (0)
; #define PG8_SCHED __builtin_amdgcn_sched_barrier(0)
;     ...
;         for (int t = 0; t < nt; t += 2) {
;             const bool last = (t == nt - 2);
;             const char* a1 = cA + (size_t)(t + 1) * kstep;
;             const char* a2 = last ? nA : cA + (size_t)(t + 2) * kstep; const char* b2 = last ? nB : cB + (size_t)(t + 2) * kstep;
;             const char* a3 = a2 + kstep; const char* b3 = b2 + kstep;
;             PG8_LDB(B0, 0, 0); PG8_LDB(B1, 0, 1); PG8_SCHED; PG8_LDA(At, 0, 0); PG8_STAGE(PG8_SA(1, 1), a1 + hstepA, voffA);
;             PG8_WAIT_V(8); PG8_WAIT_L(0); PG8_BAR; PG8_MMA(0, 0, At, B0); PG8_MMA(0, 1, At, B1); PG8_BAR; PG8_SCHED;
;             PG8_LDA(At, 0, 1); PG8_STAGE(PG8_SB(0, 0), b2, voffB); PG8_STAGE(PG8_SB(0, 1), b2 + hstepB, voffB); PG8_STAGE(PG8_SA(0, 0), a2, voffA);
;             PG8_WAIT_V(8); PG8_WAIT_L(0); PG8_BAR; PG8_MMA(1, 0, At, B0); PG8_MMA(1, 1, At, B1); PG8_BAR; PG8_SCHED;
.LBB0_673:
	ds_read_b128 v[150:153], v183
	ds_read_b128 v[154:157], v183 offset:1024
	ds_read_b128 v[158:161], v183 offset:2048
	ds_read_b128 v[162:165], v183 offset:3072
	ds_read_b128 v[166:169], v184
	ds_read_b128 v[188:191], v184 offset:1024
	ds_read_b128 v[192:195], v184 offset:2048
	ds_read_b128 v[196:199], v184 offset:3072
	s_cmp_eq_u32 s6, 12
	s_cselect_b32 s82, s0, s75
	s_cselect_b32 s83, s1, s92
	s_cselect_b32 s80, s76, s93
	s_cselect_b32 s81, s77, s94
	s_add_u32 s78, s82, 0x80
	s_addc_u32 s79, s83, 0
	ds_read_b128 v[200:203], v185
	ds_read_b128 v[204:207], v185 offset:1024
	ds_read_b128 v[208:211], v185 offset:2048
	ds_read_b128 v[212:215], v185 offset:3072
	ds_read_b128 v[216:219], v185 offset:4096
	ds_read_b128 v[220:223], v185 offset:5120
	ds_read_b128 v[224:227], v185 offset:6144
	ds_read_b128 v[228:231], v185 offset:7168
	s_mov_b32 m0, s85
	s_nop 0
	global_load_lds_dwordx4 v178, s[4:5]
	s_nop 0
	s_mov_b32 m0, s86
	s_nop 0
	global_load_lds_dwordx4 v180, s[4:5]
	s_waitcnt lgkmcnt(7)
	v_mfma_f32_16x16x32_bf16 v[126:129], v[150:153], v[200:203], v[126:129]
	v_mfma_f32_16x16x32_bf16 v[122:125], v[158:161], v[200:203], v[122:125]
	s_waitcnt lgkmcnt(5)
	v_mfma_f32_16x16x32_bf16 v[114:117], v[150:153], v[208:211], v[114:117]
	v_mfma_f32_16x16x32_bf16 v[106:109], v[158:161], v[208:211], v[106:109]
	s_waitcnt vmcnt(8)
	s_waitcnt lgkmcnt(0)
	s_barrier
	s_setprio 1
	s_waitcnt lgkmcnt(3)
	v_mfma_f32_16x16x32_bf16 v[98:101], v[150:153], v[216:219], v[98:101]
	v_mfma_f32_16x16x32_bf16 v[90:93], v[158:161], v[216:219], v[90:93]
	s_waitcnt lgkmcnt(1)
	v_mfma_f32_16x16x32_bf16 v[82:85], v[150:153], v[224:227], v[82:85]
	v_mfma_f32_16x16x32_bf16 v[74:77], v[158:161], v[224:227], v[74:77]
	v_mfma_f32_16x16x32_bf16 v[126:129], v[154:157], v[204:207], v[126:129]
	v_mfma_f32_16x16x32_bf16 v[122:125], v[162:165], v[204:207], v[122:125]
	v_mfma_f32_16x16x32_bf16 v[114:117], v[154:157], v[212:215], v[114:117]
	v_mfma_f32_16x16x32_bf16 v[106:109], v[162:165], v[212:215], v[106:109]
	v_mfma_f32_16x16x32_bf16 v[98:101], v[154:157], v[220:223], v[98:101]
	v_mfma_f32_16x16x32_bf16 v[90:93], v[162:165], v[220:223], v[90:93]
	s_waitcnt lgkmcnt(0)
	v_mfma_f32_16x16x32_bf16 v[82:85], v[154:157], v[228:231], v[82:85]
	v_mfma_f32_16x16x32_bf16 v[74:77], v[162:165], v[228:231], v[74:77]
	s_setprio 0
	s_setprio 1
	v_mfma_f32_16x16x32_bf16 v[118:121], v[166:169], v[200:203], v[118:121]
	v_mfma_f32_16x16x32_bf16 v[110:113], v[192:195], v[200:203], v[110:113]
	v_mfma_f32_16x16x32_bf16 v[102:105], v[166:169], v[208:211], v[102:105]
	v_mfma_f32_16x16x32_bf16 v[94:97], v[192:195], v[208:211], v[94:97]
	v_mfma_f32_16x16x32_bf16 v[86:89], v[166:169], v[216:219], v[86:89]
	v_mfma_f32_16x16x32_bf16 v[78:81], v[192:195], v[216:219], v[78:81]
	v_mfma_f32_16x16x32_bf16 v[70:73], v[166:169], v[224:227], v[70:73]
	v_mfma_f32_16x16x32_bf16 v[66:69], v[192:195], v[224:227], v[66:69]
	v_mfma_f32_16x16x32_bf16 v[118:121], v[188:191], v[204:207], v[118:121]
	v_mfma_f32_16x16x32_bf16 v[110:113], v[196:199], v[204:207], v[110:113]
	v_mfma_f32_16x16x32_bf16 v[102:105], v[188:191], v[212:215], v[102:105]
	v_mfma_f32_16x16x32_bf16 v[94:97], v[196:199], v[212:215], v[94:97]
	v_mfma_f32_16x16x32_bf16 v[86:89], v[188:191], v[220:223], v[86:89]
	v_mfma_f32_16x16x32_bf16 v[78:81], v[196:199], v[220:223], v[78:81]
	v_mfma_f32_16x16x32_bf16 v[70:73], v[188:191], v[228:231], v[70:73]
	v_mfma_f32_16x16x32_bf16 v[66:69], v[196:199], v[228:231], v[66:69]
	s_setprio 0
	s_barrier
	ds_read_b128 v[200:203], v185 offset:16384
	ds_read_b128 v[204:207], v185 offset:17408
	ds_read_b128 v[208:211], v185 offset:18432
	ds_read_b128 v[212:215], v185 offset:19456
	ds_read_b128 v[216:219], v185 offset:20480
	ds_read_b128 v[220:223], v185 offset:21504
	ds_read_b128 v[224:227], v185 offset:22528
	ds_read_b128 v[228:231], v185 offset:23552
	s_mov_b32 m0, s24
	s_nop 0
	global_load_lds_dwordx4 v179, s[80:81]
	s_add_u32 s96, s80, 0x100000
	s_mov_b32 m0, s25
	s_nop 0
	global_load_lds_dwordx4 v181, s[80:81]
	s_addc_u32 s97, s81, 0
	s_mov_b32 m0, s26
	s_nop 0
	global_load_lds_dwordx4 v179, s[96:97]
	s_nop 0
	s_mov_b32 m0, s27
	s_nop 0
	global_load_lds_dwordx4 v181, s[96:97]
	s_nop 0
	s_mov_b32 m0, s15
	s_nop 0
	global_load_lds_dwordx4 v178, s[82:83]
	s_nop 0
	s_mov_b32 m0, s28
	s_nop 0
	global_load_lds_dwordx4 v180, s[82:83]
	s_waitcnt lgkmcnt(7)
	v_mfma_f32_16x16x32_bf16 v[62:65], v[150:153], v[200:203], v[62:65]
	v_mfma_f32_16x16x32_bf16 v[58:61], v[158:161], v[200:203], v[58:61]
	s_waitcnt lgkmcnt(5)
	v_mfma_f32_16x16x32_bf16 v[50:53], v[150:153], v[208:211], v[50:53]
	v_mfma_f32_16x16x32_bf16 v[42:45], v[158:161], v[208:211], v[42:45]
	s_waitcnt vmcnt(8)
	s_waitcnt lgkmcnt(0)
	s_barrier
; #define PG8_STAGE(bufoff, gbase, voff) do { if constexpr (VAR != 1 && VAR != 3) { _Pragma("unroll") for (int _i = 0; _i < 2; ++_i) \
;         asm volatile("s_mov_b32 m0, %2\n\ts_nop 0\n\tglobal_load_lds_dwordx4 %0, %1" :: "v"((voff)[_i]), "s"((const char*)(gbase)), "s"(ldsbase + (unsigned)((bufoff) + _i * 8192)) : "memory", "m0"); } } while (0)
; #define PG8_LDA(dst, b, h) do { if constexpr (VAR < 2) _Pragma("unroll") for (int m = 0; m < 4; ++m) _Pragma("unroll") for (int k = 0; k < 2; ++k) dst[m][k] = *(const LAS bf16x8*)(lds + PG8_SA(b, h) + aoff + m * 2048 + k * 1024); } while (0)
; #define PG8_LDB(dst, b, h) do { if constexpr (VAR < 2) _Pragma("unroll") for (int n = 0; n < 2; ++n) _Pragma("unroll") for (int k = 0; k < 2; ++k) dst[n][k] = *(const LAS bf16x8*)(lds + PG8_SB(b, h) + boff + n * 2048 + k * 1024); } while (0)
; #define PG8_WAIT_V(n) asm volatile("s_waitcnt vmcnt(" #n ")" ::: "memory")
; #define PG8_WAIT_L(n) asm volatile("s_waitcnt lgkmcnt(" #n ")" ::: "memory")
; #define PG8_BAR do { if constexpr (VAR != 3) __builtin_amdgcn_s_barrier(); } while (0)
; #define PG8_SCHED __builtin_amdgcn_sched_barrier(0)
;     ...
;             PG8_WAIT_V(8); PG8_WAIT_L(0); PG8_BAR; PG8_MMA(1, 0, At, B0); PG8_MMA(1, 1, At, B1); PG8_BAR; PG8_SCHED;
;             PG8_LDB(B0, 1, 0); PG8_LDB(B1, 1, 1); PG8_SCHED; PG8_LDA(At, 1, 0); PG8_STAGE(PG8_SA(0, 1), a2 + hstepA, voffA);
;             PG8_WAIT_V(8); PG8_WAIT_L(0); PG8_BAR; PG8_MMA(0, 0, At, B0); PG8_MMA(0, 1, At, B1); PG8_BAR; PG8_SCHED;
	s_setprio 1
	s_waitcnt lgkmcnt(3)
	v_mfma_f32_16x16x32_bf16 v[34:37], v[150:153], v[216:219], v[34:37]
	v_mfma_f32_16x16x32_bf16 v[26:29], v[158:161], v[216:219], v[26:29]
	s_waitcnt lgkmcnt(1)
	v_mfma_f32_16x16x32_bf16 v[18:21], v[150:153], v[224:227], v[18:21]
	v_mfma_f32_16x16x32_bf16 v[10:13], v[158:161], v[224:227], v[10:13]
	v_mfma_f32_16x16x32_bf16 v[62:65], v[154:157], v[204:207], v[62:65]
	v_mfma_f32_16x16x32_bf16 v[58:61], v[162:165], v[204:207], v[58:61]
	v_mfma_f32_16x16x32_bf16 v[50:53], v[154:157], v[212:215], v[50:53]
	v_mfma_f32_16x16x32_bf16 v[42:45], v[162:165], v[212:215], v[42:45]
	v_mfma_f32_16x16x32_bf16 v[34:37], v[154:157], v[220:223], v[34:37]
	v_mfma_f32_16x16x32_bf16 v[26:29], v[162:165], v[220:223], v[26:29]
	s_waitcnt lgkmcnt(0)
	v_mfma_f32_16x16x32_bf16 v[18:21], v[154:157], v[228:231], v[18:21]
	v_mfma_f32_16x16x32_bf16 v[10:13], v[162:165], v[228:231], v[10:13]
	s_setprio 0
	s_setprio 1
	v_mfma_f32_16x16x32_bf16 v[54:57], v[166:169], v[200:203], v[54:57]
	v_mfma_f32_16x16x32_bf16 v[46:49], v[192:195], v[200:203], v[46:49]
	v_mfma_f32_16x16x32_bf16 v[38:41], v[166:169], v[208:211], v[38:41]
	v_mfma_f32_16x16x32_bf16 v[30:33], v[192:195], v[208:211], v[30:33]
	v_mfma_f32_16x16x32_bf16 v[22:25], v[166:169], v[216:219], v[22:25]
	v_mfma_f32_16x16x32_bf16 v[14:17], v[192:195], v[216:219], v[14:17]
	v_mfma_f32_16x16x32_bf16 v[6:9], v[166:169], v[224:227], v[6:9]
	v_mfma_f32_16x16x32_bf16 v[2:5], v[192:195], v[224:227], v[2:5]
	v_mfma_f32_16x16x32_bf16 v[54:57], v[188:191], v[204:207], v[54:57]
	v_mfma_f32_16x16x32_bf16 v[46:49], v[196:199], v[204:207], v[46:49]
	v_mfma_f32_16x16x32_bf16 v[38:41], v[188:191], v[212:215], v[38:41]
	v_mfma_f32_16x16x32_bf16 v[30:33], v[196:199], v[212:215], v[30:33]
	v_mfma_f32_16x16x32_bf16 v[22:25], v[188:191], v[220:223], v[22:25]
	v_mfma_f32_16x16x32_bf16 v[14:17], v[196:199], v[220:223], v[14:17]
	v_mfma_f32_16x16x32_bf16 v[6:9], v[188:191], v[228:231], v[6:9]
	v_mfma_f32_16x16x32_bf16 v[2:5], v[196:199], v[228:231], v[2:5]
	s_setprio 0
	s_barrier
	ds_read_b128 v[150:153], v186
	ds_read_b128 v[154:157], v186 offset:1024
	ds_read_b128 v[158:161], v186 offset:2048
	ds_read_b128 v[162:165], v186 offset:3072
	ds_read_b128 v[166:169], v187
	ds_read_b128 v[188:191], v187 offset:1024
	ds_read_b128 v[192:195], v187 offset:2048
	ds_read_b128 v[196:199], v187 offset:3072
	ds_read_b128 v[200:203], v185 offset:32768
	ds_read_b128 v[204:207], v185 offset:33792
	ds_read_b128 v[208:211], v185 offset:34816
	ds_read_b128 v[212:215], v185 offset:35840
	ds_read_b128 v[216:219], v185 offset:36864
	ds_read_b128 v[220:223], v185 offset:37888
	ds_read_b128 v[224:227], v185 offset:38912
	ds_read_b128 v[228:231], v185 offset:39936
	s_add_u32 s82, s82, 0x200000
	s_addc_u32 s83, s83, 0
	s_mov_b32 m0, s29
	s_nop 0
	global_load_lds_dwordx4 v178, s[82:83]
	s_nop 0
	s_mov_b32 m0, s30
	s_nop 0
	global_load_lds_dwordx4 v180, s[82:83]
	s_waitcnt lgkmcnt(7)
	v_mfma_f32_16x16x32_bf16 v[126:129], v[150:153], v[200:203], v[126:129]
	v_mfma_f32_16x16x32_bf16 v[122:125], v[158:161], v[200:203], v[122:125]
	s_waitcnt lgkmcnt(5)
	v_mfma_f32_16x16x32_bf16 v[114:117], v[150:153], v[208:211], v[114:117]
	v_mfma_f32_16x16x32_bf16 v[106:109], v[158:161], v[208:211], v[106:109]
	s_waitcnt vmcnt(8)
	s_waitcnt lgkmcnt(0)
	s_barrier
	s_setprio 1
	s_waitcnt lgkmcnt(3)
	v_mfma_f32_16x16x32_bf16 v[98:101], v[150:153], v[216:219], v[98:101]
	v_mfma_f32_16x16x32_bf16 v[90:93], v[158:161], v[216:219], v[90:93]
	s_waitcnt lgkmcnt(1)
	v_mfma_f32_16x16x32_bf16 v[82:85], v[150:153], v[224:227], v[82:85]
	v_mfma_f32_16x16x32_bf16 v[74:77], v[158:161], v[224:227], v[74:77]
	v_mfma_f32_16x16x32_bf16 v[126:129], v[154:157], v[204:207], v[126:129]
	v_mfma_f32_16x16x32_bf16 v[122:125], v[162:165], v[204:207], v[122:125]
	v_mfma_f32_16x16x32_bf16 v[114:117], v[154:157], v[212:215], v[114:117]
	v_mfma_f32_16x16x32_bf16 v[106:109], v[162:165], v[212:215], v[106:109]
	v_mfma_f32_16x16x32_bf16 v[98:101], v[154:157], v[220:223], v[98:101]
	v_mfma_f32_16x16x32_bf16 v[90:93], v[162:165], v[220:223], v[90:93]
	s_waitcnt lgkmcnt(0)
	v_mfma_f32_16x16x32_bf16 v[82:85], v[154:157], v[228:231], v[82:85]
	v_mfma_f32_16x16x32_bf16 v[74:77], v[162:165], v[228:231], v[74:77]
	s_setprio 0
	s_setprio 1
	v_mfma_f32_16x16x32_bf16 v[118:121], v[166:169], v[200:203], v[118:121]
	v_mfma_f32_16x16x32_bf16 v[110:113], v[192:195], v[200:203], v[110:113]
	v_mfma_f32_16x16x32_bf16 v[102:105], v[166:169], v[208:211], v[102:105]
	v_mfma_f32_16x16x32_bf16 v[94:97], v[192:195], v[208:211], v[94:97]
	v_mfma_f32_16x16x32_bf16 v[86:89], v[166:169], v[216:219], v[86:89]
	v_mfma_f32_16x16x32_bf16 v[78:81], v[192:195], v[216:219], v[78:81]
	v_mfma_f32_16x16x32_bf16 v[70:73], v[166:169], v[224:227], v[70:73]
	v_mfma_f32_16x16x32_bf16 v[66:69], v[192:195], v[224:227], v[66:69]
	v_mfma_f32_16x16x32_bf16 v[118:121], v[188:191], v[204:207], v[118:121]
	v_mfma_f32_16x16x32_bf16 v[110:113], v[196:199], v[204:207], v[110:113]
	v_mfma_f32_16x16x32_bf16 v[102:105], v[188:191], v[212:215], v[102:105]
	v_mfma_f32_16x16x32_bf16 v[94:97], v[196:199], v[212:215], v[94:97]
	v_mfma_f32_16x16x32_bf16 v[86:89], v[188:191], v[220:223], v[86:89]
	v_mfma_f32_16x16x32_bf16 v[78:81], v[196:199], v[220:223], v[78:81]
	v_mfma_f32_16x16x32_bf16 v[70:73], v[188:191], v[228:231], v[70:73]
	v_mfma_f32_16x16x32_bf16 v[66:69], v[196:199], v[228:231], v[66:69]
	s_setprio 0
	s_barrier
; #define PG8_STAGE(bufoff, gbase, voff) do { if constexpr (VAR != 1 && VAR != 3) { _Pragma("unroll") for (int _i = 0; _i < 2; ++_i) \
;         asm volatile("s_mov_b32 m0, %2\n\ts_nop 0\n\tglobal_load_lds_dwordx4 %0, %1" :: "v"((voff)[_i]), "s"((const char*)(gbase)), "s"(ldsbase + (unsigned)((bufoff) + _i * 8192)) : "memory", "m0"); } } while (0)
; #define PG8_LDA(dst, b, h) do { if constexpr (VAR < 2) _Pragma("unroll") for (int m = 0; m < 4; ++m) _Pragma("unroll") for (int k = 0; k < 2; ++k) dst[m][k] = *(const LAS bf16x8*)(lds + PG8_SA(b, h) + aoff + m * 2048 + k * 1024); } while (0)
; #define PG8_WAIT_V(n) asm volatile("s_waitcnt vmcnt(" #n ")" ::: "memory")
; #define PG8_WAIT_L(n) asm volatile("s_waitcnt lgkmcnt(" #n ")" ::: "memory")
; #define PG8_BAR do { if constexpr (VAR != 3) __builtin_amdgcn_s_barrier(); } while (0)
; #define PG8_SCHED __builtin_amdgcn_sched_barrier(0)
;     ...
;             PG8_LDA(At, 1, 1); PG8_STAGE(PG8_SB(1, 0), b3, voffB); PG8_STAGE(PG8_SB(1, 1), b3 + hstepB, voffB); PG8_STAGE(PG8_SA(1, 0), a3, voffA);
;             PG8_WAIT_V(8); PG8_WAIT_L(0); PG8_BAR; PG8_MMA(1, 0, At, B0); PG8_MMA(1, 1, At, B1); PG8_BAR; PG8_SCHED;
;         }
;         if (wr == 0) PG8_BAR;
	ds_read_b128 v[200:203], v185 offset:49152
	ds_read_b128 v[204:207], v185 offset:50176
	ds_read_b128 v[208:211], v185 offset:51200
	ds_read_b128 v[212:215], v185 offset:52224
	ds_read_b128 v[216:219], v185 offset:53248
	ds_read_b128 v[220:223], v185 offset:54272
	ds_read_b128 v[224:227], v185 offset:55296
	ds_read_b128 v[228:231], v185 offset:56320
	s_add_u32 s82, s80, 0x80
	s_addc_u32 s83, s81, 0
	s_mov_b32 m0, s31
	s_nop 0
	global_load_lds_dwordx4 v179, s[82:83]
	s_add_u32 s80, s80, 0x100080
	s_mov_b32 m0, s33
	s_nop 0
	global_load_lds_dwordx4 v181, s[82:83]
	s_addc_u32 s81, s81, 0
	s_mov_b32 m0, s73
	s_nop 0
	global_load_lds_dwordx4 v179, s[80:81]
	s_nop 0
	s_mov_b32 m0, s84
	s_nop 0
	global_load_lds_dwordx4 v181, s[80:81]
	s_nop 0
	s_mov_b32 m0, s56
	s_nop 0
	global_load_lds_dwordx4 v178, s[78:79]
	s_nop 0
	s_mov_b32 m0, s57
	s_nop 0
	global_load_lds_dwordx4 v180, s[78:79]
	s_waitcnt lgkmcnt(7)
	v_mfma_f32_16x16x32_bf16 v[62:65], v[150:153], v[200:203], v[62:65]
	v_mfma_f32_16x16x32_bf16 v[58:61], v[158:161], v[200:203], v[58:61]
	s_waitcnt lgkmcnt(5)
	v_mfma_f32_16x16x32_bf16 v[50:53], v[150:153], v[208:211], v[50:53]
	v_mfma_f32_16x16x32_bf16 v[42:45], v[158:161], v[208:211], v[42:45]
	s_waitcnt vmcnt(8)
	s_waitcnt lgkmcnt(0)
	s_barrier
	s_setprio 1
	s_waitcnt lgkmcnt(3)
	v_mfma_f32_16x16x32_bf16 v[34:37], v[150:153], v[216:219], v[34:37]
	v_mfma_f32_16x16x32_bf16 v[26:29], v[158:161], v[216:219], v[26:29]
	s_waitcnt lgkmcnt(1)
	v_mfma_f32_16x16x32_bf16 v[18:21], v[150:153], v[224:227], v[18:21]
	v_mfma_f32_16x16x32_bf16 v[10:13], v[158:161], v[224:227], v[10:13]
	v_mfma_f32_16x16x32_bf16 v[62:65], v[154:157], v[204:207], v[62:65]
	v_mfma_f32_16x16x32_bf16 v[58:61], v[162:165], v[204:207], v[58:61]
	v_mfma_f32_16x16x32_bf16 v[50:53], v[154:157], v[212:215], v[50:53]
	v_mfma_f32_16x16x32_bf16 v[42:45], v[162:165], v[212:215], v[42:45]
	v_mfma_f32_16x16x32_bf16 v[34:37], v[154:157], v[220:223], v[34:37]
	v_mfma_f32_16x16x32_bf16 v[26:29], v[162:165], v[220:223], v[26:29]
	s_waitcnt lgkmcnt(0)
	v_mfma_f32_16x16x32_bf16 v[18:21], v[154:157], v[228:231], v[18:21]
	v_mfma_f32_16x16x32_bf16 v[10:13], v[162:165], v[228:231], v[10:13]
	s_setprio 0
	s_setprio 1
	v_mfma_f32_16x16x32_bf16 v[54:57], v[166:169], v[200:203], v[54:57]
	v_mfma_f32_16x16x32_bf16 v[46:49], v[192:195], v[200:203], v[46:49]
	v_mfma_f32_16x16x32_bf16 v[38:41], v[166:169], v[208:211], v[38:41]
	v_mfma_f32_16x16x32_bf16 v[30:33], v[192:195], v[208:211], v[30:33]
	v_mfma_f32_16x16x32_bf16 v[22:25], v[166:169], v[216:219], v[22:25]
	v_mfma_f32_16x16x32_bf16 v[14:17], v[192:195], v[216:219], v[14:17]
	v_mfma_f32_16x16x32_bf16 v[6:9], v[166:169], v[224:227], v[6:9]
	v_mfma_f32_16x16x32_bf16 v[2:5], v[192:195], v[224:227], v[2:5]
	v_mfma_f32_16x16x32_bf16 v[54:57], v[188:191], v[204:207], v[54:57]
	v_mfma_f32_16x16x32_bf16 v[46:49], v[196:199], v[204:207], v[46:49]
	v_mfma_f32_16x16x32_bf16 v[38:41], v[188:191], v[212:215], v[38:41]
	v_mfma_f32_16x16x32_bf16 v[30:33], v[196:199], v[212:215], v[30:33]
	v_mfma_f32_16x16x32_bf16 v[22:25], v[188:191], v[220:223], v[22:25]
	v_mfma_f32_16x16x32_bf16 v[14:17], v[196:199], v[220:223], v[14:17]
	v_mfma_f32_16x16x32_bf16 v[6:9], v[188:191], v[228:231], v[6:9]
	v_mfma_f32_16x16x32_bf16 v[2:5], v[196:199], v[228:231], v[2:5]
	s_setprio 0
	s_barrier
	s_add_i32 s6, s6, 2
	s_add_u32 s75, s75, 0x100
	s_addc_u32 s92, s92, 0
	s_add_u32 s93, s93, 0x100
	s_addc_u32 s94, s94, 0
	s_add_u32 s4, s4, 0x100
	s_addc_u32 s5, s5, 0
	s_cmp_gt_u32 s6, 13
	s_cbranch_scc0 .LBB0_673
	s_and_b64 vcc, exec, s[70:71]
	s_cbranch_vccz .LBB0_676
	s_barrier

; #define PG8_STAGE(bufoff, gbase, voff) do { if constexpr (VAR != 1 && VAR != 3) { _Pragma("unroll") for (int _i = 0; _i < 2; ++_i) \
;         asm volatile("s_mov_b32 m0, %2\n\ts_nop 0\n\tglobal_load_lds_dwordx4 %0, %1" :: "v"((voff)[_i]), "s"((const char*)(gbase)), "s"(ldsbase + (unsigned)((bufoff) + _i * 8192)) : "memory", "m0"); } } while (0)
; #define PG8_LDA(dst, b, h) do { if constexpr (VAR < 2) _Pragma("unroll") for (int m = 0; m < 4; ++m) _Pragma("unroll") for (int k = 0; k < 2; ++k) dst[m][k] = *(const LAS bf16x8*)(lds + PG8_SA(b, h) + aoff + m * 2048 + k * 1024); } while (0)
; #define PG8_LDB(dst, b, h) do { if constexpr (VAR < 2) _Pragma("unroll") for (int n = 0; n < 2; ++n) _Pragma("unroll") for (int k = 0; k < 2; ++k) dst[n][k] = *(const LAS bf16x8*)(lds + PG8_SB(b, h) + boff + n * 2048 + k * 1024); } while (0)
; #define PG8_WAIT_V(n) asm volatile("s_waitcnt vmcnt(" #n ")" ::: "memory")
; #define PG8_WAIT_L(n) asm volatile("s_waitcnt lgkmcnt(" #n ")" ::: "memory")
; #define PG8_BAR do { if constexpr (VAR != 3) __builtin_amdgcn_s_barrier(); } while (0)
; #define PG8_SCHED __builtin_amdgcn_sched_barrier(0)
;     ...
;         for (int t = 0; t < nt; t += 2) {
;             const bool last = (t == nt - 2);
;             const char* a1 = cA + (size_t)(t + 1) * kstep;
;             const char* a2 = last ? nA : cA + (size_t)(t + 2) * kstep; const char* b2 = last ? nB : cB + (size_t)(t + 2) * kstep;
;             const char* a3 = a2 + kstep; const char* b3 = b2 + kstep;
;             PG8_LDB(B0, 0, 0); PG8_LDB(B1, 0, 1); PG8_SCHED; PG8_LDA(At, 0, 0); PG8_STAGE(PG8_SA(1, 1), a1 + hstepA, voffA);
;             PG8_WAIT_V(8); PG8_WAIT_L(0); PG8_BAR; PG8_MMA(0, 0, At, B0); PG8_MMA(0, 1, At, B1); PG8_BAR; PG8_SCHED;
;             PG8_LDA(At, 0, 1); PG8_STAGE(PG8_SB(0, 0), b2, voffB); PG8_STAGE(PG8_SB(0, 1), b2 + hstepB, voffB); PG8_STAGE(PG8_SA(0, 0), a2, voffA);
;             PG8_WAIT_V(8); PG8_WAIT_L(0); PG8_BAR; PG8_MMA(1, 0, At, B0); PG8_MMA(1, 1, At, B1); PG8_BAR; PG8_SCHED;
.LBB0_701:
	ds_read_b128 v[148:151], v1
	ds_read_b128 v[152:155], v1 offset:1024
	ds_read_b128 v[156:159], v1 offset:2048
	ds_read_b128 v[160:163], v1 offset:3072
	ds_read_b128 v[164:167], v143
	ds_read_b128 v[168:171], v143 offset:1024
	ds_read_b128 v[172:175], v143 offset:2048
	ds_read_b128 v[176:179], v143 offset:3072
	s_cmp_eq_u32 s6, 12
	s_cselect_b32 s70, s0, s57
	s_cselect_b32 s71, s1, s81
	s_cselect_b32 s68, s62, s82
	s_cselect_b32 s69, s63, s83
	s_add_u32 s66, s70, 0x80
	s_addc_u32 s67, s71, 0
	ds_read_b128 v[180:183], v144
	ds_read_b128 v[184:187], v144 offset:1024
	ds_read_b128 v[188:191], v144 offset:2048
	ds_read_b128 v[192:195], v144 offset:3072
	ds_read_b128 v[196:199], v144 offset:4096
	ds_read_b128 v[200:203], v144 offset:5120
	ds_read_b128 v[204:207], v144 offset:6144
	ds_read_b128 v[208:211], v144 offset:7168
	s_mov_b32 m0, s76
	s_nop 0
	global_load_lds_dwordx4 v138, s[64:65]
	s_nop 0
	s_mov_b32 m0, s77
	s_nop 0
	global_load_lds_dwordx4 v140, s[64:65]
	s_waitcnt lgkmcnt(7)
	v_mfma_f32_16x16x32_bf16 v[126:129], v[148:151], v[180:183], v[126:129]
	v_mfma_f32_16x16x32_bf16 v[122:125], v[156:159], v[180:183], v[122:125]
	s_waitcnt lgkmcnt(5)
	v_mfma_f32_16x16x32_bf16 v[118:121], v[148:151], v[188:191], v[118:121]
	v_mfma_f32_16x16x32_bf16 v[110:113], v[156:159], v[188:191], v[110:113]
	s_waitcnt vmcnt(8)
	s_waitcnt lgkmcnt(0)
	s_barrier
	s_setprio 1
	s_waitcnt lgkmcnt(3)
	v_mfma_f32_16x16x32_bf16 v[102:105], v[148:151], v[196:199], v[102:105]
	v_mfma_f32_16x16x32_bf16 v[94:97], v[156:159], v[196:199], v[94:97]
	s_waitcnt lgkmcnt(1)
	v_mfma_f32_16x16x32_bf16 v[86:89], v[148:151], v[204:207], v[86:89]
	v_mfma_f32_16x16x32_bf16 v[78:81], v[156:159], v[204:207], v[78:81]
	v_mfma_f32_16x16x32_bf16 v[126:129], v[152:155], v[184:187], v[126:129]
	v_mfma_f32_16x16x32_bf16 v[122:125], v[160:163], v[184:187], v[122:125]
	v_mfma_f32_16x16x32_bf16 v[118:121], v[152:155], v[192:195], v[118:121]
	v_mfma_f32_16x16x32_bf16 v[110:113], v[160:163], v[192:195], v[110:113]
	v_mfma_f32_16x16x32_bf16 v[102:105], v[152:155], v[200:203], v[102:105]
	v_mfma_f32_16x16x32_bf16 v[94:97], v[160:163], v[200:203], v[94:97]
	s_waitcnt lgkmcnt(0)
	v_mfma_f32_16x16x32_bf16 v[86:89], v[152:155], v[208:211], v[86:89]
	v_mfma_f32_16x16x32_bf16 v[78:81], v[160:163], v[208:211], v[78:81]
	s_setprio 0
	s_setprio 1
	v_mfma_f32_16x16x32_bf16 v[114:117], v[164:167], v[180:183], v[114:117]
	v_mfma_f32_16x16x32_bf16 v[106:109], v[172:175], v[180:183], v[106:109]
	v_mfma_f32_16x16x32_bf16 v[98:101], v[164:167], v[188:191], v[98:101]
	v_mfma_f32_16x16x32_bf16 v[90:93], v[172:175], v[188:191], v[90:93]
	v_mfma_f32_16x16x32_bf16 v[82:85], v[164:167], v[196:199], v[82:85]
	v_mfma_f32_16x16x32_bf16 v[74:77], v[172:175], v[196:199], v[74:77]
	v_mfma_f32_16x16x32_bf16 v[70:73], v[164:167], v[204:207], v[70:73]
	v_mfma_f32_16x16x32_bf16 v[66:69], v[172:175], v[204:207], v[66:69]
	v_mfma_f32_16x16x32_bf16 v[114:117], v[168:171], v[184:187], v[114:117]
	v_mfma_f32_16x16x32_bf16 v[106:109], v[176:179], v[184:187], v[106:109]
	v_mfma_f32_16x16x32_bf16 v[98:101], v[168:171], v[192:195], v[98:101]
	v_mfma_f32_16x16x32_bf16 v[90:93], v[176:179], v[192:195], v[90:93]
	v_mfma_f32_16x16x32_bf16 v[82:85], v[168:171], v[200:203], v[82:85]
	v_mfma_f32_16x16x32_bf16 v[74:77], v[176:179], v[200:203], v[74:77]
	v_mfma_f32_16x16x32_bf16 v[70:73], v[168:171], v[208:211], v[70:73]
	v_mfma_f32_16x16x32_bf16 v[66:69], v[176:179], v[208:211], v[66:69]
	s_setprio 0
	s_barrier
	ds_read_b128 v[180:183], v144 offset:16384
	ds_read_b128 v[184:187], v144 offset:17408
	ds_read_b128 v[188:191], v144 offset:18432
	ds_read_b128 v[192:195], v144 offset:19456
	ds_read_b128 v[196:199], v144 offset:20480
	ds_read_b128 v[200:203], v144 offset:21504
	ds_read_b128 v[204:207], v144 offset:22528
	ds_read_b128 v[208:211], v144 offset:23552
	s_mov_b32 m0, s24
	s_nop 0
	global_load_lds_dwordx4 v139, s[68:69]
	s_add_u32 s84, s68, 0x200000
	s_mov_b32 m0, s25
	s_nop 0
	global_load_lds_dwordx4 v141, s[68:69]
	s_addc_u32 s85, s69, 0
	s_mov_b32 m0, s26
	s_nop 0
	global_load_lds_dwordx4 v139, s[84:85]
	s_nop 0
	s_mov_b32 m0, s27
	s_nop 0
	global_load_lds_dwordx4 v141, s[84:85]
	s_nop 0
	s_mov_b32 m0, s15
	s_nop 0
	global_load_lds_dwordx4 v138, s[70:71]
	s_nop 0
	s_mov_b32 m0, s28
	s_nop 0
	global_load_lds_dwordx4 v140, s[70:71]
	s_waitcnt lgkmcnt(7)
	v_mfma_f32_16x16x32_bf16 v[62:65], v[148:151], v[180:183], v[62:65]
	v_mfma_f32_16x16x32_bf16 v[58:61], v[156:159], v[180:183], v[58:61]
	s_waitcnt lgkmcnt(5)
	v_mfma_f32_16x16x32_bf16 v[54:57], v[148:151], v[188:191], v[54:57]
	v_mfma_f32_16x16x32_bf16 v[46:49], v[156:159], v[188:191], v[46:49]
	s_waitcnt vmcnt(8)
	s_waitcnt lgkmcnt(0)
	s_barrier
; #define PG8_STAGE(bufoff, gbase, voff) do { if constexpr (VAR != 1 && VAR != 3) { _Pragma("unroll") for (int _i = 0; _i < 2; ++_i) \
;         asm volatile("s_mov_b32 m0, %2\n\ts_nop 0\n\tglobal_load_lds_dwordx4 %0, %1" :: "v"((voff)[_i]), "s"((const char*)(gbase)), "s"(ldsbase + (unsigned)((bufoff) + _i * 8192)) : "memory", "m0"); } } while (0)
; #define PG8_LDA(dst, b, h) do { if constexpr (VAR < 2) _Pragma("unroll") for (int m = 0; m < 4; ++m) _Pragma("unroll") for (int k = 0; k < 2; ++k) dst[m][k] = *(const LAS bf16x8*)(lds + PG8_SA(b, h) + aoff + m * 2048 + k * 1024); } while (0)
; #define PG8_LDB(dst, b, h) do { if constexpr (VAR < 2) _Pragma("unroll") for (int n = 0; n < 2; ++n) _Pragma("unroll") for (int k = 0; k < 2; ++k) dst[n][k] = *(const LAS bf16x8*)(lds + PG8_SB(b, h) + boff + n * 2048 + k * 1024); } while (0)
; #define PG8_WAIT_V(n) asm volatile("s_waitcnt vmcnt(" #n ")" ::: "memory")
; #define PG8_WAIT_L(n) asm volatile("s_waitcnt lgkmcnt(" #n ")" ::: "memory")
; #define PG8_BAR do { if constexpr (VAR != 3) __builtin_amdgcn_s_barrier(); } while (0)
; #define PG8_SCHED __builtin_amdgcn_sched_barrier(0)
;     ...
;             PG8_WAIT_V(8); PG8_WAIT_L(0); PG8_BAR; PG8_MMA(1, 0, At, B0); PG8_MMA(1, 1, At, B1); PG8_BAR; PG8_SCHED;
;             PG8_LDB(B0, 1, 0); PG8_LDB(B1, 1, 1); PG8_SCHED; PG8_LDA(At, 1, 0); PG8_STAGE(PG8_SA(0, 1), a2 + hstepA, voffA);
;             PG8_WAIT_V(8); PG8_WAIT_L(0); PG8_BAR; PG8_MMA(0, 0, At, B0); PG8_MMA(0, 1, At, B1); PG8_BAR; PG8_SCHED;
	s_setprio 1
	s_waitcnt lgkmcnt(3)
	v_mfma_f32_16x16x32_bf16 v[38:41], v[148:151], v[196:199], v[38:41]
	v_mfma_f32_16x16x32_bf16 v[30:33], v[156:159], v[196:199], v[30:33]
	s_waitcnt lgkmcnt(1)
	v_mfma_f32_16x16x32_bf16 v[22:25], v[148:151], v[204:207], v[22:25]
	v_mfma_f32_16x16x32_bf16 v[14:17], v[156:159], v[204:207], v[14:17]
	v_mfma_f32_16x16x32_bf16 v[62:65], v[152:155], v[184:187], v[62:65]
	v_mfma_f32_16x16x32_bf16 v[58:61], v[160:163], v[184:187], v[58:61]
	v_mfma_f32_16x16x32_bf16 v[54:57], v[152:155], v[192:195], v[54:57]
	v_mfma_f32_16x16x32_bf16 v[46:49], v[160:163], v[192:195], v[46:49]
	v_mfma_f32_16x16x32_bf16 v[38:41], v[152:155], v[200:203], v[38:41]
	v_mfma_f32_16x16x32_bf16 v[30:33], v[160:163], v[200:203], v[30:33]
	s_waitcnt lgkmcnt(0)
	v_mfma_f32_16x16x32_bf16 v[22:25], v[152:155], v[208:211], v[22:25]
	v_mfma_f32_16x16x32_bf16 v[14:17], v[160:163], v[208:211], v[14:17]
	s_setprio 0
	s_setprio 1
	v_mfma_f32_16x16x32_bf16 v[50:53], v[164:167], v[180:183], v[50:53]
	v_mfma_f32_16x16x32_bf16 v[42:45], v[172:175], v[180:183], v[42:45]
	v_mfma_f32_16x16x32_bf16 v[34:37], v[164:167], v[188:191], v[34:37]
	v_mfma_f32_16x16x32_bf16 v[26:29], v[172:175], v[188:191], v[26:29]
	v_mfma_f32_16x16x32_bf16 v[18:21], v[164:167], v[196:199], v[18:21]
	v_mfma_f32_16x16x32_bf16 v[10:13], v[172:175], v[196:199], v[10:13]
	v_mfma_f32_16x16x32_bf16 v[6:9], v[164:167], v[204:207], v[6:9]
	v_mfma_f32_16x16x32_bf16 v[2:5], v[172:175], v[204:207], v[2:5]
	v_mfma_f32_16x16x32_bf16 v[50:53], v[168:171], v[184:187], v[50:53]
	v_mfma_f32_16x16x32_bf16 v[42:45], v[176:179], v[184:187], v[42:45]
	v_mfma_f32_16x16x32_bf16 v[34:37], v[168:171], v[192:195], v[34:37]
	v_mfma_f32_16x16x32_bf16 v[26:29], v[176:179], v[192:195], v[26:29]
	v_mfma_f32_16x16x32_bf16 v[18:21], v[168:171], v[200:203], v[18:21]
	v_mfma_f32_16x16x32_bf16 v[10:13], v[176:179], v[200:203], v[10:13]
	v_mfma_f32_16x16x32_bf16 v[6:9], v[168:171], v[208:211], v[6:9]
	v_mfma_f32_16x16x32_bf16 v[2:5], v[176:179], v[208:211], v[2:5]
	s_setprio 0
	s_barrier
	ds_read_b128 v[148:151], v145
	ds_read_b128 v[152:155], v145 offset:1024
	ds_read_b128 v[156:159], v145 offset:2048
	ds_read_b128 v[160:163], v145 offset:3072
	ds_read_b128 v[164:167], v146
	ds_read_b128 v[168:171], v146 offset:1024
	ds_read_b128 v[172:175], v146 offset:2048
	ds_read_b128 v[176:179], v146 offset:3072
	ds_read_b128 v[180:183], v144 offset:32768
	ds_read_b128 v[184:187], v144 offset:33792
	ds_read_b128 v[188:191], v144 offset:34816
	ds_read_b128 v[192:195], v144 offset:35840
	ds_read_b128 v[196:199], v144 offset:36864
	ds_read_b128 v[200:203], v144 offset:37888
	ds_read_b128 v[204:207], v144 offset:38912
	ds_read_b128 v[208:211], v144 offset:39936
	s_add_u32 s70, s70, 0x100000
	s_addc_u32 s71, s71, 0
	s_mov_b32 m0, s29
	s_nop 0
	global_load_lds_dwordx4 v138, s[70:71]
	s_nop 0
	s_mov_b32 m0, s30
	s_nop 0
	global_load_lds_dwordx4 v140, s[70:71]
	s_waitcnt lgkmcnt(7)
	v_mfma_f32_16x16x32_bf16 v[126:129], v[148:151], v[180:183], v[126:129]
	v_mfma_f32_16x16x32_bf16 v[122:125], v[156:159], v[180:183], v[122:125]
	s_waitcnt lgkmcnt(5)
	v_mfma_f32_16x16x32_bf16 v[118:121], v[148:151], v[188:191], v[118:121]
	v_mfma_f32_16x16x32_bf16 v[110:113], v[156:159], v[188:191], v[110:113]
	s_waitcnt vmcnt(8)
	s_waitcnt lgkmcnt(0)
	s_barrier
	s_setprio 1
	s_waitcnt lgkmcnt(3)
	v_mfma_f32_16x16x32_bf16 v[102:105], v[148:151], v[196:199], v[102:105]
	v_mfma_f32_16x16x32_bf16 v[94:97], v[156:159], v[196:199], v[94:97]
	s_waitcnt lgkmcnt(1)
	v_mfma_f32_16x16x32_bf16 v[86:89], v[148:151], v[204:207], v[86:89]
	v_mfma_f32_16x16x32_bf16 v[78:81], v[156:159], v[204:207], v[78:81]
	v_mfma_f32_16x16x32_bf16 v[126:129], v[152:155], v[184:187], v[126:129]
	v_mfma_f32_16x16x32_bf16 v[122:125], v[160:163], v[184:187], v[122:125]
	v_mfma_f32_16x16x32_bf16 v[118:121], v[152:155], v[192:195], v[118:121]
	v_mfma_f32_16x16x32_bf16 v[110:113], v[160:163], v[192:195], v[110:113]
	v_mfma_f32_16x16x32_bf16 v[102:105], v[152:155], v[200:203], v[102:105]
	v_mfma_f32_16x16x32_bf16 v[94:97], v[160:163], v[200:203], v[94:97]
	s_waitcnt lgkmcnt(0)
	v_mfma_f32_16x16x32_bf16 v[86:89], v[152:155], v[208:211], v[86:89]
	v_mfma_f32_16x16x32_bf16 v[78:81], v[160:163], v[208:211], v[78:81]
	s_setprio 0
	s_setprio 1
	v_mfma_f32_16x16x32_bf16 v[114:117], v[164:167], v[180:183], v[114:117]
	v_mfma_f32_16x16x32_bf16 v[106:109], v[172:175], v[180:183], v[106:109]
	v_mfma_f32_16x16x32_bf16 v[98:101], v[164:167], v[188:191], v[98:101]
	v_mfma_f32_16x16x32_bf16 v[90:93], v[172:175], v[188:191], v[90:93]
	v_mfma_f32_16x16x32_bf16 v[82:85], v[164:167], v[196:199], v[82:85]
	v_mfma_f32_16x16x32_bf16 v[74:77], v[172:175], v[196:199], v[74:77]
	v_mfma_f32_16x16x32_bf16 v[70:73], v[164:167], v[204:207], v[70:73]
	v_mfma_f32_16x16x32_bf16 v[66:69], v[172:175], v[204:207], v[66:69]
	v_mfma_f32_16x16x32_bf16 v[114:117], v[168:171], v[184:187], v[114:117]
	v_mfma_f32_16x16x32_bf16 v[106:109], v[176:179], v[184:187], v[106:109]
	v_mfma_f32_16x16x32_bf16 v[98:101], v[168:171], v[192:195], v[98:101]
	v_mfma_f32_16x16x32_bf16 v[90:93], v[176:179], v[192:195], v[90:93]
	v_mfma_f32_16x16x32_bf16 v[82:85], v[168:171], v[200:203], v[82:85]
	v_mfma_f32_16x16x32_bf16 v[74:77], v[176:179], v[200:203], v[74:77]
	v_mfma_f32_16x16x32_bf16 v[70:73], v[168:171], v[208:211], v[70:73]
	v_mfma_f32_16x16x32_bf16 v[66:69], v[176:179], v[208:211], v[66:69]
	s_setprio 0
	s_barrier
; #define PG8_STAGE(bufoff, gbase, voff) do { if constexpr (VAR != 1 && VAR != 3) { _Pragma("unroll") for (int _i = 0; _i < 2; ++_i) \
;         asm volatile("s_mov_b32 m0, %2\n\ts_nop 0\n\tglobal_load_lds_dwordx4 %0, %1" :: "v"((voff)[_i]), "s"((const char*)(gbase)), "s"(ldsbase + (unsigned)((bufoff) + _i * 8192)) : "memory", "m0"); } } while (0)
; #define PG8_LDA(dst, b, h) do { if constexpr (VAR < 2) _Pragma("unroll") for (int m = 0; m < 4; ++m) _Pragma("unroll") for (int k = 0; k < 2; ++k) dst[m][k] = *(const LAS bf16x8*)(lds + PG8_SA(b, h) + aoff + m * 2048 + k * 1024); } while (0)
; #define PG8_WAIT_V(n) asm volatile("s_waitcnt vmcnt(" #n ")" ::: "memory")
; #define PG8_WAIT_L(n) asm volatile("s_waitcnt lgkmcnt(" #n ")" ::: "memory")
; #define PG8_BAR do { if constexpr (VAR != 3) __builtin_amdgcn_s_barrier(); } while (0)
; #define PG8_SCHED __builtin_amdgcn_sched_barrier(0)
;     ...
;             PG8_LDA(At, 1, 1); PG8_STAGE(PG8_SB(1, 0), b3, voffB); PG8_STAGE(PG8_SB(1, 1), b3 + hstepB, voffB); PG8_STAGE(PG8_SA(1, 0), a3, voffA);
;             PG8_WAIT_V(8); PG8_WAIT_L(0); PG8_BAR; PG8_MMA(1, 0, At, B0); PG8_MMA(1, 1, At, B1); PG8_BAR; PG8_SCHED;
;         }
;         if (wr == 0) PG8_BAR;
	ds_read_b128 v[180:183], v144 offset:49152
	ds_read_b128 v[184:187], v144 offset:50176
	ds_read_b128 v[188:191], v144 offset:51200
	ds_read_b128 v[192:195], v144 offset:52224
	ds_read_b128 v[196:199], v144 offset:53248
	ds_read_b128 v[200:203], v144 offset:54272
	ds_read_b128 v[204:207], v144 offset:55296
	ds_read_b128 v[208:211], v144 offset:56320
	s_add_u32 s70, s68, 0x80
	s_addc_u32 s71, s69, 0
	s_mov_b32 m0, s31
	s_nop 0
	global_load_lds_dwordx4 v139, s[70:71]
	s_add_u32 s68, s68, 0x200080
	s_mov_b32 m0, s33
	s_nop 0
	global_load_lds_dwordx4 v141, s[70:71]
	s_addc_u32 s69, s69, 0
	s_mov_b32 m0, s74
	s_nop 0
	global_load_lds_dwordx4 v139, s[68:69]
	s_nop 0
	s_mov_b32 m0, s75
	s_nop 0
	global_load_lds_dwordx4 v141, s[68:69]
	s_nop 0
	s_mov_b32 m0, s72
	s_nop 0
	global_load_lds_dwordx4 v138, s[66:67]
	s_nop 0
	s_mov_b32 m0, s73
	s_nop 0
	global_load_lds_dwordx4 v140, s[66:67]
	s_waitcnt lgkmcnt(7)
	v_mfma_f32_16x16x32_bf16 v[62:65], v[148:151], v[180:183], v[62:65]
	v_mfma_f32_16x16x32_bf16 v[58:61], v[156:159], v[180:183], v[58:61]
	s_waitcnt lgkmcnt(5)
	v_mfma_f32_16x16x32_bf16 v[54:57], v[148:151], v[188:191], v[54:57]
	v_mfma_f32_16x16x32_bf16 v[46:49], v[156:159], v[188:191], v[46:49]
	s_waitcnt vmcnt(8)
	s_waitcnt lgkmcnt(0)
	s_barrier
	s_setprio 1
	s_waitcnt lgkmcnt(3)
	v_mfma_f32_16x16x32_bf16 v[38:41], v[148:151], v[196:199], v[38:41]
	v_mfma_f32_16x16x32_bf16 v[30:33], v[156:159], v[196:199], v[30:33]
	s_waitcnt lgkmcnt(1)
	v_mfma_f32_16x16x32_bf16 v[22:25], v[148:151], v[204:207], v[22:25]
	v_mfma_f32_16x16x32_bf16 v[14:17], v[156:159], v[204:207], v[14:17]
	v_mfma_f32_16x16x32_bf16 v[62:65], v[152:155], v[184:187], v[62:65]
	v_mfma_f32_16x16x32_bf16 v[58:61], v[160:163], v[184:187], v[58:61]
	v_mfma_f32_16x16x32_bf16 v[54:57], v[152:155], v[192:195], v[54:57]
	v_mfma_f32_16x16x32_bf16 v[46:49], v[160:163], v[192:195], v[46:49]
	v_mfma_f32_16x16x32_bf16 v[38:41], v[152:155], v[200:203], v[38:41]
	v_mfma_f32_16x16x32_bf16 v[30:33], v[160:163], v[200:203], v[30:33]
	s_waitcnt lgkmcnt(0)
	v_mfma_f32_16x16x32_bf16 v[22:25], v[152:155], v[208:211], v[22:25]
	v_mfma_f32_16x16x32_bf16 v[14:17], v[160:163], v[208:211], v[14:17]
	s_setprio 0
	s_setprio 1
	v_mfma_f32_16x16x32_bf16 v[50:53], v[164:167], v[180:183], v[50:53]
	v_mfma_f32_16x16x32_bf16 v[42:45], v[172:175], v[180:183], v[42:45]
	v_mfma_f32_16x16x32_bf16 v[34:37], v[164:167], v[188:191], v[34:37]
	v_mfma_f32_16x16x32_bf16 v[26:29], v[172:175], v[188:191], v[26:29]
	v_mfma_f32_16x16x32_bf16 v[18:21], v[164:167], v[196:199], v[18:21]
	v_mfma_f32_16x16x32_bf16 v[10:13], v[172:175], v[196:199], v[10:13]
	v_mfma_f32_16x16x32_bf16 v[6:9], v[164:167], v[204:207], v[6:9]
	v_mfma_f32_16x16x32_bf16 v[2:5], v[172:175], v[204:207], v[2:5]
	v_mfma_f32_16x16x32_bf16 v[50:53], v[168:171], v[184:187], v[50:53]
	v_mfma_f32_16x16x32_bf16 v[42:45], v[176:179], v[184:187], v[42:45]
	v_mfma_f32_16x16x32_bf16 v[34:37], v[168:171], v[192:195], v[34:37]
	v_mfma_f32_16x16x32_bf16 v[26:29], v[176:179], v[192:195], v[26:29]
	v_mfma_f32_16x16x32_bf16 v[18:21], v[168:171], v[200:203], v[18:21]
	v_mfma_f32_16x16x32_bf16 v[10:13], v[176:179], v[200:203], v[10:13]
	v_mfma_f32_16x16x32_bf16 v[6:9], v[168:171], v[208:211], v[6:9]
	v_mfma_f32_16x16x32_bf16 v[2:5], v[176:179], v[208:211], v[2:5]
	s_setprio 0
	s_barrier
	s_add_i32 s6, s6, 2
	s_add_u32 s57, s57, 0x100
	s_addc_u32 s81, s81, 0
	s_add_u32 s82, s82, 0x100
	s_addc_u32 s83, s83, 0
	s_add_u32 s64, s64, 0x100
	s_addc_u32 s65, s65, 0
	s_cmp_gt_u32 s6, 13
	s_cbranch_scc0 .LBB0_701
	s_and_b64 vcc, exec, s[8:9]
	s_cbranch_vccz .LBB0_704
	s_barrier

; #define PG8_STAGE(bufoff, gbase, voff) do { if constexpr (VAR != 1 && VAR != 3) { _Pragma("unroll") for (int _i = 0; _i < 2; ++_i) \
;         asm volatile("s_mov_b32 m0, %2\n\ts_nop 0\n\tglobal_load_lds_dwordx4 %0, %1" :: "v"((voff)[_i]), "s"((const char*)(gbase)), "s"(ldsbase + (unsigned)((bufoff) + _i * 8192)) : "memory", "m0"); } } while (0)
; #define PG8_LDA(dst, b, h) do { if constexpr (VAR < 2) _Pragma("unroll") for (int m = 0; m < 4; ++m) _Pragma("unroll") for (int k = 0; k < 2; ++k) dst[m][k] = *(const LAS bf16x8*)(lds + PG8_SA(b, h) + aoff + m * 2048 + k * 1024); } while (0)
; #define PG8_LDB(dst, b, h) do { if constexpr (VAR < 2) _Pragma("unroll") for (int n = 0; n < 2; ++n) _Pragma("unroll") for (int k = 0; k < 2; ++k) dst[n][k] = *(const LAS bf16x8*)(lds + PG8_SB(b, h) + boff + n * 2048 + k * 1024); } while (0)
; #define PG8_WAIT_V(n) asm volatile("s_waitcnt vmcnt(" #n ")" ::: "memory")
; #define PG8_WAIT_L(n) asm volatile("s_waitcnt lgkmcnt(" #n ")" ::: "memory")
; #define PG8_BAR do { if constexpr (VAR != 3) __builtin_amdgcn_s_barrier(); } while (0)
; #define PG8_SCHED __builtin_amdgcn_sched_barrier(0)
;     ...
;         for (int t = 0; t < nt; t += 2) {
;             const bool last = (t == nt - 2);
;             const char* a1 = cA + (size_t)(t + 1) * kstep;
;             const char* a2 = last ? nA : cA + (size_t)(t + 2) * kstep; const char* b2 = last ? nB : cB + (size_t)(t + 2) * kstep;
;             const char* a3 = a2 + kstep; const char* b3 = b2 + kstep;
;             PG8_LDB(B0, 0, 0); PG8_LDB(B1, 0, 1); PG8_SCHED; PG8_LDA(At, 0, 0); PG8_STAGE(PG8_SA(1, 1), a1 + hstepA, voffA);
;             PG8_WAIT_V(8); PG8_WAIT_L(0); PG8_BAR; PG8_MMA(0, 0, At, B0); PG8_MMA(0, 1, At, B1); PG8_BAR; PG8_SCHED;
;             PG8_LDA(At, 0, 1); PG8_STAGE(PG8_SB(0, 0), b2, voffB); PG8_STAGE(PG8_SB(0, 1), b2 + hstepB, voffB); PG8_STAGE(PG8_SA(0, 0), a2, voffA);
;             PG8_WAIT_V(8); PG8_WAIT_L(0); PG8_BAR; PG8_MMA(1, 0, At, B0); PG8_MMA(1, 1, At, B1); PG8_BAR; PG8_SCHED;
.LBB0_789:
	ds_read_b128 v[98:101], v191
	ds_read_b128 v[110:113], v191 offset:1024
	ds_read_b128 v[122:125], v191 offset:2048
	ds_read_b128 v[134:137], v191 offset:3072
	ds_read_b128 v[138:141], v192
	ds_read_b128 v[150:153], v192 offset:1024
	ds_read_b128 v[154:157], v192 offset:2048
	ds_read_b128 v[162:165], v192 offset:3072
	s_cmp_eq_u32 vcc_hi, 60
	s_cselect_b32 s86, s15, s27
	s_cselect_b32 s87, s14, s71
	s_cselect_b32 s84, s26, s73
	s_cselect_b32 s85, s25, vcc_lo
	s_add_u32 s82, s86, 0x80
	s_addc_u32 s83, s87, 0
	ds_read_b128 v[166:169], v193
	ds_read_b128 v[170:173], v193 offset:1024
	ds_read_b128 v[174:177], v193 offset:2048
	ds_read_b128 v[178:181], v193 offset:3072
	ds_read_b128 v[198:201], v193 offset:4096
	ds_read_b128 v[202:205], v193 offset:5120
	ds_read_b128 v[206:209], v193 offset:6144
	ds_read_b128 v[210:213], v193 offset:7168
	s_mov_b32 m0, s31
	s_nop 0
	global_load_lds_dwordx4 v184, s[80:81]
	s_nop 0
	s_mov_b32 m0, s19
	s_nop 0
	global_load_lds_dwordx4 v186, s[80:81]
	s_waitcnt lgkmcnt(7)
	v_mfma_f32_16x16x32_bf16 v[146:149], v[98:101], v[166:169], v[146:149]
	v_mfma_f32_16x16x32_bf16 v[142:145], v[122:125], v[166:169], v[142:145]
	s_waitcnt lgkmcnt(5)
	v_mfma_f32_16x16x32_bf16 v[118:121], v[98:101], v[174:177], v[118:121]
	v_mfma_f32_16x16x32_bf16 v[114:117], v[122:125], v[174:177], v[114:117]
	s_waitcnt vmcnt(8)
	s_waitcnt lgkmcnt(0)
	s_barrier
	s_setprio 1
	s_waitcnt lgkmcnt(3)
	v_mfma_f32_16x16x32_bf16 v[94:97], v[98:101], v[198:201], v[94:97]
	v_mfma_f32_16x16x32_bf16 v[90:93], v[122:125], v[198:201], v[90:93]
	s_waitcnt lgkmcnt(1)
	v_mfma_f32_16x16x32_bf16 v[78:81], v[98:101], v[206:209], v[78:81]
	v_mfma_f32_16x16x32_bf16 v[74:77], v[122:125], v[206:209], v[74:77]
	v_mfma_f32_16x16x32_bf16 v[146:149], v[110:113], v[170:173], v[146:149]
	v_mfma_f32_16x16x32_bf16 v[142:145], v[134:137], v[170:173], v[142:145]
	v_mfma_f32_16x16x32_bf16 v[118:121], v[110:113], v[178:181], v[118:121]
	v_mfma_f32_16x16x32_bf16 v[114:117], v[134:137], v[178:181], v[114:117]
	v_mfma_f32_16x16x32_bf16 v[94:97], v[110:113], v[202:205], v[94:97]
	v_mfma_f32_16x16x32_bf16 v[90:93], v[134:137], v[202:205], v[90:93]
	s_waitcnt lgkmcnt(0)
	v_mfma_f32_16x16x32_bf16 v[78:81], v[110:113], v[210:213], v[78:81]
	v_mfma_f32_16x16x32_bf16 v[74:77], v[134:137], v[210:213], v[74:77]
	s_setprio 0
	s_setprio 1
	v_mfma_f32_16x16x32_bf16 v[130:133], v[138:141], v[166:169], v[130:133]
	v_mfma_f32_16x16x32_bf16 v[126:129], v[154:157], v[166:169], v[126:129]
	v_mfma_f32_16x16x32_bf16 v[106:109], v[138:141], v[174:177], v[106:109]
	v_mfma_f32_16x16x32_bf16 v[102:105], v[154:157], v[174:177], v[102:105]
	v_mfma_f32_16x16x32_bf16 v[86:89], v[138:141], v[198:201], v[86:89]
	v_mfma_f32_16x16x32_bf16 v[82:85], v[154:157], v[198:201], v[82:85]
	v_mfma_f32_16x16x32_bf16 v[70:73], v[138:141], v[206:209], v[70:73]
	v_mfma_f32_16x16x32_bf16 v[66:69], v[154:157], v[206:209], v[66:69]
	v_mfma_f32_16x16x32_bf16 v[130:133], v[150:153], v[170:173], v[130:133]
	v_mfma_f32_16x16x32_bf16 v[126:129], v[162:165], v[170:173], v[126:129]
	v_mfma_f32_16x16x32_bf16 v[106:109], v[150:153], v[178:181], v[106:109]
	v_mfma_f32_16x16x32_bf16 v[102:105], v[162:165], v[178:181], v[102:105]
	v_mfma_f32_16x16x32_bf16 v[86:89], v[150:153], v[202:205], v[86:89]
	v_mfma_f32_16x16x32_bf16 v[82:85], v[162:165], v[202:205], v[82:85]
	v_mfma_f32_16x16x32_bf16 v[70:73], v[150:153], v[210:213], v[70:73]
	v_mfma_f32_16x16x32_bf16 v[66:69], v[162:165], v[210:213], v[66:69]
	s_setprio 0
	s_barrier
	ds_read_b128 v[166:169], v193 offset:16384
	ds_read_b128 v[170:173], v193 offset:17408
	ds_read_b128 v[174:177], v193 offset:18432
	ds_read_b128 v[178:181], v193 offset:19456
	ds_read_b128 v[198:201], v193 offset:20480
	ds_read_b128 v[202:205], v193 offset:21504
	ds_read_b128 v[206:209], v193 offset:22528
	ds_read_b128 v[210:213], v193 offset:23552
	s_mov_b32 m0, s91
	s_nop 0
	global_load_lds_dwordx4 v185, s[84:85]
	s_add_u32 s88, s84, 0x100000
	s_mov_b32 m0, s92
	s_nop 0
	global_load_lds_dwordx4 v187, s[84:85]
	s_addc_u32 s89, s85, 0
	s_mov_b32 m0, s93
	s_nop 0
	global_load_lds_dwordx4 v185, s[88:89]
	s_nop 0
	s_mov_b32 m0, s94
	s_nop 0
	global_load_lds_dwordx4 v187, s[88:89]
	s_nop 0
	s_mov_b32 m0, s35
	s_nop 0
	global_load_lds_dwordx4 v184, s[86:87]
	s_nop 0
	s_mov_b32 m0, s79
	s_nop 0
	global_load_lds_dwordx4 v186, s[86:87]
	s_waitcnt lgkmcnt(7)
	v_mfma_f32_16x16x32_bf16 v[62:65], v[98:101], v[166:169], v[62:65]
	v_mfma_f32_16x16x32_bf16 v[58:61], v[122:125], v[166:169], v[58:61]
	s_waitcnt lgkmcnt(5)
	v_mfma_f32_16x16x32_bf16 v[46:49], v[98:101], v[174:177], v[46:49]
	v_mfma_f32_16x16x32_bf16 v[42:45], v[122:125], v[174:177], v[42:45]
	s_waitcnt vmcnt(8)
	s_waitcnt lgkmcnt(0)
	s_barrier
; #define PG8_STAGE(bufoff, gbase, voff) do { if constexpr (VAR != 1 && VAR != 3) { _Pragma("unroll") for (int _i = 0; _i < 2; ++_i) \
;         asm volatile("s_mov_b32 m0, %2\n\ts_nop 0\n\tglobal_load_lds_dwordx4 %0, %1" :: "v"((voff)[_i]), "s"((const char*)(gbase)), "s"(ldsbase + (unsigned)((bufoff) + _i * 8192)) : "memory", "m0"); } } while (0)
; #define PG8_LDA(dst, b, h) do { if constexpr (VAR < 2) _Pragma("unroll") for (int m = 0; m < 4; ++m) _Pragma("unroll") for (int k = 0; k < 2; ++k) dst[m][k] = *(const LAS bf16x8*)(lds + PG8_SA(b, h) + aoff + m * 2048 + k * 1024); } while (0)
; #define PG8_LDB(dst, b, h) do { if constexpr (VAR < 2) _Pragma("unroll") for (int n = 0; n < 2; ++n) _Pragma("unroll") for (int k = 0; k < 2; ++k) dst[n][k] = *(const LAS bf16x8*)(lds + PG8_SB(b, h) + boff + n * 2048 + k * 1024); } while (0)
; #define PG8_WAIT_V(n) asm volatile("s_waitcnt vmcnt(" #n ")" ::: "memory")
; #define PG8_WAIT_L(n) asm volatile("s_waitcnt lgkmcnt(" #n ")" ::: "memory")
; #define PG8_BAR do { if constexpr (VAR != 3) __builtin_amdgcn_s_barrier(); } while (0)
; #define PG8_SCHED __builtin_amdgcn_sched_barrier(0)
;     ...
;             PG8_WAIT_V(8); PG8_WAIT_L(0); PG8_BAR; PG8_MMA(1, 0, At, B0); PG8_MMA(1, 1, At, B1); PG8_BAR; PG8_SCHED;
;             PG8_LDB(B0, 1, 0); PG8_LDB(B1, 1, 1); PG8_SCHED; PG8_LDA(At, 1, 0); PG8_STAGE(PG8_SA(0, 1), a2 + hstepA, voffA);
;             PG8_WAIT_V(8); PG8_WAIT_L(0); PG8_BAR; PG8_MMA(0, 0, At, B0); PG8_MMA(0, 1, At, B1); PG8_BAR; PG8_SCHED;
	s_setprio 1
	s_waitcnt lgkmcnt(3)
	v_mfma_f32_16x16x32_bf16 v[30:33], v[98:101], v[198:201], v[30:33]
	v_mfma_f32_16x16x32_bf16 v[26:29], v[122:125], v[198:201], v[26:29]
	s_waitcnt lgkmcnt(1)
	v_mfma_f32_16x16x32_bf16 v[14:17], v[98:101], v[206:209], v[14:17]
	v_mfma_f32_16x16x32_bf16 v[10:13], v[122:125], v[206:209], v[10:13]
	v_mfma_f32_16x16x32_bf16 v[62:65], v[110:113], v[170:173], v[62:65]
	v_mfma_f32_16x16x32_bf16 v[58:61], v[134:137], v[170:173], v[58:61]
	v_mfma_f32_16x16x32_bf16 v[46:49], v[110:113], v[178:181], v[46:49]
	v_mfma_f32_16x16x32_bf16 v[42:45], v[134:137], v[178:181], v[42:45]
	v_mfma_f32_16x16x32_bf16 v[30:33], v[110:113], v[202:205], v[30:33]
	v_mfma_f32_16x16x32_bf16 v[26:29], v[134:137], v[202:205], v[26:29]
	s_waitcnt lgkmcnt(0)
	v_mfma_f32_16x16x32_bf16 v[14:17], v[110:113], v[210:213], v[14:17]
	v_mfma_f32_16x16x32_bf16 v[10:13], v[134:137], v[210:213], v[10:13]
	s_setprio 0
	s_setprio 1
	v_mfma_f32_16x16x32_bf16 v[54:57], v[138:141], v[166:169], v[54:57]
	v_mfma_f32_16x16x32_bf16 v[50:53], v[154:157], v[166:169], v[50:53]
	v_mfma_f32_16x16x32_bf16 v[38:41], v[138:141], v[174:177], v[38:41]
	v_mfma_f32_16x16x32_bf16 v[34:37], v[154:157], v[174:177], v[34:37]
	v_mfma_f32_16x16x32_bf16 v[22:25], v[138:141], v[198:201], v[22:25]
	v_mfma_f32_16x16x32_bf16 v[18:21], v[154:157], v[198:201], v[18:21]
	v_mfma_f32_16x16x32_bf16 v[6:9], v[138:141], v[206:209], v[6:9]
	v_mfma_f32_16x16x32_bf16 v[2:5], v[154:157], v[206:209], v[2:5]
	v_mfma_f32_16x16x32_bf16 v[54:57], v[150:153], v[170:173], v[54:57]
	v_mfma_f32_16x16x32_bf16 v[50:53], v[162:165], v[170:173], v[50:53]
	v_mfma_f32_16x16x32_bf16 v[38:41], v[150:153], v[178:181], v[38:41]
	v_mfma_f32_16x16x32_bf16 v[34:37], v[162:165], v[178:181], v[34:37]
	v_mfma_f32_16x16x32_bf16 v[22:25], v[150:153], v[202:205], v[22:25]
	v_mfma_f32_16x16x32_bf16 v[18:21], v[162:165], v[202:205], v[18:21]
	v_mfma_f32_16x16x32_bf16 v[6:9], v[150:153], v[210:213], v[6:9]
	v_mfma_f32_16x16x32_bf16 v[2:5], v[162:165], v[210:213], v[2:5]
	s_setprio 0
	s_barrier
	ds_read_b128 v[98:101], v194
	ds_read_b128 v[110:113], v194 offset:1024
	ds_read_b128 v[122:125], v194 offset:2048
	ds_read_b128 v[134:137], v194 offset:3072
	ds_read_b128 v[138:141], v195
	ds_read_b128 v[150:153], v195 offset:1024
	ds_read_b128 v[154:157], v195 offset:2048
	ds_read_b128 v[162:165], v195 offset:3072
	ds_read_b128 v[166:169], v193 offset:32768
	ds_read_b128 v[170:173], v193 offset:33792
	ds_read_b128 v[174:177], v193 offset:34816
	ds_read_b128 v[178:181], v193 offset:35840
	ds_read_b128 v[198:201], v193 offset:36864
	ds_read_b128 v[202:205], v193 offset:37888
	ds_read_b128 v[206:209], v193 offset:38912
	ds_read_b128 v[210:213], v193 offset:39936
	s_add_u32 s86, s86, 0x100000
	s_addc_u32 s87, s87, 0
	s_mov_b32 m0, s95
	s_nop 0
	global_load_lds_dwordx4 v184, s[86:87]
	s_nop 0
	s_mov_b32 m0, s96
	s_nop 0
	global_load_lds_dwordx4 v186, s[86:87]
	s_waitcnt lgkmcnt(7)
	v_mfma_f32_16x16x32_bf16 v[146:149], v[98:101], v[166:169], v[146:149]
	v_mfma_f32_16x16x32_bf16 v[142:145], v[122:125], v[166:169], v[142:145]
	s_waitcnt lgkmcnt(5)
	v_mfma_f32_16x16x32_bf16 v[118:121], v[98:101], v[174:177], v[118:121]
	v_mfma_f32_16x16x32_bf16 v[114:117], v[122:125], v[174:177], v[114:117]
	s_waitcnt vmcnt(8)
	s_waitcnt lgkmcnt(0)
	s_barrier
	s_setprio 1
	s_waitcnt lgkmcnt(3)
	v_mfma_f32_16x16x32_bf16 v[94:97], v[98:101], v[198:201], v[94:97]
	v_mfma_f32_16x16x32_bf16 v[90:93], v[122:125], v[198:201], v[90:93]
	s_waitcnt lgkmcnt(1)
	v_mfma_f32_16x16x32_bf16 v[78:81], v[98:101], v[206:209], v[78:81]
	v_mfma_f32_16x16x32_bf16 v[74:77], v[122:125], v[206:209], v[74:77]
	v_mfma_f32_16x16x32_bf16 v[146:149], v[110:113], v[170:173], v[146:149]
	v_mfma_f32_16x16x32_bf16 v[142:145], v[134:137], v[170:173], v[142:145]
	v_mfma_f32_16x16x32_bf16 v[118:121], v[110:113], v[178:181], v[118:121]
	v_mfma_f32_16x16x32_bf16 v[114:117], v[134:137], v[178:181], v[114:117]
	v_mfma_f32_16x16x32_bf16 v[94:97], v[110:113], v[202:205], v[94:97]
	v_mfma_f32_16x16x32_bf16 v[90:93], v[134:137], v[202:205], v[90:93]
	s_waitcnt lgkmcnt(0)
	v_mfma_f32_16x16x32_bf16 v[78:81], v[110:113], v[210:213], v[78:81]
	v_mfma_f32_16x16x32_bf16 v[74:77], v[134:137], v[210:213], v[74:77]
	s_setprio 0
	s_setprio 1
	v_mfma_f32_16x16x32_bf16 v[130:133], v[138:141], v[166:169], v[130:133]
	v_mfma_f32_16x16x32_bf16 v[126:129], v[154:157], v[166:169], v[126:129]
	v_mfma_f32_16x16x32_bf16 v[106:109], v[138:141], v[174:177], v[106:109]
	v_mfma_f32_16x16x32_bf16 v[102:105], v[154:157], v[174:177], v[102:105]
	v_mfma_f32_16x16x32_bf16 v[86:89], v[138:141], v[198:201], v[86:89]
	v_mfma_f32_16x16x32_bf16 v[82:85], v[154:157], v[198:201], v[82:85]
	v_mfma_f32_16x16x32_bf16 v[70:73], v[138:141], v[206:209], v[70:73]
	v_mfma_f32_16x16x32_bf16 v[66:69], v[154:157], v[206:209], v[66:69]
	v_mfma_f32_16x16x32_bf16 v[130:133], v[150:153], v[170:173], v[130:133]
	v_mfma_f32_16x16x32_bf16 v[126:129], v[162:165], v[170:173], v[126:129]
	v_mfma_f32_16x16x32_bf16 v[106:109], v[150:153], v[178:181], v[106:109]
	v_mfma_f32_16x16x32_bf16 v[102:105], v[162:165], v[178:181], v[102:105]
	v_mfma_f32_16x16x32_bf16 v[86:89], v[150:153], v[202:205], v[86:89]
	v_mfma_f32_16x16x32_bf16 v[82:85], v[162:165], v[202:205], v[82:85]
	v_mfma_f32_16x16x32_bf16 v[70:73], v[150:153], v[210:213], v[70:73]
	v_mfma_f32_16x16x32_bf16 v[66:69], v[162:165], v[210:213], v[66:69]
	s_setprio 0
	s_barrier
; #define PG8_STAGE(bufoff, gbase, voff) do { if constexpr (VAR != 1 && VAR != 3) { _Pragma("unroll") for (int _i = 0; _i < 2; ++_i) \
;         asm volatile("s_mov_b32 m0, %2\n\ts_nop 0\n\tglobal_load_lds_dwordx4 %0, %1" :: "v"((voff)[_i]), "s"((const char*)(gbase)), "s"(ldsbase + (unsigned)((bufoff) + _i * 8192)) : "memory", "m0"); } } while (0)
; #define PG8_LDA(dst, b, h) do { if constexpr (VAR < 2) _Pragma("unroll") for (int m = 0; m < 4; ++m) _Pragma("unroll") for (int k = 0; k < 2; ++k) dst[m][k] = *(const LAS bf16x8*)(lds + PG8_SA(b, h) + aoff + m * 2048 + k * 1024); } while (0)
; #define PG8_WAIT_V(n) asm volatile("s_waitcnt vmcnt(" #n ")" ::: "memory")
; #define PG8_WAIT_L(n) asm volatile("s_waitcnt lgkmcnt(" #n ")" ::: "memory")
; #define PG8_BAR do { if constexpr (VAR != 3) __builtin_amdgcn_s_barrier(); } while (0)
; #define PG8_SCHED __builtin_amdgcn_sched_barrier(0)
;     ...
;             PG8_LDA(At, 1, 1); PG8_STAGE(PG8_SB(1, 0), b3, voffB); PG8_STAGE(PG8_SB(1, 1), b3 + hstepB, voffB); PG8_STAGE(PG8_SA(1, 0), a3, voffA);
;             PG8_WAIT_V(8); PG8_WAIT_L(0); PG8_BAR; PG8_MMA(1, 0, At, B0); PG8_MMA(1, 1, At, B1); PG8_BAR; PG8_SCHED;
;         }
;         if (wr == 0) PG8_BAR;
	ds_read_b128 v[166:169], v193 offset:49152
	ds_read_b128 v[170:173], v193 offset:50176
	ds_read_b128 v[174:177], v193 offset:51200
	ds_read_b128 v[178:181], v193 offset:52224
	ds_read_b128 v[198:201], v193 offset:53248
	ds_read_b128 v[202:205], v193 offset:54272
	ds_read_b128 v[206:209], v193 offset:55296
	ds_read_b128 v[210:213], v193 offset:56320
	s_add_u32 s86, s84, 0x80
	s_addc_u32 s87, s85, 0
	s_mov_b32 m0, s64
	s_nop 0
	global_load_lds_dwordx4 v185, s[86:87]
	s_add_u32 s84, s84, 0x100080
	s_mov_b32 m0, s65
	s_nop 0
	global_load_lds_dwordx4 v187, s[86:87]
	s_addc_u32 s85, s85, 0
	s_mov_b32 m0, s33
	s_nop 0
	global_load_lds_dwordx4 v185, s[84:85]
	s_nop 0
	s_mov_b32 m0, s30
	s_nop 0
	global_load_lds_dwordx4 v187, s[84:85]
	s_nop 0
	s_mov_b32 m0, s17
	s_nop 0
	global_load_lds_dwordx4 v184, s[82:83]
	s_nop 0
	s_mov_b32 m0, s28
	s_nop 0
	global_load_lds_dwordx4 v186, s[82:83]
	s_waitcnt lgkmcnt(7)
	v_mfma_f32_16x16x32_bf16 v[62:65], v[98:101], v[166:169], v[62:65]
	v_mfma_f32_16x16x32_bf16 v[58:61], v[122:125], v[166:169], v[58:61]
	s_waitcnt lgkmcnt(5)
	v_mfma_f32_16x16x32_bf16 v[46:49], v[98:101], v[174:177], v[46:49]
	v_mfma_f32_16x16x32_bf16 v[42:45], v[122:125], v[174:177], v[42:45]
	s_waitcnt vmcnt(8)
	s_waitcnt lgkmcnt(0)
	s_barrier
	s_setprio 1
	s_waitcnt lgkmcnt(3)
	v_mfma_f32_16x16x32_bf16 v[30:33], v[98:101], v[198:201], v[30:33]
	v_mfma_f32_16x16x32_bf16 v[26:29], v[122:125], v[198:201], v[26:29]
	s_waitcnt lgkmcnt(1)
	v_mfma_f32_16x16x32_bf16 v[14:17], v[98:101], v[206:209], v[14:17]
	v_mfma_f32_16x16x32_bf16 v[10:13], v[122:125], v[206:209], v[10:13]
	v_mfma_f32_16x16x32_bf16 v[62:65], v[110:113], v[170:173], v[62:65]
	v_mfma_f32_16x16x32_bf16 v[58:61], v[134:137], v[170:173], v[58:61]
	v_mfma_f32_16x16x32_bf16 v[46:49], v[110:113], v[178:181], v[46:49]
	v_mfma_f32_16x16x32_bf16 v[42:45], v[134:137], v[178:181], v[42:45]
	v_mfma_f32_16x16x32_bf16 v[30:33], v[110:113], v[202:205], v[30:33]
	v_mfma_f32_16x16x32_bf16 v[26:29], v[134:137], v[202:205], v[26:29]
	s_waitcnt lgkmcnt(0)
	v_mfma_f32_16x16x32_bf16 v[14:17], v[110:113], v[210:213], v[14:17]
	v_mfma_f32_16x16x32_bf16 v[10:13], v[134:137], v[210:213], v[10:13]
	s_setprio 0
	s_setprio 1
	v_mfma_f32_16x16x32_bf16 v[54:57], v[138:141], v[166:169], v[54:57]
	v_mfma_f32_16x16x32_bf16 v[50:53], v[154:157], v[166:169], v[50:53]
	v_mfma_f32_16x16x32_bf16 v[38:41], v[138:141], v[174:177], v[38:41]
	v_mfma_f32_16x16x32_bf16 v[34:37], v[154:157], v[174:177], v[34:37]
	v_mfma_f32_16x16x32_bf16 v[22:25], v[138:141], v[198:201], v[22:25]
	v_mfma_f32_16x16x32_bf16 v[18:21], v[154:157], v[198:201], v[18:21]
	v_mfma_f32_16x16x32_bf16 v[6:9], v[138:141], v[206:209], v[6:9]
	v_mfma_f32_16x16x32_bf16 v[2:5], v[154:157], v[206:209], v[2:5]
	v_mfma_f32_16x16x32_bf16 v[54:57], v[150:153], v[170:173], v[54:57]
	v_mfma_f32_16x16x32_bf16 v[50:53], v[162:165], v[170:173], v[50:53]
	v_mfma_f32_16x16x32_bf16 v[38:41], v[150:153], v[178:181], v[38:41]
	v_mfma_f32_16x16x32_bf16 v[34:37], v[162:165], v[178:181], v[34:37]
	v_mfma_f32_16x16x32_bf16 v[22:25], v[150:153], v[202:205], v[22:25]
	v_mfma_f32_16x16x32_bf16 v[18:21], v[162:165], v[202:205], v[18:21]
	v_mfma_f32_16x16x32_bf16 v[6:9], v[150:153], v[210:213], v[6:9]
	v_mfma_f32_16x16x32_bf16 v[2:5], v[162:165], v[210:213], v[2:5]
	s_setprio 0
	s_barrier
	s_add_i32 vcc_hi, vcc_hi, 2
	s_add_u32 s27, s27, 0x100
	s_addc_u32 s71, s71, 0
	s_add_u32 s73, s73, 0x100
	s_addc_u32 vcc_lo, vcc_lo, 0
	s_add_u32 s80, s80, 0x100
	s_addc_u32 s81, s81, 0
	s_cmp_gt_u32 vcc_hi, 61
	s_cbranch_scc0 .LBB0_789
	s_and_b64 vcc, exec, s[68:69]
	s_cbranch_vccz .LBB0_792
	s_barrier

; #define PG8_STAGE(bufoff, gbase, voff) do { if constexpr (VAR != 1 && VAR != 3) { _Pragma("unroll") for (int _i = 0; _i < 2; ++_i) \
;         asm volatile("s_mov_b32 m0, %2\n\ts_nop 0\n\tglobal_load_lds_dwordx4 %0, %1" :: "v"((voff)[_i]), "s"((const char*)(gbase)), "s"(ldsbase + (unsigned)((bufoff) + _i * 8192)) : "memory", "m0"); } } while (0)
; #define PG8_LDA(dst, b, h) do { if constexpr (VAR < 2) _Pragma("unroll") for (int m = 0; m < 4; ++m) _Pragma("unroll") for (int k = 0; k < 2; ++k) dst[m][k] = *(const LAS bf16x8*)(lds + PG8_SA(b, h) + aoff + m * 2048 + k * 1024); } while (0)
; #define PG8_LDB(dst, b, h) do { if constexpr (VAR < 2) _Pragma("unroll") for (int n = 0; n < 2; ++n) _Pragma("unroll") for (int k = 0; k < 2; ++k) dst[n][k] = *(const LAS bf16x8*)(lds + PG8_SB(b, h) + boff + n * 2048 + k * 1024); } while (0)
; #define PG8_WAIT_V(n) asm volatile("s_waitcnt vmcnt(" #n ")" ::: "memory")
; #define PG8_WAIT_L(n) asm volatile("s_waitcnt lgkmcnt(" #n ")" ::: "memory")
; #define PG8_BAR do { if constexpr (VAR != 3) __builtin_amdgcn_s_barrier(); } while (0)
; #define PG8_SCHED __builtin_amdgcn_sched_barrier(0)
;     ...
;         for (int t = 0; t < nt; t += 2) {
;             const bool last = (t == nt - 2);
;             const char* a1 = cA + (size_t)(t + 1) * kstep;
;             const char* a2 = last ? nA : cA + (size_t)(t + 2) * kstep; const char* b2 = last ? nB : cB + (size_t)(t + 2) * kstep;
;             const char* a3 = a2 + kstep; const char* b3 = b2 + kstep;
;             PG8_LDB(B0, 0, 0); PG8_LDB(B1, 0, 1); PG8_SCHED; PG8_LDA(At, 0, 0); PG8_STAGE(PG8_SA(1, 1), a1 + hstepA, voffA);
;             PG8_WAIT_V(8); PG8_WAIT_L(0); PG8_BAR; PG8_MMA(0, 0, At, B0); PG8_MMA(0, 1, At, B1); PG8_BAR; PG8_SCHED;
;             PG8_LDA(At, 0, 1); PG8_STAGE(PG8_SB(0, 0), b2, voffB); PG8_STAGE(PG8_SB(0, 1), b2 + hstepB, voffB); PG8_STAGE(PG8_SA(0, 0), a2, voffA);
;             PG8_WAIT_V(8); PG8_WAIT_L(0); PG8_BAR; PG8_MMA(1, 0, At, B0); PG8_MMA(1, 1, At, B1); PG8_BAR; PG8_SCHED;
.LBB0_892:
	ds_read_b128 v[134:137], v201
	ds_read_b128 v[138:141], v201 offset:1024
	ds_read_b128 v[142:145], v201 offset:2048
	ds_read_b128 v[146:149], v201 offset:3072
	ds_read_b128 v[150:153], v202
	ds_read_b128 v[154:157], v202 offset:1024
	ds_read_b128 v[158:161], v202 offset:2048
	ds_read_b128 v[162:165], v202 offset:3072
	s_cmp_eq_u32 s85, 60
	s_cselect_b32 s72, s24, s25
	s_cselect_b32 s73, s1, s39
	s_cselect_b32 s70, s60, s59
	s_cselect_b32 s71, s61, s84
	s_add_u32 s68, s72, 0x80
	s_addc_u32 s69, s73, 0
	ds_read_b128 v[166:169], v203
	ds_read_b128 v[210:213], v203 offset:1024
	ds_read_b128 v[214:217], v203 offset:2048
	ds_read_b128 v[218:221], v203 offset:3072
	ds_read_b128 v[222:225], v203 offset:4096
	ds_read_b128 v[226:229], v203 offset:5120
	ds_read_b128 v[230:233], v203 offset:6144
	ds_read_b128 v[234:237], v203 offset:7168
	s_mov_b32 m0, s77
	s_nop 0
	global_load_lds_dwordx4 v1, s[6:7]
	s_nop 0
	s_mov_b32 m0, s79
	s_nop 0
	global_load_lds_dwordx4 v173, s[6:7]
	s_waitcnt lgkmcnt(7)
	v_mfma_f32_16x16x32_bf16 v[126:129], v[134:137], v[166:169], v[126:129]
	v_mfma_f32_16x16x32_bf16 v[122:125], v[142:145], v[166:169], v[122:125]
	s_waitcnt lgkmcnt(5)
	v_mfma_f32_16x16x32_bf16 v[110:113], v[134:137], v[214:217], v[110:113]
	v_mfma_f32_16x16x32_bf16 v[106:109], v[142:145], v[214:217], v[106:109]
	s_waitcnt vmcnt(8)
	s_waitcnt lgkmcnt(0)
	s_barrier
	s_setprio 1
	s_waitcnt lgkmcnt(3)
	v_mfma_f32_16x16x32_bf16 v[94:97], v[134:137], v[222:225], v[94:97]
	v_mfma_f32_16x16x32_bf16 v[90:93], v[142:145], v[222:225], v[90:93]
	s_waitcnt lgkmcnt(1)
	v_mfma_f32_16x16x32_bf16 v[78:81], v[134:137], v[230:233], v[78:81]
	v_mfma_f32_16x16x32_bf16 v[74:77], v[142:145], v[230:233], v[74:77]
	v_mfma_f32_16x16x32_bf16 v[126:129], v[138:141], v[210:213], v[126:129]
	v_mfma_f32_16x16x32_bf16 v[122:125], v[146:149], v[210:213], v[122:125]
	v_mfma_f32_16x16x32_bf16 v[110:113], v[138:141], v[218:221], v[110:113]
	v_mfma_f32_16x16x32_bf16 v[106:109], v[146:149], v[218:221], v[106:109]
	v_mfma_f32_16x16x32_bf16 v[94:97], v[138:141], v[226:229], v[94:97]
	v_mfma_f32_16x16x32_bf16 v[90:93], v[146:149], v[226:229], v[90:93]
	s_waitcnt lgkmcnt(0)
	v_mfma_f32_16x16x32_bf16 v[78:81], v[138:141], v[234:237], v[78:81]
	v_mfma_f32_16x16x32_bf16 v[74:77], v[146:149], v[234:237], v[74:77]
	s_setprio 0
	s_setprio 1
	v_mfma_f32_16x16x32_bf16 v[118:121], v[150:153], v[166:169], v[118:121]
	v_mfma_f32_16x16x32_bf16 v[114:117], v[158:161], v[166:169], v[114:117]
	v_mfma_f32_16x16x32_bf16 v[102:105], v[150:153], v[214:217], v[102:105]
	v_mfma_f32_16x16x32_bf16 v[98:101], v[158:161], v[214:217], v[98:101]
	v_mfma_f32_16x16x32_bf16 v[86:89], v[150:153], v[222:225], v[86:89]
	v_mfma_f32_16x16x32_bf16 v[82:85], v[158:161], v[222:225], v[82:85]
	v_mfma_f32_16x16x32_bf16 v[70:73], v[150:153], v[230:233], v[70:73]
	v_mfma_f32_16x16x32_bf16 v[66:69], v[158:161], v[230:233], v[66:69]
	v_mfma_f32_16x16x32_bf16 v[118:121], v[154:157], v[210:213], v[118:121]
	v_mfma_f32_16x16x32_bf16 v[114:117], v[162:165], v[210:213], v[114:117]
	v_mfma_f32_16x16x32_bf16 v[102:105], v[154:157], v[218:221], v[102:105]
	v_mfma_f32_16x16x32_bf16 v[98:101], v[162:165], v[218:221], v[98:101]
	v_mfma_f32_16x16x32_bf16 v[86:89], v[154:157], v[226:229], v[86:89]
	v_mfma_f32_16x16x32_bf16 v[82:85], v[162:165], v[226:229], v[82:85]
	v_mfma_f32_16x16x32_bf16 v[70:73], v[154:157], v[234:237], v[70:73]
	v_mfma_f32_16x16x32_bf16 v[66:69], v[162:165], v[234:237], v[66:69]
	s_setprio 0
	s_barrier
	ds_read_b128 v[166:169], v203 offset:16384
	ds_read_b128 v[210:213], v203 offset:17408
	ds_read_b128 v[214:217], v203 offset:18432
	ds_read_b128 v[218:221], v203 offset:19456
	ds_read_b128 v[222:225], v203 offset:20480
	ds_read_b128 v[226:229], v203 offset:21504
	ds_read_b128 v[230:233], v203 offset:22528
	ds_read_b128 v[234:237], v203 offset:23552
	s_mov_b32 m0, s17
	s_nop 0
	global_load_lds_dwordx4 v172, s[70:71]
	s_add_u32 s86, s70, 0x100000
	s_mov_b32 m0, s19
	s_nop 0
	global_load_lds_dwordx4 v174, s[70:71]
	s_addc_u32 s87, s71, 0
	s_mov_b32 m0, s23
	s_nop 0
	global_load_lds_dwordx4 v172, s[86:87]
	s_nop 0
	s_mov_b32 m0, s26
	s_nop 0
	global_load_lds_dwordx4 v174, s[86:87]
	s_nop 0
	s_mov_b32 m0, s15
	s_nop 0
	global_load_lds_dwordx4 v1, s[72:73]
	s_nop 0
	s_mov_b32 m0, s27
	s_nop 0
	global_load_lds_dwordx4 v173, s[72:73]
	s_waitcnt lgkmcnt(7)
	v_mfma_f32_16x16x32_bf16 v[62:65], v[134:137], v[166:169], v[62:65]
	v_mfma_f32_16x16x32_bf16 v[58:61], v[142:145], v[166:169], v[58:61]
	s_waitcnt lgkmcnt(5)
	v_mfma_f32_16x16x32_bf16 v[46:49], v[134:137], v[214:217], v[46:49]
	v_mfma_f32_16x16x32_bf16 v[42:45], v[142:145], v[214:217], v[42:45]
	s_waitcnt vmcnt(8)
	s_waitcnt lgkmcnt(0)
	s_barrier
; #define PG8_STAGE(bufoff, gbase, voff) do { if constexpr (VAR != 1 && VAR != 3) { _Pragma("unroll") for (int _i = 0; _i < 2; ++_i) \
;         asm volatile("s_mov_b32 m0, %2\n\ts_nop 0\n\tglobal_load_lds_dwordx4 %0, %1" :: "v"((voff)[_i]), "s"((const char*)(gbase)), "s"(ldsbase + (unsigned)((bufoff) + _i * 8192)) : "memory", "m0"); } } while (0)
; #define PG8_LDA(dst, b, h) do { if constexpr (VAR < 2) _Pragma("unroll") for (int m = 0; m < 4; ++m) _Pragma("unroll") for (int k = 0; k < 2; ++k) dst[m][k] = *(const LAS bf16x8*)(lds + PG8_SA(b, h) + aoff + m * 2048 + k * 1024); } while (0)
; #define PG8_LDB(dst, b, h) do { if constexpr (VAR < 2) _Pragma("unroll") for (int n = 0; n < 2; ++n) _Pragma("unroll") for (int k = 0; k < 2; ++k) dst[n][k] = *(const LAS bf16x8*)(lds + PG8_SB(b, h) + boff + n * 2048 + k * 1024); } while (0)
; #define PG8_WAIT_V(n) asm volatile("s_waitcnt vmcnt(" #n ")" ::: "memory")
; #define PG8_WAIT_L(n) asm volatile("s_waitcnt lgkmcnt(" #n ")" ::: "memory")
; #define PG8_BAR do { if constexpr (VAR != 3) __builtin_amdgcn_s_barrier(); } while (0)
; #define PG8_SCHED __builtin_amdgcn_sched_barrier(0)
;     ...
;             PG8_WAIT_V(8); PG8_WAIT_L(0); PG8_BAR; PG8_MMA(1, 0, At, B0); PG8_MMA(1, 1, At, B1); PG8_BAR; PG8_SCHED;
;             PG8_LDB(B0, 1, 0); PG8_LDB(B1, 1, 1); PG8_SCHED; PG8_LDA(At, 1, 0); PG8_STAGE(PG8_SA(0, 1), a2 + hstepA, voffA);
;             PG8_WAIT_V(8); PG8_WAIT_L(0); PG8_BAR; PG8_MMA(0, 0, At, B0); PG8_MMA(0, 1, At, B1); PG8_BAR; PG8_SCHED;
	s_setprio 1
	s_waitcnt lgkmcnt(3)
	v_mfma_f32_16x16x32_bf16 v[30:33], v[134:137], v[222:225], v[30:33]
	v_mfma_f32_16x16x32_bf16 v[26:29], v[142:145], v[222:225], v[26:29]
	s_waitcnt lgkmcnt(1)
	v_mfma_f32_16x16x32_bf16 v[14:17], v[134:137], v[230:233], v[14:17]
	v_mfma_f32_16x16x32_bf16 v[10:13], v[142:145], v[230:233], v[10:13]
	v_mfma_f32_16x16x32_bf16 v[62:65], v[138:141], v[210:213], v[62:65]
	v_mfma_f32_16x16x32_bf16 v[58:61], v[146:149], v[210:213], v[58:61]
	v_mfma_f32_16x16x32_bf16 v[46:49], v[138:141], v[218:221], v[46:49]
	v_mfma_f32_16x16x32_bf16 v[42:45], v[146:149], v[218:221], v[42:45]
	v_mfma_f32_16x16x32_bf16 v[30:33], v[138:141], v[226:229], v[30:33]
	v_mfma_f32_16x16x32_bf16 v[26:29], v[146:149], v[226:229], v[26:29]
	s_waitcnt lgkmcnt(0)
	v_mfma_f32_16x16x32_bf16 v[14:17], v[138:141], v[234:237], v[14:17]
	v_mfma_f32_16x16x32_bf16 v[10:13], v[146:149], v[234:237], v[10:13]
	s_setprio 0
	s_setprio 1
	v_mfma_f32_16x16x32_bf16 v[54:57], v[150:153], v[166:169], v[54:57]
	v_mfma_f32_16x16x32_bf16 v[50:53], v[158:161], v[166:169], v[50:53]
	v_mfma_f32_16x16x32_bf16 v[38:41], v[150:153], v[214:217], v[38:41]
	v_mfma_f32_16x16x32_bf16 v[34:37], v[158:161], v[214:217], v[34:37]
	v_mfma_f32_16x16x32_bf16 v[22:25], v[150:153], v[222:225], v[22:25]
	v_mfma_f32_16x16x32_bf16 v[18:21], v[158:161], v[222:225], v[18:21]
	v_mfma_f32_16x16x32_bf16 v[6:9], v[150:153], v[230:233], v[6:9]
	v_mfma_f32_16x16x32_bf16 v[2:5], v[158:161], v[230:233], v[2:5]
	v_mfma_f32_16x16x32_bf16 v[54:57], v[154:157], v[210:213], v[54:57]
	v_mfma_f32_16x16x32_bf16 v[50:53], v[162:165], v[210:213], v[50:53]
	v_mfma_f32_16x16x32_bf16 v[38:41], v[154:157], v[218:221], v[38:41]
	v_mfma_f32_16x16x32_bf16 v[34:37], v[162:165], v[218:221], v[34:37]
	v_mfma_f32_16x16x32_bf16 v[22:25], v[154:157], v[226:229], v[22:25]
	v_mfma_f32_16x16x32_bf16 v[18:21], v[162:165], v[226:229], v[18:21]
	v_mfma_f32_16x16x32_bf16 v[6:9], v[154:157], v[234:237], v[6:9]
	v_mfma_f32_16x16x32_bf16 v[2:5], v[162:165], v[234:237], v[2:5]
	s_setprio 0
	s_barrier
	ds_read_b128 v[134:137], v204
	ds_read_b128 v[138:141], v204 offset:1024
	ds_read_b128 v[142:145], v204 offset:2048
	ds_read_b128 v[146:149], v204 offset:3072
	ds_read_b128 v[150:153], v205
	ds_read_b128 v[154:157], v205 offset:1024
	ds_read_b128 v[158:161], v205 offset:2048
	ds_read_b128 v[162:165], v205 offset:3072
	ds_read_b128 v[166:169], v203 offset:32768
	ds_read_b128 v[210:213], v203 offset:33792
	ds_read_b128 v[214:217], v203 offset:34816
	ds_read_b128 v[218:221], v203 offset:35840
	ds_read_b128 v[222:225], v203 offset:36864
	ds_read_b128 v[226:229], v203 offset:37888
	ds_read_b128 v[230:233], v203 offset:38912
	ds_read_b128 v[234:237], v203 offset:39936
	s_add_u32 s72, s72, 0x100000
	s_addc_u32 s73, s73, 0
	s_mov_b32 m0, s28
	s_nop 0
	global_load_lds_dwordx4 v1, s[72:73]
	s_nop 0
	s_mov_b32 m0, s29
	s_nop 0
	global_load_lds_dwordx4 v173, s[72:73]
	s_waitcnt lgkmcnt(7)
	v_mfma_f32_16x16x32_bf16 v[126:129], v[134:137], v[166:169], v[126:129]
	v_mfma_f32_16x16x32_bf16 v[122:125], v[142:145], v[166:169], v[122:125]
	s_waitcnt lgkmcnt(5)
	v_mfma_f32_16x16x32_bf16 v[110:113], v[134:137], v[214:217], v[110:113]
	v_mfma_f32_16x16x32_bf16 v[106:109], v[142:145], v[214:217], v[106:109]
	s_waitcnt vmcnt(8)
	s_waitcnt lgkmcnt(0)
	s_barrier
	s_setprio 1
	s_waitcnt lgkmcnt(3)
	v_mfma_f32_16x16x32_bf16 v[94:97], v[134:137], v[222:225], v[94:97]
	v_mfma_f32_16x16x32_bf16 v[90:93], v[142:145], v[222:225], v[90:93]
	s_waitcnt lgkmcnt(1)
	v_mfma_f32_16x16x32_bf16 v[78:81], v[134:137], v[230:233], v[78:81]
	v_mfma_f32_16x16x32_bf16 v[74:77], v[142:145], v[230:233], v[74:77]
	v_mfma_f32_16x16x32_bf16 v[126:129], v[138:141], v[210:213], v[126:129]
	v_mfma_f32_16x16x32_bf16 v[122:125], v[146:149], v[210:213], v[122:125]
	v_mfma_f32_16x16x32_bf16 v[110:113], v[138:141], v[218:221], v[110:113]
	v_mfma_f32_16x16x32_bf16 v[106:109], v[146:149], v[218:221], v[106:109]
	v_mfma_f32_16x16x32_bf16 v[94:97], v[138:141], v[226:229], v[94:97]
	v_mfma_f32_16x16x32_bf16 v[90:93], v[146:149], v[226:229], v[90:93]
	s_waitcnt lgkmcnt(0)
	v_mfma_f32_16x16x32_bf16 v[78:81], v[138:141], v[234:237], v[78:81]
	v_mfma_f32_16x16x32_bf16 v[74:77], v[146:149], v[234:237], v[74:77]
	s_setprio 0
	s_setprio 1
	v_mfma_f32_16x16x32_bf16 v[118:121], v[150:153], v[166:169], v[118:121]
	v_mfma_f32_16x16x32_bf16 v[114:117], v[158:161], v[166:169], v[114:117]
	v_mfma_f32_16x16x32_bf16 v[102:105], v[150:153], v[214:217], v[102:105]
	v_mfma_f32_16x16x32_bf16 v[98:101], v[158:161], v[214:217], v[98:101]
	v_mfma_f32_16x16x32_bf16 v[86:89], v[150:153], v[222:225], v[86:89]
	v_mfma_f32_16x16x32_bf16 v[82:85], v[158:161], v[222:225], v[82:85]
	v_mfma_f32_16x16x32_bf16 v[70:73], v[150:153], v[230:233], v[70:73]
	v_mfma_f32_16x16x32_bf16 v[66:69], v[158:161], v[230:233], v[66:69]
	v_mfma_f32_16x16x32_bf16 v[118:121], v[154:157], v[210:213], v[118:121]
	v_mfma_f32_16x16x32_bf16 v[114:117], v[162:165], v[210:213], v[114:117]
	v_mfma_f32_16x16x32_bf16 v[102:105], v[154:157], v[218:221], v[102:105]
	v_mfma_f32_16x16x32_bf16 v[98:101], v[162:165], v[218:221], v[98:101]
	v_mfma_f32_16x16x32_bf16 v[86:89], v[154:157], v[226:229], v[86:89]
	v_mfma_f32_16x16x32_bf16 v[82:85], v[162:165], v[226:229], v[82:85]
	v_mfma_f32_16x16x32_bf16 v[70:73], v[154:157], v[234:237], v[70:73]
	v_mfma_f32_16x16x32_bf16 v[66:69], v[162:165], v[234:237], v[66:69]
	s_setprio 0
	s_barrier
; #define PG8_STAGE(bufoff, gbase, voff) do { if constexpr (VAR != 1 && VAR != 3) { _Pragma("unroll") for (int _i = 0; _i < 2; ++_i) \
;         asm volatile("s_mov_b32 m0, %2\n\ts_nop 0\n\tglobal_load_lds_dwordx4 %0, %1" :: "v"((voff)[_i]), "s"((const char*)(gbase)), "s"(ldsbase + (unsigned)((bufoff) + _i * 8192)) : "memory", "m0"); } } while (0)
; #define PG8_LDA(dst, b, h) do { if constexpr (VAR < 2) _Pragma("unroll") for (int m = 0; m < 4; ++m) _Pragma("unroll") for (int k = 0; k < 2; ++k) dst[m][k] = *(const LAS bf16x8*)(lds + PG8_SA(b, h) + aoff + m * 2048 + k * 1024); } while (0)
; #define PG8_WAIT_V(n) asm volatile("s_waitcnt vmcnt(" #n ")" ::: "memory")
; #define PG8_WAIT_L(n) asm volatile("s_waitcnt lgkmcnt(" #n ")" ::: "memory")
; #define PG8_BAR do { if constexpr (VAR != 3) __builtin_amdgcn_s_barrier(); } while (0)
; #define PG8_SCHED __builtin_amdgcn_sched_barrier(0)
;     ...
;             PG8_LDA(At, 1, 1); PG8_STAGE(PG8_SB(1, 0), b3, voffB); PG8_STAGE(PG8_SB(1, 1), b3 + hstepB, voffB); PG8_STAGE(PG8_SA(1, 0), a3, voffA);
;             PG8_WAIT_V(8); PG8_WAIT_L(0); PG8_BAR; PG8_MMA(1, 0, At, B0); PG8_MMA(1, 1, At, B1); PG8_BAR; PG8_SCHED;
;         }
;         if (wr == 0) PG8_BAR;
	ds_read_b128 v[166:169], v203 offset:49152
	ds_read_b128 v[210:213], v203 offset:50176
	ds_read_b128 v[214:217], v203 offset:51200
	ds_read_b128 v[218:221], v203 offset:52224
	ds_read_b128 v[222:225], v203 offset:53248
	ds_read_b128 v[226:229], v203 offset:54272
	ds_read_b128 v[230:233], v203 offset:55296
	ds_read_b128 v[234:237], v203 offset:56320
	s_add_u32 s72, s70, 0x80
	s_addc_u32 s73, s71, 0
	s_mov_b32 m0, s33
	s_nop 0
	global_load_lds_dwordx4 v172, s[72:73]
	s_add_u32 s70, s70, 0x100080
	s_mov_b32 m0, s35
	s_nop 0
	global_load_lds_dwordx4 v174, s[72:73]
	s_addc_u32 s71, s71, 0
	s_mov_b32 m0, s75
	s_nop 0
	global_load_lds_dwordx4 v172, s[70:71]
	s_nop 0
	s_mov_b32 m0, s76
	s_nop 0
	global_load_lds_dwordx4 v174, s[70:71]
	s_nop 0
	s_mov_b32 m0, s67
	s_nop 0
	global_load_lds_dwordx4 v1, s[68:69]
	s_nop 0
	s_mov_b32 m0, s74
	s_nop 0
	global_load_lds_dwordx4 v173, s[68:69]
	s_waitcnt lgkmcnt(7)
	v_mfma_f32_16x16x32_bf16 v[62:65], v[134:137], v[166:169], v[62:65]
	v_mfma_f32_16x16x32_bf16 v[58:61], v[142:145], v[166:169], v[58:61]
	s_waitcnt lgkmcnt(5)
	v_mfma_f32_16x16x32_bf16 v[46:49], v[134:137], v[214:217], v[46:49]
	v_mfma_f32_16x16x32_bf16 v[42:45], v[142:145], v[214:217], v[42:45]
	s_waitcnt vmcnt(8)
	s_waitcnt lgkmcnt(0)
	s_barrier
	s_setprio 1
	s_waitcnt lgkmcnt(3)
	v_mfma_f32_16x16x32_bf16 v[30:33], v[134:137], v[222:225], v[30:33]
	v_mfma_f32_16x16x32_bf16 v[26:29], v[142:145], v[222:225], v[26:29]
	s_waitcnt lgkmcnt(1)
	v_mfma_f32_16x16x32_bf16 v[14:17], v[134:137], v[230:233], v[14:17]
	v_mfma_f32_16x16x32_bf16 v[10:13], v[142:145], v[230:233], v[10:13]
	v_mfma_f32_16x16x32_bf16 v[62:65], v[138:141], v[210:213], v[62:65]
	v_mfma_f32_16x16x32_bf16 v[58:61], v[146:149], v[210:213], v[58:61]
	v_mfma_f32_16x16x32_bf16 v[46:49], v[138:141], v[218:221], v[46:49]
	v_mfma_f32_16x16x32_bf16 v[42:45], v[146:149], v[218:221], v[42:45]
	v_mfma_f32_16x16x32_bf16 v[30:33], v[138:141], v[226:229], v[30:33]
	v_mfma_f32_16x16x32_bf16 v[26:29], v[146:149], v[226:229], v[26:29]
	s_waitcnt lgkmcnt(0)
	v_mfma_f32_16x16x32_bf16 v[14:17], v[138:141], v[234:237], v[14:17]
	v_mfma_f32_16x16x32_bf16 v[10:13], v[146:149], v[234:237], v[10:13]
	s_setprio 0
	s_setprio 1
	v_mfma_f32_16x16x32_bf16 v[54:57], v[150:153], v[166:169], v[54:57]
	v_mfma_f32_16x16x32_bf16 v[50:53], v[158:161], v[166:169], v[50:53]
	v_mfma_f32_16x16x32_bf16 v[38:41], v[150:153], v[214:217], v[38:41]
	v_mfma_f32_16x16x32_bf16 v[34:37], v[158:161], v[214:217], v[34:37]
	v_mfma_f32_16x16x32_bf16 v[22:25], v[150:153], v[222:225], v[22:25]
	v_mfma_f32_16x16x32_bf16 v[18:21], v[158:161], v[222:225], v[18:21]
	v_mfma_f32_16x16x32_bf16 v[6:9], v[150:153], v[230:233], v[6:9]
	v_mfma_f32_16x16x32_bf16 v[2:5], v[158:161], v[230:233], v[2:5]
	v_mfma_f32_16x16x32_bf16 v[54:57], v[154:157], v[210:213], v[54:57]
	v_mfma_f32_16x16x32_bf16 v[50:53], v[162:165], v[210:213], v[50:53]
	v_mfma_f32_16x16x32_bf16 v[38:41], v[154:157], v[218:221], v[38:41]
	v_mfma_f32_16x16x32_bf16 v[34:37], v[162:165], v[218:221], v[34:37]
	v_mfma_f32_16x16x32_bf16 v[22:25], v[154:157], v[226:229], v[22:25]
	v_mfma_f32_16x16x32_bf16 v[18:21], v[162:165], v[226:229], v[18:21]
	v_mfma_f32_16x16x32_bf16 v[6:9], v[154:157], v[234:237], v[6:9]
	v_mfma_f32_16x16x32_bf16 v[2:5], v[162:165], v[234:237], v[2:5]
	s_setprio 0
	s_barrier
	s_add_i32 s85, s85, 2
	s_add_u32 s25, s25, 0x100
	s_addc_u32 s39, s39, 0
	s_add_u32 s59, s59, 0x100
	s_addc_u32 s84, s84, 0
	s_add_u32 s6, s6, 0x100
	s_addc_u32 s7, s7, 0
	s_cmp_gt_u32 s85, 61
	s_cbranch_scc0 .LBB0_892
	s_and_b64 vcc, exec, s[10:11]
	s_cbranch_vccz .LBB0_895
	s_barrier

; #define PG8_STAGE(bufoff, gbase, voff) do { if constexpr (VAR != 1 && VAR != 3) { _Pragma("unroll") for (int _i = 0; _i < 2; ++_i) \
;         asm volatile("s_mov_b32 m0, %2\n\ts_nop 0\n\tglobal_load_lds_dwordx4 %0, %1" :: "v"((voff)[_i]), "s"((const char*)(gbase)), "s"(ldsbase + (unsigned)((bufoff) + _i * 8192)) : "memory", "m0"); } } while (0)
; #define PG8_LDA(dst, b, h) do { if constexpr (VAR < 2) _Pragma("unroll") for (int m = 0; m < 4; ++m) _Pragma("unroll") for (int k = 0; k < 2; ++k) dst[m][k] = *(const LAS bf16x8*)(lds + PG8_SA(b, h) + aoff + m * 2048 + k * 1024); } while (0)
; #define PG8_LDB(dst, b, h) do { if constexpr (VAR < 2) _Pragma("unroll") for (int n = 0; n < 2; ++n) _Pragma("unroll") for (int k = 0; k < 2; ++k) dst[n][k] = *(const LAS bf16x8*)(lds + PG8_SB(b, h) + boff + n * 2048 + k * 1024); } while (0)
; #define PG8_WAIT_V(n) asm volatile("s_waitcnt vmcnt(" #n ")" ::: "memory")
; #define PG8_WAIT_L(n) asm volatile("s_waitcnt lgkmcnt(" #n ")" ::: "memory")
; #define PG8_BAR do { if constexpr (VAR != 3) __builtin_amdgcn_s_barrier(); } while (0)
; #define PG8_SCHED __builtin_amdgcn_sched_barrier(0)
;     ...
;         for (int t = 0; t < nt; t += 2) {
;             const bool last = (t == nt - 2);
;             const char* a1 = cA + (size_t)(t + 1) * kstep;
;             const char* a2 = last ? nA : cA + (size_t)(t + 2) * kstep; const char* b2 = last ? nB : cB + (size_t)(t + 2) * kstep;
;             const char* a3 = a2 + kstep; const char* b3 = b2 + kstep;
;             PG8_LDB(B0, 0, 0); PG8_LDB(B1, 0, 1); PG8_SCHED; PG8_LDA(At, 0, 0); PG8_STAGE(PG8_SA(1, 1), a1 + hstepA, voffA);
;             PG8_WAIT_V(8); PG8_WAIT_L(0); PG8_BAR; PG8_MMA(0, 0, At, B0); PG8_MMA(0, 1, At, B1); PG8_BAR; PG8_SCHED;
;             PG8_LDA(At, 0, 1); PG8_STAGE(PG8_SB(0, 0), b2, voffB); PG8_STAGE(PG8_SB(0, 1), b2 + hstepB, voffB); PG8_STAGE(PG8_SA(0, 0), a2, voffA);
;             PG8_WAIT_V(8); PG8_WAIT_L(0); PG8_BAR; PG8_MMA(1, 0, At, B0); PG8_MMA(1, 1, At, B1); PG8_BAR; PG8_SCHED;
.LBB0_1002:
	ds_read_b128 v[130:133], v183
	ds_read_b128 v[134:137], v183 offset:1024
	ds_read_b128 v[138:141], v183 offset:2048
	ds_read_b128 v[142:145], v183 offset:3072
	ds_read_b128 v[146:149], v184
	ds_read_b128 v[150:153], v184 offset:1024
	ds_read_b128 v[154:157], v184 offset:2048
	ds_read_b128 v[162:165], v184 offset:3072
	s_cmp_eq_u32 s86, 12
	s_cselect_b32 s78, s25, s63
	s_cselect_b32 s79, s24, s65
	s_cselect_b32 s76, s66, s84
	s_cselect_b32 s77, s67, s85
	s_add_u32 s74, s78, 0x80
	s_addc_u32 s75, s79, 0
	ds_read_b128 v[166:169], v185
	ds_read_b128 v[170:173], v185 offset:1024
	ds_read_b128 v[190:193], v185 offset:2048
	ds_read_b128 v[194:197], v185 offset:3072
	ds_read_b128 v[198:201], v185 offset:4096
	ds_read_b128 v[202:205], v185 offset:5120
	ds_read_b128 v[206:209], v185 offset:6144
	ds_read_b128 v[210:213], v185 offset:7168
	s_mov_b32 m0, s82
	s_nop 0
	global_load_lds_dwordx4 v176, s[12:13]
	s_nop 0
	s_mov_b32 m0, s83
	s_nop 0
	global_load_lds_dwordx4 v178, s[12:13]
	s_waitcnt lgkmcnt(7)
	v_mfma_f32_16x16x32_bf16 v[126:129], v[130:133], v[166:169], v[126:129]
	v_mfma_f32_16x16x32_bf16 v[122:125], v[138:141], v[166:169], v[122:125]
	s_waitcnt lgkmcnt(5)
	v_mfma_f32_16x16x32_bf16 v[110:113], v[130:133], v[190:193], v[110:113]
	v_mfma_f32_16x16x32_bf16 v[106:109], v[138:141], v[190:193], v[106:109]
	s_waitcnt vmcnt(8)
	s_waitcnt lgkmcnt(0)
	s_barrier
	s_setprio 1
	s_waitcnt lgkmcnt(3)
	v_mfma_f32_16x16x32_bf16 v[94:97], v[130:133], v[198:201], v[94:97]
	v_mfma_f32_16x16x32_bf16 v[90:93], v[138:141], v[198:201], v[90:93]
	s_waitcnt lgkmcnt(1)
	v_mfma_f32_16x16x32_bf16 v[78:81], v[130:133], v[206:209], v[78:81]
	v_mfma_f32_16x16x32_bf16 v[74:77], v[138:141], v[206:209], v[74:77]
	v_mfma_f32_16x16x32_bf16 v[126:129], v[134:137], v[170:173], v[126:129]
	v_mfma_f32_16x16x32_bf16 v[122:125], v[142:145], v[170:173], v[122:125]
	v_mfma_f32_16x16x32_bf16 v[110:113], v[134:137], v[194:197], v[110:113]
	v_mfma_f32_16x16x32_bf16 v[106:109], v[142:145], v[194:197], v[106:109]
	v_mfma_f32_16x16x32_bf16 v[94:97], v[134:137], v[202:205], v[94:97]
	v_mfma_f32_16x16x32_bf16 v[90:93], v[142:145], v[202:205], v[90:93]
	s_waitcnt lgkmcnt(0)
	v_mfma_f32_16x16x32_bf16 v[78:81], v[134:137], v[210:213], v[78:81]
	v_mfma_f32_16x16x32_bf16 v[74:77], v[142:145], v[210:213], v[74:77]
	s_setprio 0
	s_setprio 1
	v_mfma_f32_16x16x32_bf16 v[118:121], v[146:149], v[166:169], v[118:121]
	v_mfma_f32_16x16x32_bf16 v[114:117], v[154:157], v[166:169], v[114:117]
	v_mfma_f32_16x16x32_bf16 v[102:105], v[146:149], v[190:193], v[102:105]
	v_mfma_f32_16x16x32_bf16 v[98:101], v[154:157], v[190:193], v[98:101]
	v_mfma_f32_16x16x32_bf16 v[86:89], v[146:149], v[198:201], v[86:89]
	v_mfma_f32_16x16x32_bf16 v[82:85], v[154:157], v[198:201], v[82:85]
	v_mfma_f32_16x16x32_bf16 v[70:73], v[146:149], v[206:209], v[70:73]
	v_mfma_f32_16x16x32_bf16 v[66:69], v[154:157], v[206:209], v[66:69]
	v_mfma_f32_16x16x32_bf16 v[118:121], v[150:153], v[170:173], v[118:121]
	v_mfma_f32_16x16x32_bf16 v[114:117], v[162:165], v[170:173], v[114:117]
	v_mfma_f32_16x16x32_bf16 v[102:105], v[150:153], v[194:197], v[102:105]
	v_mfma_f32_16x16x32_bf16 v[98:101], v[162:165], v[194:197], v[98:101]
	v_mfma_f32_16x16x32_bf16 v[86:89], v[150:153], v[202:205], v[86:89]
	v_mfma_f32_16x16x32_bf16 v[82:85], v[162:165], v[202:205], v[82:85]
	v_mfma_f32_16x16x32_bf16 v[70:73], v[150:153], v[210:213], v[70:73]
	v_mfma_f32_16x16x32_bf16 v[66:69], v[162:165], v[210:213], v[66:69]
	s_setprio 0
	s_barrier
	ds_read_b128 v[166:169], v185 offset:16384
	ds_read_b128 v[170:173], v185 offset:17408
	ds_read_b128 v[190:193], v185 offset:18432
	ds_read_b128 v[194:197], v185 offset:19456
	ds_read_b128 v[198:201], v185 offset:20480
	ds_read_b128 v[202:205], v185 offset:21504
	ds_read_b128 v[206:209], v185 offset:22528
	ds_read_b128 v[210:213], v185 offset:23552
	s_mov_b32 m0, s17
	s_nop 0
	global_load_lds_dwordx4 v177, s[76:77]
	s_add_u32 s88, s76, 0x40000
	s_mov_b32 m0, s19
	s_nop 0
	global_load_lds_dwordx4 v179, s[76:77]
	s_addc_u32 s89, s77, 0
	s_mov_b32 m0, s23
	s_nop 0
	global_load_lds_dwordx4 v177, s[88:89]
	s_nop 0
	s_mov_b32 m0, s26
	s_nop 0
	global_load_lds_dwordx4 v179, s[88:89]
	s_nop 0
	s_mov_b32 m0, s15
	s_nop 0
	global_load_lds_dwordx4 v176, s[78:79]
	s_nop 0
	s_mov_b32 m0, s27
	s_nop 0
	global_load_lds_dwordx4 v178, s[78:79]
	s_waitcnt lgkmcnt(7)
	v_mfma_f32_16x16x32_bf16 v[62:65], v[130:133], v[166:169], v[62:65]
	v_mfma_f32_16x16x32_bf16 v[58:61], v[138:141], v[166:169], v[58:61]
	s_waitcnt lgkmcnt(5)
	v_mfma_f32_16x16x32_bf16 v[46:49], v[130:133], v[190:193], v[46:49]
	v_mfma_f32_16x16x32_bf16 v[42:45], v[138:141], v[190:193], v[42:45]
	s_waitcnt vmcnt(8)
	s_waitcnt lgkmcnt(0)
	s_barrier
; #define PG8_STAGE(bufoff, gbase, voff) do { if constexpr (VAR != 1 && VAR != 3) { _Pragma("unroll") for (int _i = 0; _i < 2; ++_i) \
;         asm volatile("s_mov_b32 m0, %2\n\ts_nop 0\n\tglobal_load_lds_dwordx4 %0, %1" :: "v"((voff)[_i]), "s"((const char*)(gbase)), "s"(ldsbase + (unsigned)((bufoff) + _i * 8192)) : "memory", "m0"); } } while (0)
; #define PG8_LDA(dst, b, h) do { if constexpr (VAR < 2) _Pragma("unroll") for (int m = 0; m < 4; ++m) _Pragma("unroll") for (int k = 0; k < 2; ++k) dst[m][k] = *(const LAS bf16x8*)(lds + PG8_SA(b, h) + aoff + m * 2048 + k * 1024); } while (0)
; #define PG8_LDB(dst, b, h) do { if constexpr (VAR < 2) _Pragma("unroll") for (int n = 0; n < 2; ++n) _Pragma("unroll") for (int k = 0; k < 2; ++k) dst[n][k] = *(const LAS bf16x8*)(lds + PG8_SB(b, h) + boff + n * 2048 + k * 1024); } while (0)
; #define PG8_WAIT_V(n) asm volatile("s_waitcnt vmcnt(" #n ")" ::: "memory")
; #define PG8_WAIT_L(n) asm volatile("s_waitcnt lgkmcnt(" #n ")" ::: "memory")
; #define PG8_BAR do { if constexpr (VAR != 3) __builtin_amdgcn_s_barrier(); } while (0)
; #define PG8_SCHED __builtin_amdgcn_sched_barrier(0)
;     ...
;             PG8_WAIT_V(8); PG8_WAIT_L(0); PG8_BAR; PG8_MMA(1, 0, At, B0); PG8_MMA(1, 1, At, B1); PG8_BAR; PG8_SCHED;
;             PG8_LDB(B0, 1, 0); PG8_LDB(B1, 1, 1); PG8_SCHED; PG8_LDA(At, 1, 0); PG8_STAGE(PG8_SA(0, 1), a2 + hstepA, voffA);
;             PG8_WAIT_V(8); PG8_WAIT_L(0); PG8_BAR; PG8_MMA(0, 0, At, B0); PG8_MMA(0, 1, At, B1); PG8_BAR; PG8_SCHED;
	s_setprio 1
	s_waitcnt lgkmcnt(3)
	v_mfma_f32_16x16x32_bf16 v[30:33], v[130:133], v[198:201], v[30:33]
	v_mfma_f32_16x16x32_bf16 v[26:29], v[138:141], v[198:201], v[26:29]
	s_waitcnt lgkmcnt(1)
	v_mfma_f32_16x16x32_bf16 v[14:17], v[130:133], v[206:209], v[14:17]
	v_mfma_f32_16x16x32_bf16 v[10:13], v[138:141], v[206:209], v[10:13]
	v_mfma_f32_16x16x32_bf16 v[62:65], v[134:137], v[170:173], v[62:65]
	v_mfma_f32_16x16x32_bf16 v[58:61], v[142:145], v[170:173], v[58:61]
	v_mfma_f32_16x16x32_bf16 v[46:49], v[134:137], v[194:197], v[46:49]
	v_mfma_f32_16x16x32_bf16 v[42:45], v[142:145], v[194:197], v[42:45]
	v_mfma_f32_16x16x32_bf16 v[30:33], v[134:137], v[202:205], v[30:33]
	v_mfma_f32_16x16x32_bf16 v[26:29], v[142:145], v[202:205], v[26:29]
	s_waitcnt lgkmcnt(0)
	v_mfma_f32_16x16x32_bf16 v[14:17], v[134:137], v[210:213], v[14:17]
	v_mfma_f32_16x16x32_bf16 v[10:13], v[142:145], v[210:213], v[10:13]
	s_setprio 0
	s_setprio 1
	v_mfma_f32_16x16x32_bf16 v[54:57], v[146:149], v[166:169], v[54:57]
	v_mfma_f32_16x16x32_bf16 v[50:53], v[154:157], v[166:169], v[50:53]
	v_mfma_f32_16x16x32_bf16 v[38:41], v[146:149], v[190:193], v[38:41]
	v_mfma_f32_16x16x32_bf16 v[34:37], v[154:157], v[190:193], v[34:37]
	v_mfma_f32_16x16x32_bf16 v[22:25], v[146:149], v[198:201], v[22:25]
	v_mfma_f32_16x16x32_bf16 v[18:21], v[154:157], v[198:201], v[18:21]
	v_mfma_f32_16x16x32_bf16 v[6:9], v[146:149], v[206:209], v[6:9]
	v_mfma_f32_16x16x32_bf16 v[2:5], v[154:157], v[206:209], v[2:5]
	v_mfma_f32_16x16x32_bf16 v[54:57], v[150:153], v[170:173], v[54:57]
	v_mfma_f32_16x16x32_bf16 v[50:53], v[162:165], v[170:173], v[50:53]
	v_mfma_f32_16x16x32_bf16 v[38:41], v[150:153], v[194:197], v[38:41]
	v_mfma_f32_16x16x32_bf16 v[34:37], v[162:165], v[194:197], v[34:37]
	v_mfma_f32_16x16x32_bf16 v[22:25], v[150:153], v[202:205], v[22:25]
	v_mfma_f32_16x16x32_bf16 v[18:21], v[162:165], v[202:205], v[18:21]
	v_mfma_f32_16x16x32_bf16 v[6:9], v[150:153], v[210:213], v[6:9]
	v_mfma_f32_16x16x32_bf16 v[2:5], v[162:165], v[210:213], v[2:5]
	s_setprio 0
	s_barrier
	ds_read_b128 v[130:133], v186
	ds_read_b128 v[134:137], v186 offset:1024
	ds_read_b128 v[138:141], v186 offset:2048
	ds_read_b128 v[142:145], v186 offset:3072
	ds_read_b128 v[146:149], v187
	ds_read_b128 v[150:153], v187 offset:1024
	ds_read_b128 v[154:157], v187 offset:2048
	ds_read_b128 v[162:165], v187 offset:3072
	ds_read_b128 v[166:169], v185 offset:32768
	ds_read_b128 v[170:173], v185 offset:33792
	ds_read_b128 v[190:193], v185 offset:34816
	ds_read_b128 v[194:197], v185 offset:35840
	ds_read_b128 v[198:201], v185 offset:36864
	ds_read_b128 v[202:205], v185 offset:37888
	ds_read_b128 v[206:209], v185 offset:38912
	ds_read_b128 v[210:213], v185 offset:39936
	s_add_u32 s78, s78, 0x40000
	s_addc_u32 s79, s79, 0
	s_mov_b32 m0, s28
	s_nop 0
	global_load_lds_dwordx4 v176, s[78:79]
	s_nop 0
	s_mov_b32 m0, s29
	s_nop 0
	global_load_lds_dwordx4 v178, s[78:79]
	s_waitcnt lgkmcnt(7)
	v_mfma_f32_16x16x32_bf16 v[126:129], v[130:133], v[166:169], v[126:129]
	v_mfma_f32_16x16x32_bf16 v[122:125], v[138:141], v[166:169], v[122:125]
	s_waitcnt lgkmcnt(5)
	v_mfma_f32_16x16x32_bf16 v[110:113], v[130:133], v[190:193], v[110:113]
	v_mfma_f32_16x16x32_bf16 v[106:109], v[138:141], v[190:193], v[106:109]
	s_waitcnt vmcnt(8)
	s_waitcnt lgkmcnt(0)
	s_barrier
	s_setprio 1
	s_waitcnt lgkmcnt(3)
	v_mfma_f32_16x16x32_bf16 v[94:97], v[130:133], v[198:201], v[94:97]
	v_mfma_f32_16x16x32_bf16 v[90:93], v[138:141], v[198:201], v[90:93]
	s_waitcnt lgkmcnt(1)
	v_mfma_f32_16x16x32_bf16 v[78:81], v[130:133], v[206:209], v[78:81]
	v_mfma_f32_16x16x32_bf16 v[74:77], v[138:141], v[206:209], v[74:77]
	v_mfma_f32_16x16x32_bf16 v[126:129], v[134:137], v[170:173], v[126:129]
	v_mfma_f32_16x16x32_bf16 v[122:125], v[142:145], v[170:173], v[122:125]
	v_mfma_f32_16x16x32_bf16 v[110:113], v[134:137], v[194:197], v[110:113]
	v_mfma_f32_16x16x32_bf16 v[106:109], v[142:145], v[194:197], v[106:109]
	v_mfma_f32_16x16x32_bf16 v[94:97], v[134:137], v[202:205], v[94:97]
	v_mfma_f32_16x16x32_bf16 v[90:93], v[142:145], v[202:205], v[90:93]
	s_waitcnt lgkmcnt(0)
	v_mfma_f32_16x16x32_bf16 v[78:81], v[134:137], v[210:213], v[78:81]
	v_mfma_f32_16x16x32_bf16 v[74:77], v[142:145], v[210:213], v[74:77]
	s_setprio 0
	s_setprio 1
	v_mfma_f32_16x16x32_bf16 v[118:121], v[146:149], v[166:169], v[118:121]
	v_mfma_f32_16x16x32_bf16 v[114:117], v[154:157], v[166:169], v[114:117]
	v_mfma_f32_16x16x32_bf16 v[102:105], v[146:149], v[190:193], v[102:105]
	v_mfma_f32_16x16x32_bf16 v[98:101], v[154:157], v[190:193], v[98:101]
	v_mfma_f32_16x16x32_bf16 v[86:89], v[146:149], v[198:201], v[86:89]
	v_mfma_f32_16x16x32_bf16 v[82:85], v[154:157], v[198:201], v[82:85]
	v_mfma_f32_16x16x32_bf16 v[70:73], v[146:149], v[206:209], v[70:73]
	v_mfma_f32_16x16x32_bf16 v[66:69], v[154:157], v[206:209], v[66:69]
	v_mfma_f32_16x16x32_bf16 v[118:121], v[150:153], v[170:173], v[118:121]
	v_mfma_f32_16x16x32_bf16 v[114:117], v[162:165], v[170:173], v[114:117]
	v_mfma_f32_16x16x32_bf16 v[102:105], v[150:153], v[194:197], v[102:105]
	v_mfma_f32_16x16x32_bf16 v[98:101], v[162:165], v[194:197], v[98:101]
	v_mfma_f32_16x16x32_bf16 v[86:89], v[150:153], v[202:205], v[86:89]
	v_mfma_f32_16x16x32_bf16 v[82:85], v[162:165], v[202:205], v[82:85]
	v_mfma_f32_16x16x32_bf16 v[70:73], v[150:153], v[210:213], v[70:73]
	v_mfma_f32_16x16x32_bf16 v[66:69], v[162:165], v[210:213], v[66:69]
	s_setprio 0
	s_barrier
; #define PG8_STAGE(bufoff, gbase, voff) do { if constexpr (VAR != 1 && VAR != 3) { _Pragma("unroll") for (int _i = 0; _i < 2; ++_i) \
;         asm volatile("s_mov_b32 m0, %2\n\ts_nop 0\n\tglobal_load_lds_dwordx4 %0, %1" :: "v"((voff)[_i]), "s"((const char*)(gbase)), "s"(ldsbase + (unsigned)((bufoff) + _i * 8192)) : "memory", "m0"); } } while (0)
; #define PG8_LDA(dst, b, h) do { if constexpr (VAR < 2) _Pragma("unroll") for (int m = 0; m < 4; ++m) _Pragma("unroll") for (int k = 0; k < 2; ++k) dst[m][k] = *(const LAS bf16x8*)(lds + PG8_SA(b, h) + aoff + m * 2048 + k * 1024); } while (0)
; #define PG8_WAIT_V(n) asm volatile("s_waitcnt vmcnt(" #n ")" ::: "memory")
; #define PG8_WAIT_L(n) asm volatile("s_waitcnt lgkmcnt(" #n ")" ::: "memory")
; #define PG8_BAR do { if constexpr (VAR != 3) __builtin_amdgcn_s_barrier(); } while (0)
; #define PG8_SCHED __builtin_amdgcn_sched_barrier(0)
;     ...
;             PG8_LDA(At, 1, 1); PG8_STAGE(PG8_SB(1, 0), b3, voffB); PG8_STAGE(PG8_SB(1, 1), b3 + hstepB, voffB); PG8_STAGE(PG8_SA(1, 0), a3, voffA);
;             PG8_WAIT_V(8); PG8_WAIT_L(0); PG8_BAR; PG8_MMA(1, 0, At, B0); PG8_MMA(1, 1, At, B1); PG8_BAR; PG8_SCHED;
;         }
;         if (wr == 0) PG8_BAR;
	ds_read_b128 v[166:169], v185 offset:49152
	ds_read_b128 v[170:173], v185 offset:50176
	ds_read_b128 v[190:193], v185 offset:51200
	ds_read_b128 v[194:197], v185 offset:52224
	ds_read_b128 v[198:201], v185 offset:53248
	ds_read_b128 v[202:205], v185 offset:54272
	ds_read_b128 v[206:209], v185 offset:55296
	ds_read_b128 v[210:213], v185 offset:56320
	s_add_u32 s78, s76, 0x80
	s_addc_u32 s79, s77, 0
	s_mov_b32 m0, s33
	s_nop 0
	global_load_lds_dwordx4 v177, s[78:79]
	s_add_u32 s76, s76, 0x40080
	s_mov_b32 m0, s35
	s_nop 0
	global_load_lds_dwordx4 v179, s[78:79]
	s_addc_u32 s77, s77, 0
	s_mov_b32 m0, s80
	s_nop 0
	global_load_lds_dwordx4 v177, s[76:77]
	s_nop 0
	s_mov_b32 m0, s81
	s_nop 0
	global_load_lds_dwordx4 v179, s[76:77]
	s_nop 0
	s_mov_b32 m0, s71
	s_nop 0
	global_load_lds_dwordx4 v176, s[74:75]
	s_nop 0
	s_mov_b32 m0, s73
	s_nop 0
	global_load_lds_dwordx4 v178, s[74:75]
	s_waitcnt lgkmcnt(7)
	v_mfma_f32_16x16x32_bf16 v[62:65], v[130:133], v[166:169], v[62:65]
	v_mfma_f32_16x16x32_bf16 v[58:61], v[138:141], v[166:169], v[58:61]
	s_waitcnt lgkmcnt(5)
	v_mfma_f32_16x16x32_bf16 v[46:49], v[130:133], v[190:193], v[46:49]
	v_mfma_f32_16x16x32_bf16 v[42:45], v[138:141], v[190:193], v[42:45]
	s_waitcnt vmcnt(8)
	s_waitcnt lgkmcnt(0)
	s_barrier
	s_setprio 1
	s_waitcnt lgkmcnt(3)
	v_mfma_f32_16x16x32_bf16 v[30:33], v[130:133], v[198:201], v[30:33]
	v_mfma_f32_16x16x32_bf16 v[26:29], v[138:141], v[198:201], v[26:29]
	s_waitcnt lgkmcnt(1)
	v_mfma_f32_16x16x32_bf16 v[14:17], v[130:133], v[206:209], v[14:17]
	v_mfma_f32_16x16x32_bf16 v[10:13], v[138:141], v[206:209], v[10:13]
	v_mfma_f32_16x16x32_bf16 v[62:65], v[134:137], v[170:173], v[62:65]
	v_mfma_f32_16x16x32_bf16 v[58:61], v[142:145], v[170:173], v[58:61]
	v_mfma_f32_16x16x32_bf16 v[46:49], v[134:137], v[194:197], v[46:49]
	v_mfma_f32_16x16x32_bf16 v[42:45], v[142:145], v[194:197], v[42:45]
	v_mfma_f32_16x16x32_bf16 v[30:33], v[134:137], v[202:205], v[30:33]
	v_mfma_f32_16x16x32_bf16 v[26:29], v[142:145], v[202:205], v[26:29]
	s_waitcnt lgkmcnt(0)
	v_mfma_f32_16x16x32_bf16 v[14:17], v[134:137], v[210:213], v[14:17]
	v_mfma_f32_16x16x32_bf16 v[10:13], v[142:145], v[210:213], v[10:13]
	s_setprio 0
	s_setprio 1
	v_mfma_f32_16x16x32_bf16 v[54:57], v[146:149], v[166:169], v[54:57]
	v_mfma_f32_16x16x32_bf16 v[50:53], v[154:157], v[166:169], v[50:53]
	v_mfma_f32_16x16x32_bf16 v[38:41], v[146:149], v[190:193], v[38:41]
	v_mfma_f32_16x16x32_bf16 v[34:37], v[154:157], v[190:193], v[34:37]
	v_mfma_f32_16x16x32_bf16 v[22:25], v[146:149], v[198:201], v[22:25]
	v_mfma_f32_16x16x32_bf16 v[18:21], v[154:157], v[198:201], v[18:21]
	v_mfma_f32_16x16x32_bf16 v[6:9], v[146:149], v[206:209], v[6:9]
	v_mfma_f32_16x16x32_bf16 v[2:5], v[154:157], v[206:209], v[2:5]
	v_mfma_f32_16x16x32_bf16 v[54:57], v[150:153], v[170:173], v[54:57]
	v_mfma_f32_16x16x32_bf16 v[50:53], v[162:165], v[170:173], v[50:53]
	v_mfma_f32_16x16x32_bf16 v[38:41], v[150:153], v[194:197], v[38:41]
	v_mfma_f32_16x16x32_bf16 v[34:37], v[162:165], v[194:197], v[34:37]
	v_mfma_f32_16x16x32_bf16 v[22:25], v[150:153], v[202:205], v[22:25]
	v_mfma_f32_16x16x32_bf16 v[18:21], v[162:165], v[202:205], v[18:21]
	v_mfma_f32_16x16x32_bf16 v[6:9], v[150:153], v[210:213], v[6:9]
	v_mfma_f32_16x16x32_bf16 v[2:5], v[162:165], v[210:213], v[2:5]
	s_setprio 0
	s_barrier
	s_add_i32 s86, s86, 2
	s_add_u32 s63, s63, 0x100
	s_addc_u32 s65, s65, 0
	s_add_u32 s84, s84, 0x100
	s_addc_u32 s85, s85, 0
	s_add_u32 s12, s12, 0x100
	s_addc_u32 s13, s13, 0
	s_cmp_gt_u32 s86, 13
	s_cbranch_scc0 .LBB0_1002
	s_and_b64 vcc, exec, s[60:61]
	s_cbranch_vccz .LBB0_1005
	s_barrier

; #define PG8_STAGE(bufoff, gbase, voff) do { if constexpr (VAR != 1 && VAR != 3) { _Pragma("unroll") for (int _i = 0; _i < 2; ++_i) \
;         asm volatile("s_mov_b32 m0, %2\n\ts_nop 0\n\tglobal_load_lds_dwordx4 %0, %1" :: "v"((voff)[_i]), "s"((const char*)(gbase)), "s"(ldsbase + (unsigned)((bufoff) + _i * 8192)) : "memory", "m0"); } } while (0)
; #define PG8_LDA(dst, b, h) do { if constexpr (VAR < 2) _Pragma("unroll") for (int m = 0; m < 4; ++m) _Pragma("unroll") for (int k = 0; k < 2; ++k) dst[m][k] = *(const LAS bf16x8*)(lds + PG8_SA(b, h) + aoff + m * 2048 + k * 1024); } while (0)
; #define PG8_LDB(dst, b, h) do { if constexpr (VAR < 2) _Pragma("unroll") for (int n = 0; n < 2; ++n) _Pragma("unroll") for (int k = 0; k < 2; ++k) dst[n][k] = *(const LAS bf16x8*)(lds + PG8_SB(b, h) + boff + n * 2048 + k * 1024); } while (0)
; #define PG8_WAIT_V(n) asm volatile("s_waitcnt vmcnt(" #n ")" ::: "memory")
; #define PG8_WAIT_L(n) asm volatile("s_waitcnt lgkmcnt(" #n ")" ::: "memory")
; #define PG8_BAR do { if constexpr (VAR != 3) __builtin_amdgcn_s_barrier(); } while (0)
; #define PG8_SCHED __builtin_amdgcn_sched_barrier(0)
;     ...
;         for (int t = 0; t < nt; t += 2) {
;             const bool last = (t == nt - 2);
;             const char* a1 = cA + (size_t)(t + 1) * kstep;
;             const char* a2 = last ? nA : cA + (size_t)(t + 2) * kstep; const char* b2 = last ? nB : cB + (size_t)(t + 2) * kstep;
;             const char* a3 = a2 + kstep; const char* b3 = b2 + kstep;
;             PG8_LDB(B0, 0, 0); PG8_LDB(B1, 0, 1); PG8_SCHED; PG8_LDA(At, 0, 0); PG8_STAGE(PG8_SA(1, 1), a1 + hstepA, voffA);
;             PG8_WAIT_V(8); PG8_WAIT_L(0); PG8_BAR; PG8_MMA(0, 0, At, B0); PG8_MMA(0, 1, At, B1); PG8_BAR; PG8_SCHED;
;             PG8_LDA(At, 0, 1); PG8_STAGE(PG8_SB(0, 0), b2, voffB); PG8_STAGE(PG8_SB(0, 1), b2 + hstepB, voffB); PG8_STAGE(PG8_SA(0, 0), a2, voffA);
;             PG8_WAIT_V(8); PG8_WAIT_L(0); PG8_BAR; PG8_MMA(1, 0, At, B0); PG8_MMA(1, 1, At, B1); PG8_BAR; PG8_SCHED;
.LBB0_1191:
	ds_read_b128 v[2:5], v231
	ds_read_b128 v[6:9], v231 offset:1024
	ds_read_b128 v[10:13], v231 offset:2048
	ds_read_b128 v[14:17], v231 offset:3072
	ds_read_b128 v[18:21], v232
	ds_read_b128 v[26:29], v232 offset:1024
	ds_read_b128 v[154:157], v232 offset:2048
	ds_read_b128 v[158:161], v232 offset:3072
	s_cmp_eq_u32 s71, 28
	s_cselect_b32 s82, s72, s25
	s_cselect_b32 s83, s73, s26
	s_cselect_b32 s80, s24, s27
	s_cselect_b32 s81, s11, s69
	s_add_u32 s78, s82, 0x80
	s_addc_u32 s79, s83, 0
	ds_read_b128 v[162:165], v233
	ds_read_b128 v[166:169], v233 offset:1024
	ds_read_b128 v[178:181], v233 offset:2048
	ds_read_b128 v[182:185], v233 offset:3072
	ds_read_b128 v[186:189], v233 offset:4096
	ds_read_b128 v[190:193], v233 offset:5120
	ds_read_b128 v[194:197], v233 offset:6144
	ds_read_b128 v[198:201], v233 offset:7168
	s_mov_b32 m0, s90
	s_nop 0
	global_load_lds_dwordx4 v208, s[0:1]
	s_nop 0
	s_mov_b32 m0, s91
	s_nop 0
	global_load_lds_dwordx4 v210, s[0:1]
	s_waitcnt lgkmcnt(7)
	v_mfma_i32_16x16x64_i8 v[150:153], v[2:5], v[162:165], v[150:153]
	v_mfma_i32_16x16x64_i8 v[142:145], v[10:13], v[162:165], v[142:145]
	s_waitcnt lgkmcnt(5)
	v_mfma_i32_16x16x64_i8 v[126:129], v[2:5], v[178:181], v[126:129]
	v_mfma_i32_16x16x64_i8 v[122:125], v[10:13], v[178:181], v[122:125]
	s_waitcnt vmcnt(8)
	s_waitcnt lgkmcnt(0)
	s_barrier
	s_setprio 1
	s_waitcnt lgkmcnt(3)
	v_mfma_i32_16x16x64_i8 v[114:117], v[2:5], v[186:189], v[114:117]
	v_mfma_i32_16x16x64_i8 v[106:109], v[10:13], v[186:189], v[106:109]
	s_waitcnt lgkmcnt(1)
	v_mfma_i32_16x16x64_i8 v[146:149], v[2:5], v[194:197], v[146:149]
	v_mfma_i32_16x16x64_i8 v[138:141], v[10:13], v[194:197], v[138:141]
	v_mfma_i32_16x16x64_i8 v[150:153], v[6:9], v[166:169], v[150:153]
	v_mfma_i32_16x16x64_i8 v[142:145], v[14:17], v[166:169], v[142:145]
	v_mfma_i32_16x16x64_i8 v[126:129], v[6:9], v[182:185], v[126:129]
	v_mfma_i32_16x16x64_i8 v[122:125], v[14:17], v[182:185], v[122:125]
	v_mfma_i32_16x16x64_i8 v[114:117], v[6:9], v[190:193], v[114:117]
	v_mfma_i32_16x16x64_i8 v[106:109], v[14:17], v[190:193], v[106:109]
	s_waitcnt lgkmcnt(0)
	v_mfma_i32_16x16x64_i8 v[146:149], v[6:9], v[198:201], v[146:149]
	v_mfma_i32_16x16x64_i8 v[138:141], v[14:17], v[198:201], v[138:141]
	s_setprio 0
	s_setprio 1
	v_mfma_i32_16x16x64_i8 v[134:137], v[18:21], v[162:165], v[134:137]
	v_mfma_i32_16x16x64_i8 v[130:133], v[154:157], v[162:165], v[130:133]
	v_mfma_i32_16x16x64_i8 v[118:121], v[18:21], v[178:181], v[118:121]
	v_mfma_i32_16x16x64_i8 v[110:113], v[154:157], v[178:181], v[110:113]
	v_mfma_i32_16x16x64_i8 v[102:105], v[18:21], v[186:189], v[102:105]
	v_mfma_i32_16x16x64_i8 v[98:101], v[154:157], v[186:189], v[98:101]
	v_mfma_i32_16x16x64_i8 v[94:97], v[18:21], v[194:197], v[94:97]
	v_mfma_i32_16x16x64_i8 v[90:93], v[154:157], v[194:197], v[90:93]
	v_mfma_i32_16x16x64_i8 v[134:137], v[26:29], v[166:169], v[134:137]
	v_mfma_i32_16x16x64_i8 v[130:133], v[158:161], v[166:169], v[130:133]
	v_mfma_i32_16x16x64_i8 v[118:121], v[26:29], v[182:185], v[118:121]
	v_mfma_i32_16x16x64_i8 v[110:113], v[158:161], v[182:185], v[110:113]
	v_mfma_i32_16x16x64_i8 v[102:105], v[26:29], v[190:193], v[102:105]
	v_mfma_i32_16x16x64_i8 v[98:101], v[158:161], v[190:193], v[98:101]
	v_mfma_i32_16x16x64_i8 v[94:97], v[26:29], v[198:201], v[94:97]
	v_mfma_i32_16x16x64_i8 v[90:93], v[158:161], v[198:201], v[90:93]
	s_setprio 0
	s_barrier
	ds_read_b128 v[162:165], v233 offset:16384
	ds_read_b128 v[166:169], v233 offset:17408
	ds_read_b128 v[178:181], v233 offset:18432
	ds_read_b128 v[182:185], v233 offset:19456
	ds_read_b128 v[186:189], v233 offset:20480
	ds_read_b128 v[190:193], v233 offset:21504
	ds_read_b128 v[194:197], v233 offset:22528
	ds_read_b128 v[198:201], v233 offset:23552
	s_mov_b32 m0, s21
	s_nop 0
	global_load_lds_dwordx4 v209, s[80:81]
	s_add_u32 s96, s80, 0x80000
	s_mov_b32 m0, s23
	s_nop 0
	global_load_lds_dwordx4 v211, s[80:81]
	s_addc_u32 s97, s81, 0
	s_mov_b32 m0, s28
	s_nop 0
	global_load_lds_dwordx4 v209, s[96:97]
	s_nop 0
	s_mov_b32 m0, s29
	s_nop 0
	global_load_lds_dwordx4 v211, s[96:97]
	s_nop 0
	s_mov_b32 m0, s15
	s_nop 0
	global_load_lds_dwordx4 v208, s[82:83]
	s_nop 0
	s_mov_b32 m0, s30
	s_nop 0
	global_load_lds_dwordx4 v210, s[82:83]
	s_waitcnt lgkmcnt(7)
	v_mfma_i32_16x16x64_i8 v[86:89], v[2:5], v[162:165], v[86:89]
	v_mfma_i32_16x16x64_i8 v[82:85], v[10:13], v[162:165], v[82:85]
	s_waitcnt lgkmcnt(5)
	v_mfma_i32_16x16x64_i8 v[74:77], v[2:5], v[178:181], v[74:77]
	v_mfma_i32_16x16x64_i8 v[66:69], v[10:13], v[178:181], v[66:69]
	s_waitcnt vmcnt(8)
	s_waitcnt lgkmcnt(0)
	s_barrier
	s_setprio 1
	s_waitcnt lgkmcnt(3)
	v_mfma_i32_16x16x64_i8 v[58:61], v[2:5], v[186:189], v[58:61]
	v_mfma_i32_16x16x64_i8 v[50:53], v[10:13], v[186:189], v[50:53]
	s_waitcnt lgkmcnt(1)
	v_mfma_i32_16x16x64_i8 v[2:5], v[2:5], v[194:197], v[30:33]
	v_mfma_i32_16x16x64_i8 v[86:89], v[6:9], v[166:169], v[86:89]
	v_mfma_i32_16x16x64_i8 v[82:85], v[14:17], v[166:169], v[82:85]
	v_mfma_i32_16x16x64_i8 v[74:77], v[6:9], v[182:185], v[74:77]
	v_mfma_i32_16x16x64_i8 v[66:69], v[14:17], v[182:185], v[66:69]
	v_mfma_i32_16x16x64_i8 v[58:61], v[6:9], v[190:193], v[58:61]
	v_mfma_i32_16x16x64_i8 v[50:53], v[14:17], v[190:193], v[50:53]
	s_waitcnt lgkmcnt(0)
	v_mfma_i32_16x16x64_i8 v[2:5], v[6:9], v[198:201], v[2:5]
	v_mfma_i32_16x16x64_i8 v[6:9], v[10:13], v[194:197], v[22:25]
	v_mfma_i32_16x16x64_i8 v[6:9], v[14:17], v[198:201], v[6:9]
	s_setprio 0
	s_setprio 1
	v_mfma_i32_16x16x64_i8 v[22:25], v[18:21], v[178:181], v[62:65]
	v_mfma_i32_16x16x64_i8 v[62:65], v[26:29], v[182:185], v[22:25]
	v_mfma_i32_16x16x64_i8 v[22:25], v[154:157], v[178:181], v[54:57]
	v_mfma_i32_16x16x64_i8 v[54:57], v[158:161], v[182:185], v[22:25]
	v_mfma_i32_16x16x64_i8 v[22:25], v[18:21], v[186:189], v[46:49]
	v_mfma_i32_16x16x64_i8 v[46:49], v[26:29], v[190:193], v[22:25]
	v_mfma_i32_16x16x64_i8 v[22:25], v[154:157], v[186:189], v[42:45]
	v_mfma_i32_16x16x64_i8 v[10:13], v[18:21], v[162:165], v[78:81]
	v_mfma_i32_16x16x64_i8 v[14:17], v[154:157], v[162:165], v[70:73]
	v_mfma_i32_16x16x64_i8 v[42:45], v[158:161], v[190:193], v[22:25]
	v_mfma_i32_16x16x64_i8 v[18:21], v[18:21], v[194:197], v[38:41]
	v_mfma_i32_16x16x64_i8 v[22:25], v[154:157], v[194:197], v[34:37]
	v_mfma_i32_16x16x64_i8 v[10:13], v[26:29], v[166:169], v[10:13]
	v_mfma_i32_16x16x64_i8 v[14:17], v[158:161], v[166:169], v[14:17]
	v_mfma_i32_16x16x64_i8 v[18:21], v[26:29], v[198:201], v[18:21]
	v_mfma_i32_16x16x64_i8 v[26:29], v[158:161], v[198:201], v[22:25]
	s_setprio 0
	s_barrier
; #define PG8_STAGE(bufoff, gbase, voff) do { if constexpr (VAR != 1 && VAR != 3) { _Pragma("unroll") for (int _i = 0; _i < 2; ++_i) \
;         asm volatile("s_mov_b32 m0, %2\n\ts_nop 0\n\tglobal_load_lds_dwordx4 %0, %1" :: "v"((voff)[_i]), "s"((const char*)(gbase)), "s"(ldsbase + (unsigned)((bufoff) + _i * 8192)) : "memory", "m0"); } } while (0)
; #define PG8_LDA(dst, b, h) do { if constexpr (VAR < 2) _Pragma("unroll") for (int m = 0; m < 4; ++m) _Pragma("unroll") for (int k = 0; k < 2; ++k) dst[m][k] = *(const LAS bf16x8*)(lds + PG8_SA(b, h) + aoff + m * 2048 + k * 1024); } while (0)
; #define PG8_LDB(dst, b, h) do { if constexpr (VAR < 2) _Pragma("unroll") for (int n = 0; n < 2; ++n) _Pragma("unroll") for (int k = 0; k < 2; ++k) dst[n][k] = *(const LAS bf16x8*)(lds + PG8_SB(b, h) + boff + n * 2048 + k * 1024); } while (0)
; #define PG8_WAIT_V(n) asm volatile("s_waitcnt vmcnt(" #n ")" ::: "memory")
; #define PG8_WAIT_L(n) asm volatile("s_waitcnt lgkmcnt(" #n ")" ::: "memory")
; #define PG8_BAR do { if constexpr (VAR != 3) __builtin_amdgcn_s_barrier(); } while (0)
; #define PG8_SCHED __builtin_amdgcn_sched_barrier(0)
;     ...
;             PG8_LDB(B0, 1, 0); PG8_LDB(B1, 1, 1); PG8_SCHED; PG8_LDA(At, 1, 0); PG8_STAGE(PG8_SA(0, 1), a2 + hstepA, voffA);
;             PG8_WAIT_V(8); PG8_WAIT_L(0); PG8_BAR; PG8_MMA(0, 0, At, B0); PG8_MMA(0, 1, At, B1); PG8_BAR; PG8_SCHED;
;             PG8_LDA(At, 1, 1); PG8_STAGE(PG8_SB(1, 0), b3, voffB); PG8_STAGE(PG8_SB(1, 1), b3 + hstepB, voffB); PG8_STAGE(PG8_SA(1, 0), a3, voffA);
;             PG8_WAIT_V(8); PG8_WAIT_L(0); PG8_BAR; PG8_MMA(1, 0, At, B0); PG8_MMA(1, 1, At, B1); PG8_BAR; PG8_SCHED;
;         }
;         if (wr == 0) PG8_BAR;
	s_nop 1
	ds_read_b128 v[22:25], v234
	ds_read_b128 v[30:33], v234 offset:1024
	ds_read_b128 v[34:37], v234 offset:2048
	ds_read_b128 v[38:41], v234 offset:3072
	ds_read_b128 v[154:157], v235
	ds_read_b128 v[158:161], v235 offset:1024
	ds_read_b128 v[162:165], v235 offset:2048
	ds_read_b128 v[166:169], v235 offset:3072
	ds_read_b128 v[70:73], v233 offset:32768
	ds_read_b128 v[78:81], v233 offset:33792
	ds_read_b128 v[178:181], v233 offset:34816
	ds_read_b128 v[182:185], v233 offset:35840
	ds_read_b128 v[186:189], v233 offset:36864
	ds_read_b128 v[190:193], v233 offset:37888
	ds_read_b128 v[194:197], v233 offset:38912
	ds_read_b128 v[198:201], v233 offset:39936
	s_add_u32 s82, s82, 0x80000
	s_addc_u32 s83, s83, 0
	s_mov_b32 m0, s31
	s_nop 0
	global_load_lds_dwordx4 v208, s[82:83]
	s_nop 0
	s_mov_b32 m0, s33
	s_nop 0
	global_load_lds_dwordx4 v210, s[82:83]
	s_waitcnt lgkmcnt(7)
	v_mfma_i32_16x16x64_i8 v[150:153], v[22:25], v[70:73], v[150:153]
	v_mfma_i32_16x16x64_i8 v[142:145], v[34:37], v[70:73], v[142:145]
	s_waitcnt lgkmcnt(5)
	v_mfma_i32_16x16x64_i8 v[126:129], v[22:25], v[178:181], v[126:129]
	v_mfma_i32_16x16x64_i8 v[122:125], v[34:37], v[178:181], v[122:125]
	s_waitcnt vmcnt(8)
	s_waitcnt lgkmcnt(0)
	s_barrier
	s_setprio 1
	s_waitcnt lgkmcnt(3)
	v_mfma_i32_16x16x64_i8 v[114:117], v[22:25], v[186:189], v[114:117]
	v_mfma_i32_16x16x64_i8 v[106:109], v[34:37], v[186:189], v[106:109]
	s_waitcnt lgkmcnt(1)
	v_mfma_i32_16x16x64_i8 v[146:149], v[22:25], v[194:197], v[146:149]
	v_mfma_i32_16x16x64_i8 v[138:141], v[34:37], v[194:197], v[138:141]
	v_mfma_i32_16x16x64_i8 v[150:153], v[30:33], v[78:81], v[150:153]
	v_mfma_i32_16x16x64_i8 v[142:145], v[38:41], v[78:81], v[142:145]
	v_mfma_i32_16x16x64_i8 v[126:129], v[30:33], v[182:185], v[126:129]
	v_mfma_i32_16x16x64_i8 v[122:125], v[38:41], v[182:185], v[122:125]
	v_mfma_i32_16x16x64_i8 v[114:117], v[30:33], v[190:193], v[114:117]
	v_mfma_i32_16x16x64_i8 v[106:109], v[38:41], v[190:193], v[106:109]
	s_waitcnt lgkmcnt(0)
	v_mfma_i32_16x16x64_i8 v[146:149], v[30:33], v[198:201], v[146:149]
	v_mfma_i32_16x16x64_i8 v[138:141], v[38:41], v[198:201], v[138:141]
	s_setprio 0
	s_setprio 1
	v_mfma_i32_16x16x64_i8 v[134:137], v[154:157], v[70:73], v[134:137]
	v_mfma_i32_16x16x64_i8 v[70:73], v[162:165], v[70:73], v[130:133]
	v_mfma_i32_16x16x64_i8 v[130:133], v[166:169], v[78:81], v[70:73]
	v_mfma_i32_16x16x64_i8 v[70:73], v[154:157], v[178:181], v[118:121]
	v_mfma_i32_16x16x64_i8 v[118:121], v[158:161], v[182:185], v[70:73]
	v_mfma_i32_16x16x64_i8 v[70:73], v[162:165], v[178:181], v[110:113]
	v_mfma_i32_16x16x64_i8 v[110:113], v[166:169], v[182:185], v[70:73]
	v_mfma_i32_16x16x64_i8 v[70:73], v[154:157], v[186:189], v[102:105]
	v_mfma_i32_16x16x64_i8 v[102:105], v[158:161], v[190:193], v[70:73]
	v_mfma_i32_16x16x64_i8 v[70:73], v[162:165], v[186:189], v[98:101]
	v_mfma_i32_16x16x64_i8 v[98:101], v[166:169], v[190:193], v[70:73]
	v_mfma_i32_16x16x64_i8 v[70:73], v[154:157], v[194:197], v[94:97]
	v_mfma_i32_16x16x64_i8 v[94:97], v[158:161], v[198:201], v[70:73]
	v_mfma_i32_16x16x64_i8 v[70:73], v[162:165], v[194:197], v[90:93]
	v_mfma_i32_16x16x64_i8 v[134:137], v[158:161], v[78:81], v[134:137]
	v_mfma_i32_16x16x64_i8 v[90:93], v[166:169], v[198:201], v[70:73]
	s_setprio 0
	s_barrier
	s_nop 3
	ds_read_b128 v[70:73], v233 offset:49152
	ds_read_b128 v[178:181], v233 offset:50176
	ds_read_b128 v[182:185], v233 offset:51200
	ds_read_b128 v[186:189], v233 offset:52224
	ds_read_b128 v[190:193], v233 offset:53248
	ds_read_b128 v[194:197], v233 offset:54272
	ds_read_b128 v[198:201], v233 offset:55296
	ds_read_b128 v[202:205], v233 offset:56320
	s_add_u32 s82, s80, 0x80
	s_addc_u32 s83, s81, 0
	s_mov_b32 m0, s84
	s_nop 0
	global_load_lds_dwordx4 v209, s[82:83]
	s_add_u32 s80, s80, 0x80080
	s_mov_b32 m0, s85
	s_nop 0
	global_load_lds_dwordx4 v211, s[82:83]
	s_addc_u32 s81, s81, 0
	s_mov_b32 m0, s88
	s_nop 0
	global_load_lds_dwordx4 v209, s[80:81]
	s_nop 0
	s_mov_b32 m0, s89
	s_nop 0
	global_load_lds_dwordx4 v211, s[80:81]
	s_nop 0
	s_mov_b32 m0, s86
	s_nop 0
	global_load_lds_dwordx4 v208, s[78:79]
	s_nop 0
	s_mov_b32 m0, s87
	s_nop 0
	global_load_lds_dwordx4 v210, s[78:79]
	s_waitcnt lgkmcnt(7)
	v_mfma_i32_16x16x64_i8 v[78:81], v[22:25], v[70:73], v[86:89]
	s_waitcnt lgkmcnt(5)
	v_mfma_i32_16x16x64_i8 v[74:77], v[22:25], v[182:185], v[74:77]
	s_waitcnt lgkmcnt(3)
	v_mfma_i32_16x16x64_i8 v[58:61], v[22:25], v[190:193], v[58:61]
	s_waitcnt lgkmcnt(1)
	v_mfma_i32_16x16x64_i8 v[2:5], v[22:25], v[198:201], v[2:5]
	s_waitcnt vmcnt(8)
	s_waitcnt lgkmcnt(0)
	s_barrier
	s_setprio 1
	v_mfma_i32_16x16x64_i8 v[86:89], v[30:33], v[178:181], v[78:81]
	v_mfma_i32_16x16x64_i8 v[78:81], v[34:37], v[70:73], v[82:85]
	v_mfma_i32_16x16x64_i8 v[74:77], v[30:33], v[186:189], v[74:77]
	v_mfma_i32_16x16x64_i8 v[66:69], v[34:37], v[182:185], v[66:69]
	v_mfma_i32_16x16x64_i8 v[58:61], v[30:33], v[194:197], v[58:61]
	v_mfma_i32_16x16x64_i8 v[50:53], v[34:37], v[190:193], v[50:53]
	s_waitcnt lgkmcnt(0)
	v_mfma_i32_16x16x64_i8 v[30:33], v[30:33], v[202:205], v[2:5]
	v_mfma_i32_16x16x64_i8 v[2:5], v[34:37], v[198:201], v[6:9]
	v_mfma_i32_16x16x64_i8 v[82:85], v[38:41], v[178:181], v[78:81]
	v_mfma_i32_16x16x64_i8 v[66:69], v[38:41], v[186:189], v[66:69]
	v_mfma_i32_16x16x64_i8 v[50:53], v[38:41], v[194:197], v[50:53]
	v_mfma_i32_16x16x64_i8 v[22:25], v[38:41], v[202:205], v[2:5]
	s_setprio 0
	s_setprio 1
	v_mfma_i32_16x16x64_i8 v[2:5], v[154:157], v[70:73], v[10:13]
	v_mfma_i32_16x16x64_i8 v[78:81], v[158:161], v[178:181], v[2:5]
	v_mfma_i32_16x16x64_i8 v[2:5], v[162:165], v[70:73], v[14:17]
	v_mfma_i32_16x16x64_i8 v[70:73], v[166:169], v[178:181], v[2:5]
	v_mfma_i32_16x16x64_i8 v[2:5], v[154:157], v[182:185], v[62:65]
	v_mfma_i32_16x16x64_i8 v[62:65], v[158:161], v[186:189], v[2:5]
	v_mfma_i32_16x16x64_i8 v[2:5], v[162:165], v[182:185], v[54:57]
	v_mfma_i32_16x16x64_i8 v[54:57], v[166:169], v[186:189], v[2:5]
	v_mfma_i32_16x16x64_i8 v[2:5], v[154:157], v[190:193], v[46:49]
	v_mfma_i32_16x16x64_i8 v[46:49], v[158:161], v[194:197], v[2:5]
	v_mfma_i32_16x16x64_i8 v[2:5], v[162:165], v[190:193], v[42:45]
	v_mfma_i32_16x16x64_i8 v[42:45], v[166:169], v[194:197], v[2:5]
	v_mfma_i32_16x16x64_i8 v[2:5], v[154:157], v[198:201], v[18:21]
	v_mfma_i32_16x16x64_i8 v[38:41], v[158:161], v[202:205], v[2:5]
	v_mfma_i32_16x16x64_i8 v[2:5], v[162:165], v[198:201], v[26:29]
	v_mfma_i32_16x16x64_i8 v[34:37], v[166:169], v[202:205], v[2:5]
	s_setprio 0
	s_barrier
	s_add_i32 s71, s71, 2
	s_add_u32 s25, s25, 0x100
	s_addc_u32 s26, s26, 0
	s_add_u32 s27, s27, 0x100
	s_addc_u32 s69, s69, 0
	s_add_u32 s0, s0, 0x100
	s_addc_u32 s1, s1, 0
	s_cmp_gt_u32 s71, 29
	s_cbranch_scc0 .LBB0_1191
	s_and_b64 vcc, exec, s[64:65]
	s_cbranch_vccz .LBB0_1194
	s_barrier

; #define PG8_STAGE(bufoff, gbase, voff) do { if constexpr (VAR != 1 && VAR != 3) { _Pragma("unroll") for (int _i = 0; _i < 2; ++_i) \
;         asm volatile("s_mov_b32 m0, %2\n\ts_nop 0\n\tglobal_load_lds_dwordx4 %0, %1" :: "v"((voff)[_i]), "s"((const char*)(gbase)), "s"(ldsbase + (unsigned)((bufoff) + _i * 8192)) : "memory", "m0"); } } while (0)
; #define PG8_LDA(dst, b, h) do { if constexpr (VAR < 2) _Pragma("unroll") for (int m = 0; m < 4; ++m) _Pragma("unroll") for (int k = 0; k < 2; ++k) dst[m][k] = *(const LAS bf16x8*)(lds + PG8_SA(b, h) + aoff + m * 2048 + k * 1024); } while (0)
; #define PG8_LDB(dst, b, h) do { if constexpr (VAR < 2) _Pragma("unroll") for (int n = 0; n < 2; ++n) _Pragma("unroll") for (int k = 0; k < 2; ++k) dst[n][k] = *(const LAS bf16x8*)(lds + PG8_SB(b, h) + boff + n * 2048 + k * 1024); } while (0)
; #define PG8_WAIT_V(n) asm volatile("s_waitcnt vmcnt(" #n ")" ::: "memory")
; #define PG8_WAIT_L(n) asm volatile("s_waitcnt lgkmcnt(" #n ")" ::: "memory")
; #define PG8_BAR do { if constexpr (VAR != 3) __builtin_amdgcn_s_barrier(); } while (0)
; #define PG8_SCHED __builtin_amdgcn_sched_barrier(0)
;     ...
;             PG8_LDB(B0, 0, 0); PG8_LDB(B1, 0, 1); PG8_SCHED; PG8_LDA(At, 0, 0); PG8_STAGE(PG8_SA(1, 1), a1 + hstepA, voffA);
;             PG8_WAIT_V(8); PG8_WAIT_L(0); PG8_BAR; PG8_MMA(0, 0, At, B0); PG8_MMA(0, 1, At, B1); PG8_BAR; PG8_SCHED;
;             PG8_LDA(At, 0, 1); PG8_STAGE(PG8_SB(0, 0), b2, voffB); PG8_STAGE(PG8_SB(0, 1), b2 + hstepB, voffB); PG8_STAGE(PG8_SA(0, 0), a2, voffA);
;             PG8_WAIT_V(8); PG8_WAIT_L(0); PG8_BAR; PG8_MMA(1, 0, At, B0); PG8_MMA(1, 1, At, B1); PG8_BAR; PG8_SCHED;
.LBB0_1361:
	ds_read_b128 v[130:133], v160
	ds_read_b128 v[134:137], v160 offset:1024
	ds_read_b128 v[142:145], v160 offset:2048
	ds_read_b128 v[146:149], v160 offset:3072
	ds_read_b128 v[150:153], v161
	ds_read_b128 v[166:169], v161 offset:1024
	ds_read_b128 v[170:173], v161 offset:2048
	ds_read_b128 v[174:177], v161 offset:3072
	s_cmpk_eq_i32 s78, 0xa8
	s_cselect_b32 s64, s12, s74
	s_cselect_b32 s65, s13, s75
	s_cselect_b32 s62, s56, s76
	s_cselect_b32 s63, s57, s77
	s_add_u32 s60, s64, 0x80
	s_addc_u32 s61, s65, 0
	ds_read_b128 v[178:181], v162
	ds_read_b128 v[182:185], v162 offset:1024
	ds_read_b128 v[186:189], v162 offset:2048
	ds_read_b128 v[190:193], v162 offset:3072
	ds_read_b128 v[194:197], v162 offset:4096
	ds_read_b128 v[198:201], v162 offset:5120
	ds_read_b128 v[202:205], v162 offset:6144
	ds_read_b128 v[206:209], v162 offset:7168
	s_mov_b32 m0, s69
	s_nop 0
	global_load_lds_dwordx4 v1, s[58:59]
	s_nop 0
	s_mov_b32 m0, s70
	s_nop 0
	global_load_lds_dwordx4 v155, s[58:59]
	s_waitcnt lgkmcnt(7)
	v_mfma_f32_16x16x32_bf16 v[126:129], v[130:133], v[178:181], v[126:129]
	v_mfma_f32_16x16x32_bf16 v[122:125], v[142:145], v[178:181], v[122:125]
	s_waitcnt lgkmcnt(5)
	v_mfma_f32_16x16x32_bf16 v[110:113], v[130:133], v[186:189], v[110:113]
	v_mfma_f32_16x16x32_bf16 v[106:109], v[142:145], v[186:189], v[106:109]
	s_waitcnt vmcnt(8)
	s_waitcnt lgkmcnt(0)
	s_barrier
	s_setprio 1
	s_waitcnt lgkmcnt(3)
	v_mfma_f32_16x16x32_bf16 v[94:97], v[130:133], v[194:197], v[94:97]
	v_mfma_f32_16x16x32_bf16 v[90:93], v[142:145], v[194:197], v[90:93]
	s_waitcnt lgkmcnt(1)
	v_mfma_f32_16x16x32_bf16 v[78:81], v[130:133], v[202:205], v[78:81]
	v_mfma_f32_16x16x32_bf16 v[74:77], v[142:145], v[202:205], v[74:77]
	v_mfma_f32_16x16x32_bf16 v[126:129], v[134:137], v[182:185], v[126:129]
	v_mfma_f32_16x16x32_bf16 v[122:125], v[146:149], v[182:185], v[122:125]
	v_mfma_f32_16x16x32_bf16 v[110:113], v[134:137], v[190:193], v[110:113]
	v_mfma_f32_16x16x32_bf16 v[106:109], v[146:149], v[190:193], v[106:109]
	v_mfma_f32_16x16x32_bf16 v[94:97], v[134:137], v[198:201], v[94:97]
	v_mfma_f32_16x16x32_bf16 v[90:93], v[146:149], v[198:201], v[90:93]
	s_waitcnt lgkmcnt(0)
	v_mfma_f32_16x16x32_bf16 v[78:81], v[134:137], v[206:209], v[78:81]
	v_mfma_f32_16x16x32_bf16 v[74:77], v[146:149], v[206:209], v[74:77]
	s_setprio 0
	s_setprio 1
	v_mfma_f32_16x16x32_bf16 v[118:121], v[150:153], v[178:181], v[118:121]
	v_mfma_f32_16x16x32_bf16 v[114:117], v[170:173], v[178:181], v[114:117]
	v_mfma_f32_16x16x32_bf16 v[102:105], v[150:153], v[186:189], v[102:105]
	v_mfma_f32_16x16x32_bf16 v[98:101], v[170:173], v[186:189], v[98:101]
	v_mfma_f32_16x16x32_bf16 v[86:89], v[150:153], v[194:197], v[86:89]
	v_mfma_f32_16x16x32_bf16 v[82:85], v[170:173], v[194:197], v[82:85]
	v_mfma_f32_16x16x32_bf16 v[70:73], v[150:153], v[202:205], v[70:73]
	v_mfma_f32_16x16x32_bf16 v[66:69], v[170:173], v[202:205], v[66:69]
	v_mfma_f32_16x16x32_bf16 v[118:121], v[166:169], v[182:185], v[118:121]
	v_mfma_f32_16x16x32_bf16 v[114:117], v[174:177], v[182:185], v[114:117]
	v_mfma_f32_16x16x32_bf16 v[102:105], v[166:169], v[190:193], v[102:105]
	v_mfma_f32_16x16x32_bf16 v[98:101], v[174:177], v[190:193], v[98:101]
	v_mfma_f32_16x16x32_bf16 v[86:89], v[166:169], v[198:201], v[86:89]
	v_mfma_f32_16x16x32_bf16 v[82:85], v[174:177], v[198:201], v[82:85]
	v_mfma_f32_16x16x32_bf16 v[70:73], v[166:169], v[206:209], v[70:73]
	v_mfma_f32_16x16x32_bf16 v[66:69], v[174:177], v[206:209], v[66:69]
	s_setprio 0
	s_barrier
	ds_read_b128 v[178:181], v162 offset:16384
	ds_read_b128 v[182:185], v162 offset:17408
	ds_read_b128 v[186:189], v162 offset:18432
	ds_read_b128 v[190:193], v162 offset:19456
	ds_read_b128 v[194:197], v162 offset:20480
	ds_read_b128 v[198:201], v162 offset:21504
	ds_read_b128 v[202:205], v162 offset:22528
	ds_read_b128 v[206:209], v162 offset:23552
	s_mov_b32 m0, s19
	s_nop 0
	global_load_lds_dwordx4 v154, s[62:63]
	s_add_u32 s80, s62, 0x2b0000
	s_mov_b32 m0, s21
	s_nop 0
	global_load_lds_dwordx4 v156, s[62:63]
	s_addc_u32 s81, s63, 0
	s_mov_b32 m0, s23
	s_nop 0
	global_load_lds_dwordx4 v154, s[80:81]
	s_nop 0
	s_mov_b32 m0, s26
	s_nop 0
	global_load_lds_dwordx4 v156, s[80:81]
	s_nop 0
	s_mov_b32 m0, s17
	s_nop 0
	global_load_lds_dwordx4 v1, s[64:65]
	s_nop 0
	s_mov_b32 m0, s27
	s_nop 0
	global_load_lds_dwordx4 v155, s[64:65]
	s_waitcnt lgkmcnt(7)
	v_mfma_f32_16x16x32_bf16 v[62:65], v[130:133], v[178:181], v[62:65]
	v_mfma_f32_16x16x32_bf16 v[58:61], v[142:145], v[178:181], v[58:61]
	s_waitcnt lgkmcnt(5)
	v_mfma_f32_16x16x32_bf16 v[46:49], v[130:133], v[186:189], v[46:49]
	v_mfma_f32_16x16x32_bf16 v[42:45], v[142:145], v[186:189], v[42:45]
	s_waitcnt vmcnt(8)
	s_waitcnt lgkmcnt(0)
	s_barrier
; #define PG8_STAGE(bufoff, gbase, voff) do { if constexpr (VAR != 1 && VAR != 3) { _Pragma("unroll") for (int _i = 0; _i < 2; ++_i) \
;         asm volatile("s_mov_b32 m0, %2\n\ts_nop 0\n\tglobal_load_lds_dwordx4 %0, %1" :: "v"((voff)[_i]), "s"((const char*)(gbase)), "s"(ldsbase + (unsigned)((bufoff) + _i * 8192)) : "memory", "m0"); } } while (0)
; #define PG8_LDA(dst, b, h) do { if constexpr (VAR < 2) _Pragma("unroll") for (int m = 0; m < 4; ++m) _Pragma("unroll") for (int k = 0; k < 2; ++k) dst[m][k] = *(const LAS bf16x8*)(lds + PG8_SA(b, h) + aoff + m * 2048 + k * 1024); } while (0)
; #define PG8_LDB(dst, b, h) do { if constexpr (VAR < 2) _Pragma("unroll") for (int n = 0; n < 2; ++n) _Pragma("unroll") for (int k = 0; k < 2; ++k) dst[n][k] = *(const LAS bf16x8*)(lds + PG8_SB(b, h) + boff + n * 2048 + k * 1024); } while (0)
; #define PG8_WAIT_V(n) asm volatile("s_waitcnt vmcnt(" #n ")" ::: "memory")
; #define PG8_WAIT_L(n) asm volatile("s_waitcnt lgkmcnt(" #n ")" ::: "memory")
; #define PG8_BAR do { if constexpr (VAR != 3) __builtin_amdgcn_s_barrier(); } while (0)
; #define PG8_SCHED __builtin_amdgcn_sched_barrier(0)
;     ...
;             PG8_WAIT_V(8); PG8_WAIT_L(0); PG8_BAR; PG8_MMA(1, 0, At, B0); PG8_MMA(1, 1, At, B1); PG8_BAR; PG8_SCHED;
;             PG8_LDB(B0, 1, 0); PG8_LDB(B1, 1, 1); PG8_SCHED; PG8_LDA(At, 1, 0); PG8_STAGE(PG8_SA(0, 1), a2 + hstepA, voffA);
;             PG8_WAIT_V(8); PG8_WAIT_L(0); PG8_BAR; PG8_MMA(0, 0, At, B0); PG8_MMA(0, 1, At, B1); PG8_BAR; PG8_SCHED;
	s_setprio 1
	s_waitcnt lgkmcnt(3)
	v_mfma_f32_16x16x32_bf16 v[30:33], v[130:133], v[194:197], v[30:33]
	v_mfma_f32_16x16x32_bf16 v[26:29], v[142:145], v[194:197], v[26:29]
	s_waitcnt lgkmcnt(1)
	v_mfma_f32_16x16x32_bf16 v[14:17], v[130:133], v[202:205], v[14:17]
	v_mfma_f32_16x16x32_bf16 v[10:13], v[142:145], v[202:205], v[10:13]
	v_mfma_f32_16x16x32_bf16 v[62:65], v[134:137], v[182:185], v[62:65]
	v_mfma_f32_16x16x32_bf16 v[58:61], v[146:149], v[182:185], v[58:61]
	v_mfma_f32_16x16x32_bf16 v[46:49], v[134:137], v[190:193], v[46:49]
	v_mfma_f32_16x16x32_bf16 v[42:45], v[146:149], v[190:193], v[42:45]
	v_mfma_f32_16x16x32_bf16 v[30:33], v[134:137], v[198:201], v[30:33]
	v_mfma_f32_16x16x32_bf16 v[26:29], v[146:149], v[198:201], v[26:29]
	s_waitcnt lgkmcnt(0)
	v_mfma_f32_16x16x32_bf16 v[14:17], v[134:137], v[206:209], v[14:17]
	v_mfma_f32_16x16x32_bf16 v[10:13], v[146:149], v[206:209], v[10:13]
	s_setprio 0
	s_setprio 1
	v_mfma_f32_16x16x32_bf16 v[54:57], v[150:153], v[178:181], v[54:57]
	v_mfma_f32_16x16x32_bf16 v[50:53], v[170:173], v[178:181], v[50:53]
	v_mfma_f32_16x16x32_bf16 v[38:41], v[150:153], v[186:189], v[38:41]
	v_mfma_f32_16x16x32_bf16 v[34:37], v[170:173], v[186:189], v[34:37]
	v_mfma_f32_16x16x32_bf16 v[22:25], v[150:153], v[194:197], v[22:25]
	v_mfma_f32_16x16x32_bf16 v[18:21], v[170:173], v[194:197], v[18:21]
	v_mfma_f32_16x16x32_bf16 v[6:9], v[150:153], v[202:205], v[6:9]
	v_mfma_f32_16x16x32_bf16 v[2:5], v[170:173], v[202:205], v[2:5]
	v_mfma_f32_16x16x32_bf16 v[54:57], v[166:169], v[182:185], v[54:57]
	v_mfma_f32_16x16x32_bf16 v[50:53], v[174:177], v[182:185], v[50:53]
	v_mfma_f32_16x16x32_bf16 v[38:41], v[166:169], v[190:193], v[38:41]
	v_mfma_f32_16x16x32_bf16 v[34:37], v[174:177], v[190:193], v[34:37]
	v_mfma_f32_16x16x32_bf16 v[22:25], v[166:169], v[198:201], v[22:25]
	v_mfma_f32_16x16x32_bf16 v[18:21], v[174:177], v[198:201], v[18:21]
	v_mfma_f32_16x16x32_bf16 v[6:9], v[166:169], v[206:209], v[6:9]
	v_mfma_f32_16x16x32_bf16 v[2:5], v[174:177], v[206:209], v[2:5]
	s_setprio 0
	s_barrier
	ds_read_b128 v[130:133], v163
	ds_read_b128 v[134:137], v163 offset:1024
	ds_read_b128 v[142:145], v163 offset:2048
	ds_read_b128 v[146:149], v163 offset:3072
	ds_read_b128 v[150:153], v164
	ds_read_b128 v[166:169], v164 offset:1024
	ds_read_b128 v[170:173], v164 offset:2048
	ds_read_b128 v[174:177], v164 offset:3072
	ds_read_b128 v[178:181], v162 offset:32768
	ds_read_b128 v[182:185], v162 offset:33792
	ds_read_b128 v[186:189], v162 offset:34816
	ds_read_b128 v[190:193], v162 offset:35840
	ds_read_b128 v[194:197], v162 offset:36864
	ds_read_b128 v[198:201], v162 offset:37888
	ds_read_b128 v[202:205], v162 offset:38912
	ds_read_b128 v[206:209], v162 offset:39936
	s_add_u32 s64, s64, 0x2b0000
	s_addc_u32 s65, s65, 0
	s_mov_b32 m0, s28
	s_nop 0
	global_load_lds_dwordx4 v1, s[64:65]
	s_nop 0
	s_mov_b32 m0, s29
	s_nop 0
	global_load_lds_dwordx4 v155, s[64:65]
	s_waitcnt lgkmcnt(7)
	v_mfma_f32_16x16x32_bf16 v[126:129], v[130:133], v[178:181], v[126:129]
	v_mfma_f32_16x16x32_bf16 v[122:125], v[142:145], v[178:181], v[122:125]
	s_waitcnt lgkmcnt(5)
	v_mfma_f32_16x16x32_bf16 v[110:113], v[130:133], v[186:189], v[110:113]
	v_mfma_f32_16x16x32_bf16 v[106:109], v[142:145], v[186:189], v[106:109]
	s_waitcnt vmcnt(8)
	s_waitcnt lgkmcnt(0)
	s_barrier
	s_setprio 1
	s_waitcnt lgkmcnt(3)
	v_mfma_f32_16x16x32_bf16 v[94:97], v[130:133], v[194:197], v[94:97]
	v_mfma_f32_16x16x32_bf16 v[90:93], v[142:145], v[194:197], v[90:93]
	s_waitcnt lgkmcnt(1)
	v_mfma_f32_16x16x32_bf16 v[78:81], v[130:133], v[202:205], v[78:81]
	v_mfma_f32_16x16x32_bf16 v[74:77], v[142:145], v[202:205], v[74:77]
	v_mfma_f32_16x16x32_bf16 v[126:129], v[134:137], v[182:185], v[126:129]
	v_mfma_f32_16x16x32_bf16 v[122:125], v[146:149], v[182:185], v[122:125]
	v_mfma_f32_16x16x32_bf16 v[110:113], v[134:137], v[190:193], v[110:113]
	v_mfma_f32_16x16x32_bf16 v[106:109], v[146:149], v[190:193], v[106:109]
	v_mfma_f32_16x16x32_bf16 v[94:97], v[134:137], v[198:201], v[94:97]
	v_mfma_f32_16x16x32_bf16 v[90:93], v[146:149], v[198:201], v[90:93]
	s_waitcnt lgkmcnt(0)
	v_mfma_f32_16x16x32_bf16 v[78:81], v[134:137], v[206:209], v[78:81]
	v_mfma_f32_16x16x32_bf16 v[74:77], v[146:149], v[206:209], v[74:77]
	s_setprio 0
	s_setprio 1
	v_mfma_f32_16x16x32_bf16 v[118:121], v[150:153], v[178:181], v[118:121]
	v_mfma_f32_16x16x32_bf16 v[114:117], v[170:173], v[178:181], v[114:117]
	v_mfma_f32_16x16x32_bf16 v[102:105], v[150:153], v[186:189], v[102:105]
	v_mfma_f32_16x16x32_bf16 v[98:101], v[170:173], v[186:189], v[98:101]
	v_mfma_f32_16x16x32_bf16 v[86:89], v[150:153], v[194:197], v[86:89]
	v_mfma_f32_16x16x32_bf16 v[82:85], v[170:173], v[194:197], v[82:85]
	v_mfma_f32_16x16x32_bf16 v[70:73], v[150:153], v[202:205], v[70:73]
	v_mfma_f32_16x16x32_bf16 v[66:69], v[170:173], v[202:205], v[66:69]
	v_mfma_f32_16x16x32_bf16 v[118:121], v[166:169], v[182:185], v[118:121]
	v_mfma_f32_16x16x32_bf16 v[114:117], v[174:177], v[182:185], v[114:117]
	v_mfma_f32_16x16x32_bf16 v[102:105], v[166:169], v[190:193], v[102:105]
	v_mfma_f32_16x16x32_bf16 v[98:101], v[174:177], v[190:193], v[98:101]
	v_mfma_f32_16x16x32_bf16 v[86:89], v[166:169], v[198:201], v[86:89]
	v_mfma_f32_16x16x32_bf16 v[82:85], v[174:177], v[198:201], v[82:85]
	v_mfma_f32_16x16x32_bf16 v[70:73], v[166:169], v[206:209], v[70:73]
	v_mfma_f32_16x16x32_bf16 v[66:69], v[174:177], v[206:209], v[66:69]
	s_setprio 0
	s_barrier
; #define PG8_STAGE(bufoff, gbase, voff) do { if constexpr (VAR != 1 && VAR != 3) { _Pragma("unroll") for (int _i = 0; _i < 2; ++_i) \
;         asm volatile("s_mov_b32 m0, %2\n\ts_nop 0\n\tglobal_load_lds_dwordx4 %0, %1" :: "v"((voff)[_i]), "s"((const char*)(gbase)), "s"(ldsbase + (unsigned)((bufoff) + _i * 8192)) : "memory", "m0"); } } while (0)
; #define PG8_LDA(dst, b, h) do { if constexpr (VAR < 2) _Pragma("unroll") for (int m = 0; m < 4; ++m) _Pragma("unroll") for (int k = 0; k < 2; ++k) dst[m][k] = *(const LAS bf16x8*)(lds + PG8_SA(b, h) + aoff + m * 2048 + k * 1024); } while (0)
; #define PG8_WAIT_V(n) asm volatile("s_waitcnt vmcnt(" #n ")" ::: "memory")
; #define PG8_WAIT_L(n) asm volatile("s_waitcnt lgkmcnt(" #n ")" ::: "memory")
; #define PG8_BAR do { if constexpr (VAR != 3) __builtin_amdgcn_s_barrier(); } while (0)
; #define PG8_SCHED __builtin_amdgcn_sched_barrier(0)
;     ...
;             PG8_LDA(At, 1, 1); PG8_STAGE(PG8_SB(1, 0), b3, voffB); PG8_STAGE(PG8_SB(1, 1), b3 + hstepB, voffB); PG8_STAGE(PG8_SA(1, 0), a3, voffA);
;             PG8_WAIT_V(8); PG8_WAIT_L(0); PG8_BAR; PG8_MMA(1, 0, At, B0); PG8_MMA(1, 1, At, B1); PG8_BAR; PG8_SCHED;
;         }
;         if (wr == 0) PG8_BAR;
	ds_read_b128 v[178:181], v162 offset:49152
	ds_read_b128 v[182:185], v162 offset:50176
	ds_read_b128 v[186:189], v162 offset:51200
	ds_read_b128 v[190:193], v162 offset:52224
	ds_read_b128 v[194:197], v162 offset:53248
	ds_read_b128 v[198:201], v162 offset:54272
	ds_read_b128 v[202:205], v162 offset:55296
	ds_read_b128 v[206:209], v162 offset:56320
	s_add_u32 s64, s62, 0x80
	s_addc_u32 s65, s63, 0
	s_mov_b32 m0, s30
	s_nop 0
	global_load_lds_dwordx4 v154, s[64:65]
	s_add_u32 s62, s62, 0x2b0080
	s_mov_b32 m0, s31
	s_nop 0
	global_load_lds_dwordx4 v156, s[64:65]
	s_addc_u32 s63, s63, 0
	s_mov_b32 m0, s67
	s_nop 0
	global_load_lds_dwordx4 v154, s[62:63]
	s_nop 0
	s_mov_b32 m0, s68
	s_nop 0
	global_load_lds_dwordx4 v156, s[62:63]
	s_nop 0
	s_mov_b32 m0, s33
	s_nop 0
	global_load_lds_dwordx4 v1, s[60:61]
	s_nop 0
	s_mov_b32 m0, s66
	s_nop 0
	global_load_lds_dwordx4 v155, s[60:61]
	s_waitcnt lgkmcnt(7)
	v_mfma_f32_16x16x32_bf16 v[62:65], v[130:133], v[178:181], v[62:65]
	v_mfma_f32_16x16x32_bf16 v[58:61], v[142:145], v[178:181], v[58:61]
	s_waitcnt lgkmcnt(5)
	v_mfma_f32_16x16x32_bf16 v[46:49], v[130:133], v[186:189], v[46:49]
	v_mfma_f32_16x16x32_bf16 v[42:45], v[142:145], v[186:189], v[42:45]
	s_waitcnt vmcnt(8)
	s_waitcnt lgkmcnt(0)
	s_barrier
	s_setprio 1
	s_waitcnt lgkmcnt(3)
	v_mfma_f32_16x16x32_bf16 v[30:33], v[130:133], v[194:197], v[30:33]
	v_mfma_f32_16x16x32_bf16 v[26:29], v[142:145], v[194:197], v[26:29]
	s_waitcnt lgkmcnt(1)
	v_mfma_f32_16x16x32_bf16 v[14:17], v[130:133], v[202:205], v[14:17]
	v_mfma_f32_16x16x32_bf16 v[10:13], v[142:145], v[202:205], v[10:13]
	v_mfma_f32_16x16x32_bf16 v[62:65], v[134:137], v[182:185], v[62:65]
	v_mfma_f32_16x16x32_bf16 v[58:61], v[146:149], v[182:185], v[58:61]
	v_mfma_f32_16x16x32_bf16 v[46:49], v[134:137], v[190:193], v[46:49]
	v_mfma_f32_16x16x32_bf16 v[42:45], v[146:149], v[190:193], v[42:45]
	v_mfma_f32_16x16x32_bf16 v[30:33], v[134:137], v[198:201], v[30:33]
	v_mfma_f32_16x16x32_bf16 v[26:29], v[146:149], v[198:201], v[26:29]
	s_waitcnt lgkmcnt(0)
	v_mfma_f32_16x16x32_bf16 v[14:17], v[134:137], v[206:209], v[14:17]
	v_mfma_f32_16x16x32_bf16 v[10:13], v[146:149], v[206:209], v[10:13]
	s_setprio 0
	s_setprio 1
	v_mfma_f32_16x16x32_bf16 v[54:57], v[150:153], v[178:181], v[54:57]
	v_mfma_f32_16x16x32_bf16 v[50:53], v[170:173], v[178:181], v[50:53]
	v_mfma_f32_16x16x32_bf16 v[38:41], v[150:153], v[186:189], v[38:41]
	v_mfma_f32_16x16x32_bf16 v[34:37], v[170:173], v[186:189], v[34:37]
	v_mfma_f32_16x16x32_bf16 v[22:25], v[150:153], v[194:197], v[22:25]
	v_mfma_f32_16x16x32_bf16 v[18:21], v[170:173], v[194:197], v[18:21]
	v_mfma_f32_16x16x32_bf16 v[6:9], v[150:153], v[202:205], v[6:9]
	v_mfma_f32_16x16x32_bf16 v[2:5], v[170:173], v[202:205], v[2:5]
	v_mfma_f32_16x16x32_bf16 v[54:57], v[166:169], v[182:185], v[54:57]
	v_mfma_f32_16x16x32_bf16 v[50:53], v[174:177], v[182:185], v[50:53]
	v_mfma_f32_16x16x32_bf16 v[38:41], v[166:169], v[190:193], v[38:41]
	v_mfma_f32_16x16x32_bf16 v[34:37], v[174:177], v[190:193], v[34:37]
	v_mfma_f32_16x16x32_bf16 v[22:25], v[166:169], v[198:201], v[22:25]
	v_mfma_f32_16x16x32_bf16 v[18:21], v[174:177], v[198:201], v[18:21]
	v_mfma_f32_16x16x32_bf16 v[6:9], v[166:169], v[206:209], v[6:9]
	v_mfma_f32_16x16x32_bf16 v[2:5], v[174:177], v[206:209], v[2:5]
	s_setprio 0
	s_barrier
	s_add_i32 s78, s78, 2
	s_add_u32 s74, s74, 0x100
	s_addc_u32 s75, s75, 0
	s_add_u32 s76, s76, 0x100
	s_addc_u32 s77, s77, 0
	s_add_u32 s58, s58, 0x100
	s_addc_u32 s59, s59, 0
	s_cmpk_gt_u32 s78, 0xa9
	s_cbranch_scc0 .LBB0_1361
	s_and_b64 vcc, exec, s[36:37]
	s_cbranch_vccz .LBB0_1364
	s_barrier
